# v44 + GEMM k-loop stage-address strength reduction: s2 is the read-stage byte offset toggled by one s_xor, fragment-read bases hoisted to loop-invariant VGPRs (-5 instrs per k-block per wave in all 7
# baseline (speedup 1.0000x reference)
; DI int TID8() { int t = threadIdx.x; asm volatile("" : "+v"(t)); return t; }
; DI void gemm8_accum(f32x4 (&acc)[8][4], const bf16_t* a, size_t lda, const bf16_t* b, size_t ldb, int nkb, bf16_t* L,
;                     const bool pre, const bf16_t* an, size_t ldan, const bf16_t* bn, size_t ldbn) {
;   const int tid = TID8(), lane = tid & 63, w = tid >> 6;
;   const int wm = w >> 2, wn = w & 3;
;   const int lrow = tid >> 3, lch = tid & 7;
;   u32x4 ra[4], rb[4];
;   unsigned offa[4], offb[4];
; #pragma unroll
;   for (int i = 0; i < 4; ++i) {
;     offa[i] = (unsigned)(lrow + 64 * i) * (unsigned)lda + (unsigned)(lch * 8);
;     offb[i] = (unsigned)(lrow + 64 * i) * (unsigned)ldb + (unsigned)(lch * 8);
;   }
;   if (!pre) {
;     g8_load1o(ra, a, offa);
;     g8_load1o(rb, b, offb);
;     __syncthreads();
;     g8_store(L, ra, rb, lrow, lch);
;   }
;   g8_load1o(ra, a + 64, offa);
;   g8_load1o(rb, b + 64, offb);
; DI void zero_acc8(f32x4 (&acc)[8][4]) {
; #pragma unroll
;   for (int i = 0; i < 8; ++i)
; #pragma unroll
;     for (int j = 0; j < 4; ++j) acc[i][j] = f32x4{0.f, 0.f, 0.f, 0.f};
; }
.LBB0_133:
	v_lshlrev_b64 v[40:41], 1, v[168:169]
	v_lshlrev_b64 v[42:43], 1, v[166:167]
	v_lshl_add_u64 v[6:7], s[2:3], 0, v[40:41]
	v_lshl_add_u64 v[8:9], s[2:3], 0, v[42:43]
	v_lshlrev_b64 v[44:45], 1, v[0:1]
	global_load_dwordx4 v[18:21], v[6:7], off offset:128
	global_load_dwordx4 v[26:29], v[8:9], off offset:128
	v_lshl_add_u64 v[10:11], s[2:3], 0, v[44:45]
	global_load_dwordx4 v[22:25], v[4:5], off offset:128
	global_load_dwordx4 v[30:33], v[10:11], off offset:128
	global_load_dwordx4 v[6:9], v[2:3], off offset:128
	v_lshl_add_u64 v[2:3], s[0:1], 0, v[40:41]
	s_nop 1
	global_load_dwordx4 v[2:5], v[2:3], off offset:128
	v_lshl_add_u64 v[10:11], s[0:1], 0, v[42:43]
	v_lshl_add_u64 v[14:15], s[0:1], 0, v[44:45]
	global_load_dwordx4 v[10:13], v[10:11], off offset:128
	s_nop 0
	global_load_dwordx4 v[14:17], v[14:15], off offset:128
	v_bfe_u32 v39, v36, 4, 2
	v_lshrrev_b32_e32 v46, 1, v36
	v_bitop3_b32 v46, v46, v39, 7 bitop3:0x6c
	v_lshlrev_b32_e32 v191, 3, v46
	v_lshlrev_b32_e32 v46, 5, v36
	v_bfe_u32 v47, v36, 1, 3
	v_and_b32_e32 v46, 0xffffe000, v46
	v_lshlrev_b32_e32 v36, 6, v36
	s_movk_i32 s0, 0x3c0
	v_and_or_b32 v46, v36, s0, v46
	s_add_u32 s0, s39, s13
	v_add_u32_e32 v34, v35, v34
	v_mov_b32_e32 v35, v1
	s_addc_u32 s1, s40, 0
	v_lshlrev_b64 v[34:35], 1, v[34:35]
	v_lshl_add_u64 v[170:171], s[0:1], 0, v[44:45]
	v_lshl_add_u64 v[172:173], s[0:1], 0, v[42:43]
	v_lshl_add_u64 v[174:175], s[0:1], 0, v[40:41]
	v_lshl_add_u64 v[176:177], s[0:1], 0, v[34:35]
	s_add_i32 s0, s38, s11
	s_add_i32 s0, s0, s12
	s_lshl_b32 s0, s0, 19
	v_readlane_b32 s1, v253, 57
	s_add_u32 s0, s1, s0
	v_readlane_b32 s1, v253, 58
	s_addc_u32 s1, s1, 0
	v_and_b32_e32 v36, 0x33c0, v36
	v_bitop3_b32 v39, v39, v47, 4 bitop3:0x36
	v_lshlrev_b32_e32 v189, 1, v38
	v_lshlrev_b32_e32 v190, 1, v37
	v_lshl_add_u64 v[184:185], s[0:1], 0, v[34:35]
	v_mov_b32_e32 v34, 0
	v_lshlrev_b32_e32 v188, 3, v39
	v_add3_u32 v163, 0, v189, v190
	v_lshl_add_u64 v[178:179], s[0:1], 0, v[44:45]
	v_lshl_add_u64 v[180:181], s[0:1], 0, v[42:43]
	v_lshl_add_u64 v[182:183], s[0:1], 0, v[40:41]
	s_mov_b64 s[0:1], 0
	s_mov_b32 s2, 0
	v_lshlrev_b32_e32 v187, 1, v46
	v_lshlrev_b32_e32 v186, 1, v36
	v_mov_b32_e32 v35, v34
	v_mov_b64_e32 v[36:37], v[34:35]
	v_mov_b64_e32 v[38:39], v[34:35]
	v_mov_b64_e32 v[40:41], v[34:35]
	v_mov_b64_e32 v[42:43], v[34:35]
	v_mov_b64_e32 v[44:45], v[34:35]
	v_mov_b64_e32 v[46:47], v[34:35]
	v_mov_b64_e32 v[48:49], v[34:35]
	v_mov_b64_e32 v[50:51], v[34:35]
	v_mov_b64_e32 v[52:53], v[34:35]
	v_mov_b64_e32 v[54:55], v[34:35]
	v_mov_b64_e32 v[56:57], v[34:35]
	v_mov_b64_e32 v[58:59], v[34:35]
	v_mov_b64_e32 v[60:61], v[34:35]
	v_mov_b64_e32 v[62:63], v[34:35]
	v_mov_b64_e32 v[64:65], v[34:35]
	v_mov_b64_e32 v[66:67], v[34:35]
	v_mov_b64_e32 v[68:69], v[34:35]
	v_mov_b64_e32 v[70:71], v[34:35]
	v_mov_b64_e32 v[72:73], v[34:35]
	v_mov_b64_e32 v[74:75], v[34:35]
	v_mov_b64_e32 v[76:77], v[34:35]
	v_mov_b64_e32 v[78:79], v[34:35]
	v_mov_b64_e32 v[80:81], v[34:35]
	v_mov_b64_e32 v[82:83], v[34:35]
	v_mov_b64_e32 v[84:85], v[34:35]
	v_mov_b64_e32 v[86:87], v[34:35]
	v_mov_b64_e32 v[88:89], v[34:35]
	v_mov_b64_e32 v[90:91], v[34:35]
	v_mov_b64_e32 v[92:93], v[34:35]
	v_mov_b64_e32 v[94:95], v[34:35]
	v_mov_b64_e32 v[96:97], v[34:35]
	v_mov_b64_e32 v[98:99], v[34:35]
	v_mov_b64_e32 v[100:101], v[34:35]
	v_mov_b64_e32 v[102:103], v[34:35]
	v_mov_b64_e32 v[104:105], v[34:35]
	v_mov_b64_e32 v[106:107], v[34:35]
	v_mov_b64_e32 v[108:109], v[34:35]
	v_mov_b64_e32 v[110:111], v[34:35]
	v_mov_b64_e32 v[112:113], v[34:35]
	v_mov_b64_e32 v[114:115], v[34:35]
	v_mov_b64_e32 v[116:117], v[34:35]
	v_mov_b64_e32 v[118:119], v[34:35]
	v_mov_b64_e32 v[120:121], v[34:35]
	v_mov_b64_e32 v[122:123], v[34:35]
	v_mov_b64_e32 v[124:125], v[34:35]
	v_mov_b64_e32 v[126:127], v[34:35]
	v_mov_b64_e32 v[128:129], v[34:35]
	v_mov_b64_e32 v[130:131], v[34:35]
	v_mov_b64_e32 v[132:133], v[34:35]
	v_mov_b64_e32 v[134:135], v[34:35]
	v_mov_b64_e32 v[136:137], v[34:35]
	v_mov_b64_e32 v[138:139], v[34:35]
	v_mov_b64_e32 v[140:141], v[34:35]
	v_mov_b64_e32 v[142:143], v[34:35]
	v_mov_b64_e32 v[144:145], v[34:35]
	v_mov_b64_e32 v[146:147], v[34:35]
	v_mov_b64_e32 v[148:149], v[34:35]
	v_mov_b64_e32 v[150:151], v[34:35]
	v_mov_b64_e32 v[152:153], v[34:35]
	v_mov_b64_e32 v[154:155], v[34:35]
	v_mov_b64_e32 v[156:157], v[34:35]
	v_mov_b64_e32 v[158:159], v[34:35]
	v_mov_b64_e32 v[160:161], v[34:35]
	v_readfirstlane_b32 s52, v184
	v_readfirstlane_b32 s53, v185
	s_sub_u32 s52, s52, 0x40000000
	s_subb_u32 s53, s53, 0
	v_readfirstlane_b32 s56, v176
	v_readfirstlane_b32 s57, v177
	s_sub_u32 s56, s56, 0x40000000
	s_subb_u32 s57, s57, 0
	v_subrev_u32_e32 v185, s52, v184
	v_subrev_u32_e32 v181, s52, v180
	v_subrev_u32_e32 v179, s52, v178
	v_subrev_u32_e32 v183, s52, v182
	v_subrev_u32_e32 v177, s56, v176
	v_subrev_u32_e32 v175, s56, v174
	v_subrev_u32_e32 v173, s56, v172
	v_subrev_u32_e32 v171, s56, v170
	v_lshl_add_u32 v170, v191, 1, v187
	v_lshl_add_u32 v172, v191, 1, v186
	v_lshl_add_u32 v174, v188, 1, v187
	v_lshl_add_u32 v176, v188, 1, v186
; DI f32x4 mfma16(bf16x8 a, bf16x8 b, f32x4 c) { return __builtin_amdgcn_mfma_f32_16x16x32_bf16(a, b, c, 0, 0, 0); }
; #pragma unroll
;   for (int ks = KS0; ks < KS1; ++ks) {
;     bf16x8 af[8], bfr[4];
; #pragma unroll
;     for (int i = 0; i < 8; ++i) {
;       const int r = wm * 128 + i * 16 + (lane & 15);
;       af[i] = *(const bf16x8*)(S + r * 64 + (((ks * 4 + (lane >> 4)) ^ ((r >> 1) & 7)) << 3));
;     }
; #pragma unroll
;     for (int j = 0; j < 4; ++j) {
;       const int r = wn * 64 + j * 16 + (lane & 15);
;       bfr[j] = *(const bf16x8*)(S + 16384 + r * 64 + (((ks * 4 + (lane >> 4)) ^ ((r >> 1) & 7)) << 3));
;     }
;     __builtin_amdgcn_s_setprio(1);
; #pragma unroll
;     for (int i = 0; i < 8; ++i)
; #pragma unroll
;       for (int j = 0; j < 4; ++j) acc[i][j] = mfma16(bfr[j], af[i], acc[i][j]);
;     __builtin_amdgcn_s_setprio(0);
;   }
; }
; DI void gemm8_accum(f32x4 (&acc)[8][4], const bf16_t* a, size_t lda, const bf16_t* b, size_t ldb, int nkb, bf16_t* L,
;                     const bool pre, const bf16_t* an, size_t ldan, const bf16_t* bn, size_t ldbn) {
;     ...
;   for (int kb = 0; kb + 2 < nkb; ++kb) {
;     __syncthreads();
;     g8_store1(L + ((kb + 1) & 1) * 32768, ra, lrow, lch);
;     g8_load1o(ra, a + (kb + 2) * 64, offa);
;     __builtin_amdgcn_sched_barrier(0);
;     g8_compute<0, 1>(acc, L + (kb & 1) * 32768, wm, wn, lane);
;     __builtin_amdgcn_sched_barrier(0);
;     g8_store1(L + ((kb + 1) & 1) * 32768 + 16384, rb, lrow, lch);
;     g8_load1o(rb, b + (kb + 2) * 64, offb);
;     __builtin_amdgcn_sched_barrier(0);
;     g8_compute<1, 2>(acc, L + (kb & 1) * 32768, wm, wn, lane);
;   }
.LBB0_134:
	s_xor_b32 s6, s2, 0x10000
	v_add_u32_e32 v167, s6, v163
	s_waitcnt lgkmcnt(0)
	s_barrier
	s_cmp_eq_u32 s100, 0
	s_cbranch_scc1 .Lstg_134_a
	v_mfma_f32_16x16x32_bf16 v[34:37], v[234:237], v[192:195], v[34:37]
	v_mfma_f32_16x16x32_bf16 v[38:41], v[238:241], v[192:195], v[38:41]
	v_mfma_f32_16x16x32_bf16 v[42:45], v[242:245], v[192:195], v[42:45]
	v_mfma_f32_16x16x32_bf16 v[46:49], v[246:249], v[192:195], v[46:49]
	v_mfma_f32_16x16x32_bf16 v[50:53], v[234:237], v[206:209], v[50:53]
	v_mfma_f32_16x16x32_bf16 v[54:57], v[238:241], v[206:209], v[54:57]
	v_mfma_f32_16x16x32_bf16 v[58:61], v[242:245], v[206:209], v[58:61]
	v_mfma_f32_16x16x32_bf16 v[62:65], v[246:249], v[206:209], v[62:65]
	v_mfma_f32_16x16x32_bf16 v[66:69], v[234:237], v[210:213], v[66:69]
	v_mfma_f32_16x16x32_bf16 v[70:73], v[238:241], v[210:213], v[70:73]
	v_mfma_f32_16x16x32_bf16 v[74:77], v[242:245], v[210:213], v[74:77]
	v_mfma_f32_16x16x32_bf16 v[78:81], v[246:249], v[210:213], v[78:81]
	v_mfma_f32_16x16x32_bf16 v[82:85], v[234:237], v[214:217], v[82:85]
	v_mfma_f32_16x16x32_bf16 v[86:89], v[238:241], v[214:217], v[86:89]
	v_mfma_f32_16x16x32_bf16 v[90:93], v[242:245], v[214:217], v[90:93]
	v_mfma_f32_16x16x32_bf16 v[94:97], v[246:249], v[214:217], v[94:97]
	v_mfma_f32_16x16x32_bf16 v[98:101], v[234:237], v[218:221], v[98:101]
	v_mfma_f32_16x16x32_bf16 v[102:105], v[238:241], v[218:221], v[102:105]
	v_mfma_f32_16x16x32_bf16 v[106:109], v[242:245], v[218:221], v[106:109]
	v_mfma_f32_16x16x32_bf16 v[110:113], v[246:249], v[218:221], v[110:113]
	v_mfma_f32_16x16x32_bf16 v[114:117], v[234:237], v[222:225], v[114:117]
	v_mfma_f32_16x16x32_bf16 v[118:121], v[238:241], v[222:225], v[118:121]
	v_mfma_f32_16x16x32_bf16 v[122:125], v[242:245], v[222:225], v[122:125]
	v_mfma_f32_16x16x32_bf16 v[126:129], v[246:249], v[222:225], v[126:129]
	v_mfma_f32_16x16x32_bf16 v[130:133], v[234:237], v[226:229], v[130:133]
	v_mfma_f32_16x16x32_bf16 v[134:137], v[238:241], v[226:229], v[134:137]
	v_mfma_f32_16x16x32_bf16 v[138:141], v[242:245], v[226:229], v[138:141]
	v_mfma_f32_16x16x32_bf16 v[142:145], v[246:249], v[226:229], v[142:145]
	v_mfma_f32_16x16x32_bf16 v[146:149], v[234:237], v[230:233], v[146:149]
	v_mfma_f32_16x16x32_bf16 v[150:153], v[238:241], v[230:233], v[150:153]
	v_mfma_f32_16x16x32_bf16 v[154:157], v[242:245], v[230:233], v[154:157]
	v_mfma_f32_16x16x32_bf16 v[158:161], v[246:249], v[230:233], v[158:161]
.Lstg_134_a:
	s_waitcnt vmcnt(4)
	ds_write_b128 v167, v[22:25]
	ds_write_b128 v167, v[18:21] offset:8192
	ds_write_b128 v167, v[26:29] offset:16384
	ds_write_b128 v167, v[30:33] offset:24576
	s_add_u32 s54, s52, s0
	s_addc_u32 s55, s53, s1
	global_load_dwordx4 v[22:25], v185, s[54:55]
	global_load_dwordx4 v[26:29], v181, s[54:55]
	global_load_dwordx4 v[18:21], v183, s[54:55]
	global_load_dwordx4 v[30:33], v179, s[54:55]
	v_add_u32_e32 v198, s2, v170
	ds_read_b128 v[192:195], v198
	ds_read_b128 v[206:209], v198 offset:2048
	ds_read_b128 v[210:213], v198 offset:4096
	ds_read_b128 v[214:217], v198 offset:6144
	ds_read_b128 v[218:221], v198 offset:8192
	ds_read_b128 v[222:225], v198 offset:10240
	ds_read_b128 v[226:229], v198 offset:12288
	ds_read_b128 v[230:233], v198 offset:14336
	v_add_u32_e32 v169, s2, v172
	ds_read_b128 v[234:237], v169 offset:32768
	ds_read_b128 v[238:241], v169 offset:34816
	ds_read_b128 v[242:245], v169 offset:36864
	ds_read_b128 v[246:249], v169 offset:38912
	s_waitcnt lgkmcnt(3)
	v_mfma_f32_16x16x32_bf16 v[34:37], v[234:237], v[192:195], v[34:37]
	s_waitcnt lgkmcnt(2)
	v_mfma_f32_16x16x32_bf16 v[38:41], v[238:241], v[192:195], v[38:41]
	s_waitcnt lgkmcnt(1)
	v_mfma_f32_16x16x32_bf16 v[42:45], v[242:245], v[192:195], v[42:45]
	s_waitcnt lgkmcnt(0)
	v_mfma_f32_16x16x32_bf16 v[46:49], v[246:249], v[192:195], v[46:49]
	v_mfma_f32_16x16x32_bf16 v[50:53], v[234:237], v[206:209], v[50:53]
	v_mfma_f32_16x16x32_bf16 v[54:57], v[238:241], v[206:209], v[54:57]
	v_mfma_f32_16x16x32_bf16 v[58:61], v[242:245], v[206:209], v[58:61]
	v_mfma_f32_16x16x32_bf16 v[62:65], v[246:249], v[206:209], v[62:65]
	v_mfma_f32_16x16x32_bf16 v[66:69], v[234:237], v[210:213], v[66:69]
	v_mfma_f32_16x16x32_bf16 v[70:73], v[238:241], v[210:213], v[70:73]
	v_mfma_f32_16x16x32_bf16 v[74:77], v[242:245], v[210:213], v[74:77]
	v_mfma_f32_16x16x32_bf16 v[78:81], v[246:249], v[210:213], v[78:81]
	v_mfma_f32_16x16x32_bf16 v[82:85], v[234:237], v[214:217], v[82:85]
	v_mfma_f32_16x16x32_bf16 v[86:89], v[238:241], v[214:217], v[86:89]
	v_mfma_f32_16x16x32_bf16 v[90:93], v[242:245], v[214:217], v[90:93]
	v_mfma_f32_16x16x32_bf16 v[94:97], v[246:249], v[214:217], v[94:97]
	v_mfma_f32_16x16x32_bf16 v[98:101], v[234:237], v[218:221], v[98:101]
	v_mfma_f32_16x16x32_bf16 v[102:105], v[238:241], v[218:221], v[102:105]
	v_mfma_f32_16x16x32_bf16 v[106:109], v[242:245], v[218:221], v[106:109]
	v_mfma_f32_16x16x32_bf16 v[110:113], v[246:249], v[218:221], v[110:113]
	v_mfma_f32_16x16x32_bf16 v[114:117], v[234:237], v[222:225], v[114:117]
	v_mfma_f32_16x16x32_bf16 v[118:121], v[238:241], v[222:225], v[118:121]
	v_mfma_f32_16x16x32_bf16 v[122:125], v[242:245], v[222:225], v[122:125]
	v_mfma_f32_16x16x32_bf16 v[126:129], v[246:249], v[222:225], v[126:129]
	v_mfma_f32_16x16x32_bf16 v[130:133], v[234:237], v[226:229], v[130:133]
	v_mfma_f32_16x16x32_bf16 v[134:137], v[238:241], v[226:229], v[134:137]
	v_mfma_f32_16x16x32_bf16 v[138:141], v[242:245], v[226:229], v[138:141]
	v_mfma_f32_16x16x32_bf16 v[142:145], v[246:249], v[226:229], v[142:145]
	v_mfma_f32_16x16x32_bf16 v[146:149], v[234:237], v[230:233], v[146:149]
	v_mfma_f32_16x16x32_bf16 v[150:153], v[238:241], v[230:233], v[150:153]
	v_mfma_f32_16x16x32_bf16 v[154:157], v[242:245], v[230:233], v[154:157]
	v_mfma_f32_16x16x32_bf16 v[158:161], v[246:249], v[230:233], v[158:161]
	s_waitcnt vmcnt(4)
	ds_write_b128 v167, v[6:9] offset:32768
	ds_write_b128 v167, v[2:5] offset:40960
	ds_write_b128 v167, v[10:13] offset:49152
	ds_write_b128 v167, v[14:17] offset:57344
	s_add_u32 s58, s56, s0
	s_addc_u32 s59, s57, s1
	global_load_dwordx4 v[6:9], v177, s[58:59]
	global_load_dwordx4 v[2:5], v175, s[58:59]
	global_load_dwordx4 v[10:13], v173, s[58:59]
	global_load_dwordx4 v[14:17], v171, s[58:59]
	v_add_u32_e32 v169, s2, v174
	ds_read_b128 v[192:195], v169
	ds_read_b128 v[206:209], v169 offset:2048
	ds_read_b128 v[210:213], v169 offset:4096
	ds_read_b128 v[214:217], v169 offset:6144
	ds_read_b128 v[218:221], v169 offset:8192
	ds_read_b128 v[222:225], v169 offset:10240
	ds_read_b128 v[226:229], v169 offset:12288
	ds_read_b128 v[230:233], v169 offset:14336
	v_add_u32_e32 v167, s2, v176
	ds_read_b128 v[234:237], v167 offset:32768
	ds_read_b128 v[238:241], v167 offset:34816
	ds_read_b128 v[242:245], v167 offset:36864
	ds_read_b128 v[246:249], v167 offset:38912
	s_cmp_lg_u32 s101, 0
	s_cbranch_scc1 .Lstg_134_b
; DI f32x4 mfma16(bf16x8 a, bf16x8 b, f32x4 c) { return __builtin_amdgcn_mfma_f32_16x16x32_bf16(a, b, c, 0, 0, 0); }
; #pragma unroll
;   for (int ks = KS0; ks < KS1; ++ks) {
;     bf16x8 af[8], bfr[4];
; #pragma unroll
;     for (int i = 0; i < 8; ++i) {
;       const int r = wm * 128 + i * 16 + (lane & 15);
;       af[i] = *(const bf16x8*)(S + r * 64 + (((ks * 4 + (lane >> 4)) ^ ((r >> 1) & 7)) << 3));
;     }
; #pragma unroll
;     for (int j = 0; j < 4; ++j) {
;       const int r = wn * 64 + j * 16 + (lane & 15);
;       bfr[j] = *(const bf16x8*)(S + 16384 + r * 64 + (((ks * 4 + (lane >> 4)) ^ ((r >> 1) & 7)) << 3));
;     }
;     __builtin_amdgcn_s_setprio(1);
; #pragma unroll
;     for (int i = 0; i < 8; ++i)
; #pragma unroll
;       for (int j = 0; j < 4; ++j) acc[i][j] = mfma16(bfr[j], af[i], acc[i][j]);
;     __builtin_amdgcn_s_setprio(0);
;   }
; }
; DI void gemm8_accum(f32x4 (&acc)[8][4], const bf16_t* a, size_t lda, const bf16_t* b, size_t ldb, int nkb, bf16_t* L,
;                     const bool pre, const bf16_t* an, size_t ldan, const bf16_t* bn, size_t ldbn) {
;     ...
;   for (int kb = 0; kb + 2 < nkb; ++kb) {
;     __syncthreads();
;     g8_store1(L + ((kb + 1) & 1) * 32768, ra, lrow, lch);
;     g8_load1o(ra, a + (kb + 2) * 64, offa);
;     __builtin_amdgcn_sched_barrier(0);
;     g8_compute<0, 1>(acc, L + (kb & 1) * 32768, wm, wn, lane);
;     __builtin_amdgcn_sched_barrier(0);
;     g8_store1(L + ((kb + 1) & 1) * 32768 + 16384, rb, lrow, lch);
;     g8_load1o(rb, b + (kb + 2) * 64, offb);
;     __builtin_amdgcn_sched_barrier(0);
;     g8_compute<1, 2>(acc, L + (kb & 1) * 32768, wm, wn, lane);
;   }
	s_waitcnt lgkmcnt(3)
	v_mfma_f32_16x16x32_bf16 v[34:37], v[234:237], v[192:195], v[34:37]
	s_waitcnt lgkmcnt(2)
	v_mfma_f32_16x16x32_bf16 v[38:41], v[238:241], v[192:195], v[38:41]
	s_waitcnt lgkmcnt(1)
	v_mfma_f32_16x16x32_bf16 v[42:45], v[242:245], v[192:195], v[42:45]
	s_waitcnt lgkmcnt(0)
	v_mfma_f32_16x16x32_bf16 v[46:49], v[246:249], v[192:195], v[46:49]
	v_mfma_f32_16x16x32_bf16 v[50:53], v[234:237], v[206:209], v[50:53]
	v_mfma_f32_16x16x32_bf16 v[54:57], v[238:241], v[206:209], v[54:57]
	v_mfma_f32_16x16x32_bf16 v[58:61], v[242:245], v[206:209], v[58:61]
	v_mfma_f32_16x16x32_bf16 v[62:65], v[246:249], v[206:209], v[62:65]
	v_mfma_f32_16x16x32_bf16 v[66:69], v[234:237], v[210:213], v[66:69]
	v_mfma_f32_16x16x32_bf16 v[70:73], v[238:241], v[210:213], v[70:73]
	v_mfma_f32_16x16x32_bf16 v[74:77], v[242:245], v[210:213], v[74:77]
	v_mfma_f32_16x16x32_bf16 v[78:81], v[246:249], v[210:213], v[78:81]
	v_mfma_f32_16x16x32_bf16 v[82:85], v[234:237], v[214:217], v[82:85]
	v_mfma_f32_16x16x32_bf16 v[86:89], v[238:241], v[214:217], v[86:89]
	v_mfma_f32_16x16x32_bf16 v[90:93], v[242:245], v[214:217], v[90:93]
	v_mfma_f32_16x16x32_bf16 v[94:97], v[246:249], v[214:217], v[94:97]
	v_mfma_f32_16x16x32_bf16 v[98:101], v[234:237], v[218:221], v[98:101]
	v_mfma_f32_16x16x32_bf16 v[102:105], v[238:241], v[218:221], v[102:105]
	v_mfma_f32_16x16x32_bf16 v[106:109], v[242:245], v[218:221], v[106:109]
	v_mfma_f32_16x16x32_bf16 v[110:113], v[246:249], v[218:221], v[110:113]
	v_mfma_f32_16x16x32_bf16 v[114:117], v[234:237], v[222:225], v[114:117]
	v_mfma_f32_16x16x32_bf16 v[118:121], v[238:241], v[222:225], v[118:121]
	v_mfma_f32_16x16x32_bf16 v[122:125], v[242:245], v[222:225], v[122:125]
	v_mfma_f32_16x16x32_bf16 v[126:129], v[246:249], v[222:225], v[126:129]
	v_mfma_f32_16x16x32_bf16 v[130:133], v[234:237], v[226:229], v[130:133]
	v_mfma_f32_16x16x32_bf16 v[134:137], v[238:241], v[226:229], v[134:137]
	v_mfma_f32_16x16x32_bf16 v[138:141], v[242:245], v[226:229], v[138:141]
	v_mfma_f32_16x16x32_bf16 v[142:145], v[246:249], v[226:229], v[142:145]
	v_mfma_f32_16x16x32_bf16 v[146:149], v[234:237], v[230:233], v[146:149]
	v_mfma_f32_16x16x32_bf16 v[150:153], v[238:241], v[230:233], v[150:153]
	v_mfma_f32_16x16x32_bf16 v[154:157], v[242:245], v[230:233], v[154:157]
	v_mfma_f32_16x16x32_bf16 v[158:161], v[246:249], v[230:233], v[158:161]
.Lstg_134_b:
	s_mov_b32 s100, s101
	s_xor_b32 s2, s2, 0x10000
	s_add_u32 s0, s0, 0x80
	s_addc_u32 s1, s1, 0
	s_cmpk_lg_i32 s0, 0x700
	s_cbranch_scc1 .LBB0_134
	s_cmp_eq_u32 s100, 0
	s_cbranch_scc1 .Lstg_134_c
	s_waitcnt lgkmcnt(0)
	v_mfma_f32_16x16x32_bf16 v[34:37], v[234:237], v[192:195], v[34:37]
	v_mfma_f32_16x16x32_bf16 v[38:41], v[238:241], v[192:195], v[38:41]
	v_mfma_f32_16x16x32_bf16 v[42:45], v[242:245], v[192:195], v[42:45]
	v_mfma_f32_16x16x32_bf16 v[46:49], v[246:249], v[192:195], v[46:49]
	v_mfma_f32_16x16x32_bf16 v[50:53], v[234:237], v[206:209], v[50:53]
	v_mfma_f32_16x16x32_bf16 v[54:57], v[238:241], v[206:209], v[54:57]
	v_mfma_f32_16x16x32_bf16 v[58:61], v[242:245], v[206:209], v[58:61]
	v_mfma_f32_16x16x32_bf16 v[62:65], v[246:249], v[206:209], v[62:65]
	v_mfma_f32_16x16x32_bf16 v[66:69], v[234:237], v[210:213], v[66:69]
	v_mfma_f32_16x16x32_bf16 v[70:73], v[238:241], v[210:213], v[70:73]
	v_mfma_f32_16x16x32_bf16 v[74:77], v[242:245], v[210:213], v[74:77]
	v_mfma_f32_16x16x32_bf16 v[78:81], v[246:249], v[210:213], v[78:81]
	v_mfma_f32_16x16x32_bf16 v[82:85], v[234:237], v[214:217], v[82:85]
	v_mfma_f32_16x16x32_bf16 v[86:89], v[238:241], v[214:217], v[86:89]
	v_mfma_f32_16x16x32_bf16 v[90:93], v[242:245], v[214:217], v[90:93]
	v_mfma_f32_16x16x32_bf16 v[94:97], v[246:249], v[214:217], v[94:97]
	v_mfma_f32_16x16x32_bf16 v[98:101], v[234:237], v[218:221], v[98:101]
	v_mfma_f32_16x16x32_bf16 v[102:105], v[238:241], v[218:221], v[102:105]
	v_mfma_f32_16x16x32_bf16 v[106:109], v[242:245], v[218:221], v[106:109]
	v_mfma_f32_16x16x32_bf16 v[110:113], v[246:249], v[218:221], v[110:113]
	v_mfma_f32_16x16x32_bf16 v[114:117], v[234:237], v[222:225], v[114:117]
	v_mfma_f32_16x16x32_bf16 v[118:121], v[238:241], v[222:225], v[118:121]
	v_mfma_f32_16x16x32_bf16 v[122:125], v[242:245], v[222:225], v[122:125]
	v_mfma_f32_16x16x32_bf16 v[126:129], v[246:249], v[222:225], v[126:129]
	v_mfma_f32_16x16x32_bf16 v[130:133], v[234:237], v[226:229], v[130:133]
	v_mfma_f32_16x16x32_bf16 v[134:137], v[238:241], v[226:229], v[134:137]
	v_mfma_f32_16x16x32_bf16 v[138:141], v[242:245], v[226:229], v[138:141]
	v_mfma_f32_16x16x32_bf16 v[142:145], v[246:249], v[226:229], v[142:145]
	v_mfma_f32_16x16x32_bf16 v[146:149], v[234:237], v[230:233], v[146:149]
	v_mfma_f32_16x16x32_bf16 v[150:153], v[238:241], v[230:233], v[150:153]
	v_mfma_f32_16x16x32_bf16 v[154:157], v[242:245], v[230:233], v[154:157]
	v_mfma_f32_16x16x32_bf16 v[158:161], v[246:249], v[230:233], v[158:161]
	s_mov_b32 s100, 0

; DI int TID8() { int t = threadIdx.x; asm volatile("" : "+v"(t)); return t; }
; DI void gemm8_accum(f32x4 (&acc)[8][4], const bf16_t* a, size_t lda, const bf16_t* b, size_t ldb, int nkb, bf16_t* L,
;                     const bool pre, const bf16_t* an, size_t ldan, const bf16_t* bn, size_t ldbn) {
;   const int tid = TID8(), lane = tid & 63, w = tid >> 6;
;   const int wm = w >> 2, wn = w & 3;
;   const int lrow = tid >> 3, lch = tid & 7;
;   u32x4 ra[4], rb[4];
;   unsigned offa[4], offb[4];
; #pragma unroll
;   for (int i = 0; i < 4; ++i) {
;     offa[i] = (unsigned)(lrow + 64 * i) * (unsigned)lda + (unsigned)(lch * 8);
;     offb[i] = (unsigned)(lrow + 64 * i) * (unsigned)ldb + (unsigned)(lch * 8);
;   }
;   if (!pre) {
;     g8_load1o(ra, a, offa);
;     g8_load1o(rb, b, offb);
;     __syncthreads();
;     g8_store(L, ra, rb, lrow, lch);
;   }
;   g8_load1o(ra, a + 64, offa);
;   g8_load1o(rb, b + 64, offb);
; DI void zero_acc8(f32x4 (&acc)[8][4]) {
; #pragma unroll
;   for (int i = 0; i < 8; ++i)
; #pragma unroll
;     for (int j = 0; j < 4; ++j) acc[i][j] = f32x4{0.f, 0.f, 0.f, 0.f};
; }
.LBB0_777:
	v_lshlrev_b64 v[38:39], 1, v[168:169]
	v_lshl_add_u64 v[6:7], s[2:3], 0, v[38:39]
	v_lshlrev_b64 v[40:41], 1, v[166:167]
	v_lshlrev_b64 v[42:43], 1, v[164:165]
	v_lshl_add_u64 v[8:9], s[2:3], 0, v[40:41]
	global_load_dwordx4 v[18:21], v[6:7], off offset:128
	global_load_dwordx4 v[26:29], v[8:9], off offset:128
	v_lshl_add_u64 v[6:7], s[2:3], 0, v[42:43]
	global_load_dwordx4 v[22:25], v[4:5], off offset:128
	global_load_dwordx4 v[30:33], v[6:7], off offset:128
	global_load_dwordx4 v[14:17], v[2:3], off offset:128
	v_lshl_add_u64 v[2:3], s[0:1], 0, v[38:39]
	s_nop 1
	global_load_dwordx4 v[2:5], v[2:3], off offset:128
	v_lshl_add_u64 v[6:7], s[0:1], 0, v[40:41]
	v_lshl_add_u64 v[10:11], s[0:1], 0, v[42:43]
	global_load_dwordx4 v[6:9], v[6:7], off offset:128
	s_nop 0
	global_load_dwordx4 v[10:13], v[10:11], off offset:128
	s_lshl_b32 s7, s11, 10
	v_bfe_u32 v44, v35, 4, 2
	v_lshrrev_b32_e32 v45, 1, v35
	s_and_b32 s21, s7, 0xc0000
	s_and_b32 s7, s10, 0x60
	v_readlane_b32 s20, v252, 25
	v_bitop3_b32 v45, v45, v44, 7 bitop3:0x6c
	s_or_b32 s7, s20, s7
	s_and_b32 s20, s9, 3
	v_lshlrev_b32_e32 v169, 3, v45
	v_lshlrev_b32_e32 v45, 5, v35
	s_add_i32 s7, s7, s20
	v_bfe_u32 v46, v35, 1, 3
	v_and_b32_e32 v45, 0xffffe000, v45
	v_lshlrev_b32_e32 v35, 6, v35
	s_movk_i32 s0, 0x3c0
	s_lshl_b32 s13, s13, 8
	s_lshl_b32 s6, s12, 9
	s_lshl_b32 s20, s7, 18
	v_and_or_b32 v45, v35, s0, v45
	v_and_b32_e32 v47, 0x33c0, v35
	v_bitop3_b32 v35, v44, v46, 4 bitop3:0x36
	v_readlane_b32 s0, v254, 10
	v_lshlrev_b32_e32 v189, 3, v35
	s_add_u32 s0, s0, s21
	v_readlane_b32 s1, v254, 11
	v_add_u32_e32 v34, v34, v170
	v_mov_b32_e32 v35, v1
	s_addc_u32 s1, s1, 0
	v_lshlrev_b64 v[34:35], 1, v[34:35]
	v_lshl_add_u64 v[172:173], s[0:1], 0, v[42:43]
	v_lshl_add_u64 v[174:175], s[0:1], 0, v[40:41]
	v_lshl_add_u64 v[176:177], s[0:1], 0, v[38:39]
	v_lshl_add_u64 v[178:179], s[0:1], 0, v[34:35]
	v_readlane_b32 s0, v254, 14
	s_add_u32 s0, s0, s20
	v_readlane_b32 s1, v254, 15
	s_addc_u32 s1, s1, 0
	v_lshlrev_b32_e32 v165, 1, v37
	v_lshlrev_b32_e32 v167, 1, v36
	v_lshl_add_u64 v[186:187], s[0:1], 0, v[34:35]
	v_mov_b32_e32 v34, 0
	v_add3_u32 v163, 0, v165, v167
	v_lshl_add_u64 v[180:181], s[0:1], 0, v[42:43]
	v_lshl_add_u64 v[182:183], s[0:1], 0, v[40:41]
	v_lshl_add_u64 v[184:185], s[0:1], 0, v[38:39]
	s_mov_b64 s[0:1], 0
	s_mov_b32 s2, 0
	v_lshlrev_b32_e32 v188, 1, v45
	v_lshlrev_b32_e32 v171, 1, v47
	v_mov_b32_e32 v35, v34
	v_mov_b64_e32 v[36:37], v[34:35]
	v_mov_b64_e32 v[38:39], v[34:35]
	v_mov_b64_e32 v[40:41], v[34:35]
	v_mov_b64_e32 v[42:43], v[34:35]
	v_mov_b64_e32 v[44:45], v[34:35]
	v_mov_b64_e32 v[46:47], v[34:35]
	v_mov_b64_e32 v[48:49], v[34:35]
	v_mov_b64_e32 v[50:51], v[34:35]
	v_mov_b64_e32 v[52:53], v[34:35]
	v_mov_b64_e32 v[54:55], v[34:35]
	v_mov_b64_e32 v[56:57], v[34:35]
	v_mov_b64_e32 v[58:59], v[34:35]
	v_mov_b64_e32 v[60:61], v[34:35]
	v_mov_b64_e32 v[62:63], v[34:35]
	v_mov_b64_e32 v[64:65], v[34:35]
	v_mov_b64_e32 v[66:67], v[34:35]
	v_mov_b64_e32 v[68:69], v[34:35]
	v_mov_b64_e32 v[70:71], v[34:35]
	v_mov_b64_e32 v[72:73], v[34:35]
	v_mov_b64_e32 v[74:75], v[34:35]
	v_mov_b64_e32 v[76:77], v[34:35]
	v_mov_b64_e32 v[78:79], v[34:35]
	v_mov_b64_e32 v[80:81], v[34:35]
	v_mov_b64_e32 v[82:83], v[34:35]
	v_mov_b64_e32 v[84:85], v[34:35]
	v_mov_b64_e32 v[86:87], v[34:35]
	v_mov_b64_e32 v[88:89], v[34:35]
	v_mov_b64_e32 v[90:91], v[34:35]
	v_mov_b64_e32 v[92:93], v[34:35]
	v_mov_b64_e32 v[94:95], v[34:35]
	v_mov_b64_e32 v[96:97], v[34:35]
	v_mov_b64_e32 v[98:99], v[34:35]
	v_mov_b64_e32 v[100:101], v[34:35]
	v_mov_b64_e32 v[102:103], v[34:35]
	v_mov_b64_e32 v[104:105], v[34:35]
	v_mov_b64_e32 v[106:107], v[34:35]
	v_mov_b64_e32 v[108:109], v[34:35]
	v_mov_b64_e32 v[110:111], v[34:35]
	v_mov_b64_e32 v[112:113], v[34:35]
	v_mov_b64_e32 v[114:115], v[34:35]
	v_mov_b64_e32 v[116:117], v[34:35]
	v_mov_b64_e32 v[118:119], v[34:35]
	v_mov_b64_e32 v[120:121], v[34:35]
	v_mov_b64_e32 v[122:123], v[34:35]
	v_mov_b64_e32 v[124:125], v[34:35]
	v_mov_b64_e32 v[126:127], v[34:35]
	v_mov_b64_e32 v[128:129], v[34:35]
	v_mov_b64_e32 v[130:131], v[34:35]
	v_mov_b64_e32 v[132:133], v[34:35]
	v_mov_b64_e32 v[134:135], v[34:35]
	v_mov_b64_e32 v[136:137], v[34:35]
	v_mov_b64_e32 v[138:139], v[34:35]
	v_mov_b64_e32 v[140:141], v[34:35]
	v_mov_b64_e32 v[142:143], v[34:35]
	v_mov_b64_e32 v[144:145], v[34:35]
	v_mov_b64_e32 v[146:147], v[34:35]
	v_mov_b64_e32 v[148:149], v[34:35]
	v_mov_b64_e32 v[150:151], v[34:35]
	v_mov_b64_e32 v[152:153], v[34:35]
	v_mov_b64_e32 v[154:155], v[34:35]
	v_mov_b64_e32 v[156:157], v[34:35]
	v_mov_b64_e32 v[158:159], v[34:35]
	v_mov_b64_e32 v[160:161], v[34:35]
	v_readfirstlane_b32 s52, v186
	v_readfirstlane_b32 s53, v187
	s_sub_u32 s52, s52, 0x40000000
	s_subb_u32 s53, s53, 0
	v_readfirstlane_b32 s56, v178
	v_readfirstlane_b32 s57, v179
	s_sub_u32 s56, s56, 0x40000000
	s_subb_u32 s57, s57, 0
	v_subrev_u32_e32 v187, s52, v186
	v_subrev_u32_e32 v183, s52, v182
	v_subrev_u32_e32 v181, s52, v180
	v_subrev_u32_e32 v185, s52, v184
	v_subrev_u32_e32 v179, s56, v178
	v_subrev_u32_e32 v177, s56, v176
	v_subrev_u32_e32 v175, s56, v174
	v_subrev_u32_e32 v173, s56, v172
	v_lshl_add_u32 v172, v169, 1, v188
	v_lshl_add_u32 v174, v169, 1, v171
	v_lshl_add_u32 v176, v189, 1, v188
	v_lshl_add_u32 v178, v189, 1, v171
; DI f32x4 mfma16(bf16x8 a, bf16x8 b, f32x4 c) { return __builtin_amdgcn_mfma_f32_16x16x32_bf16(a, b, c, 0, 0, 0); }
; #pragma unroll
;   for (int ks = KS0; ks < KS1; ++ks) {
;     bf16x8 af[8], bfr[4];
; #pragma unroll
;     for (int i = 0; i < 8; ++i) {
;       const int r = wm * 128 + i * 16 + (lane & 15);
;       af[i] = *(const bf16x8*)(S + r * 64 + (((ks * 4 + (lane >> 4)) ^ ((r >> 1) & 7)) << 3));
;     }
; #pragma unroll
;     for (int j = 0; j < 4; ++j) {
;       const int r = wn * 64 + j * 16 + (lane & 15);
;       bfr[j] = *(const bf16x8*)(S + 16384 + r * 64 + (((ks * 4 + (lane >> 4)) ^ ((r >> 1) & 7)) << 3));
;     }
;     __builtin_amdgcn_s_setprio(1);
; #pragma unroll
;     for (int i = 0; i < 8; ++i)
; #pragma unroll
;       for (int j = 0; j < 4; ++j) acc[i][j] = mfma16(bfr[j], af[i], acc[i][j]);
;     __builtin_amdgcn_s_setprio(0);
;   }
; }
; DI void gemm8_accum(f32x4 (&acc)[8][4], const bf16_t* a, size_t lda, const bf16_t* b, size_t ldb, int nkb, bf16_t* L,
;                     const bool pre, const bf16_t* an, size_t ldan, const bf16_t* bn, size_t ldbn) {
;     ...
;   for (int kb = 0; kb + 2 < nkb; ++kb) {
;     __syncthreads();
;     g8_store1(L + ((kb + 1) & 1) * 32768, ra, lrow, lch);
;     g8_load1o(ra, a + (kb + 2) * 64, offa);
;     __builtin_amdgcn_sched_barrier(0);
;     g8_compute<0, 1>(acc, L + (kb & 1) * 32768, wm, wn, lane);
;     __builtin_amdgcn_sched_barrier(0);
;     g8_store1(L + ((kb + 1) & 1) * 32768 + 16384, rb, lrow, lch);
;     g8_load1o(rb, b + (kb + 2) * 64, offb);
;     __builtin_amdgcn_sched_barrier(0);
;     g8_compute<1, 2>(acc, L + (kb & 1) * 32768, wm, wn, lane);
;   }
.LBB0_778:
	s_xor_b32 s20, s2, 0x10000
	v_add_u32_e32 v191, s20, v163
	s_waitcnt lgkmcnt(0)
	s_barrier
	s_cmp_eq_u32 s100, 0
	s_cbranch_scc1 .Lstg_778_a
	v_mfma_f32_16x16x32_bf16 v[158:161], v[230:233], v[192:195], v[158:161]
	v_mfma_f32_16x16x32_bf16 v[154:157], v[234:237], v[192:195], v[154:157]
	v_mfma_f32_16x16x32_bf16 v[150:153], v[238:241], v[192:195], v[150:153]
	v_mfma_f32_16x16x32_bf16 v[146:149], v[242:245], v[192:195], v[146:149]
	v_mfma_f32_16x16x32_bf16 v[142:145], v[230:233], v[198:201], v[142:145]
	v_mfma_f32_16x16x32_bf16 v[138:141], v[234:237], v[198:201], v[138:141]
	v_mfma_f32_16x16x32_bf16 v[134:137], v[238:241], v[198:201], v[134:137]
	v_mfma_f32_16x16x32_bf16 v[130:133], v[242:245], v[198:201], v[130:133]
	v_mfma_f32_16x16x32_bf16 v[126:129], v[230:233], v[206:209], v[126:129]
	v_mfma_f32_16x16x32_bf16 v[122:125], v[234:237], v[206:209], v[122:125]
	v_mfma_f32_16x16x32_bf16 v[118:121], v[238:241], v[206:209], v[118:121]
	v_mfma_f32_16x16x32_bf16 v[114:117], v[242:245], v[206:209], v[114:117]
	v_mfma_f32_16x16x32_bf16 v[110:113], v[230:233], v[210:213], v[110:113]
	v_mfma_f32_16x16x32_bf16 v[106:109], v[234:237], v[210:213], v[106:109]
	v_mfma_f32_16x16x32_bf16 v[102:105], v[238:241], v[210:213], v[102:105]
	v_mfma_f32_16x16x32_bf16 v[98:101], v[242:245], v[210:213], v[98:101]
	v_mfma_f32_16x16x32_bf16 v[94:97], v[230:233], v[214:217], v[94:97]
	v_mfma_f32_16x16x32_bf16 v[90:93], v[234:237], v[214:217], v[90:93]
	v_mfma_f32_16x16x32_bf16 v[86:89], v[238:241], v[214:217], v[86:89]
	v_mfma_f32_16x16x32_bf16 v[82:85], v[242:245], v[214:217], v[82:85]
	v_mfma_f32_16x16x32_bf16 v[78:81], v[230:233], v[218:221], v[78:81]
	v_mfma_f32_16x16x32_bf16 v[74:77], v[234:237], v[218:221], v[74:77]
	v_mfma_f32_16x16x32_bf16 v[70:73], v[238:241], v[218:221], v[70:73]
	v_mfma_f32_16x16x32_bf16 v[66:69], v[242:245], v[218:221], v[66:69]
	v_mfma_f32_16x16x32_bf16 v[62:65], v[230:233], v[222:225], v[62:65]
	v_mfma_f32_16x16x32_bf16 v[58:61], v[234:237], v[222:225], v[58:61]
	v_mfma_f32_16x16x32_bf16 v[54:57], v[238:241], v[222:225], v[54:57]
	v_mfma_f32_16x16x32_bf16 v[50:53], v[242:245], v[222:225], v[50:53]
	v_mfma_f32_16x16x32_bf16 v[46:49], v[230:233], v[226:229], v[46:49]
	v_mfma_f32_16x16x32_bf16 v[42:45], v[234:237], v[226:229], v[42:45]
	v_mfma_f32_16x16x32_bf16 v[38:41], v[238:241], v[226:229], v[38:41]
	v_mfma_f32_16x16x32_bf16 v[34:37], v[242:245], v[226:229], v[34:37]
.Lstg_778_a:
	s_waitcnt vmcnt(4)
	ds_write_b128 v191, v[22:25]
	ds_write_b128 v191, v[18:21] offset:8192
	ds_write_b128 v191, v[26:29] offset:16384
	ds_write_b128 v191, v[30:33] offset:24576
	s_add_u32 s54, s52, s0
	s_addc_u32 s55, s53, s1
	global_load_dwordx4 v[22:25], v187, s[54:55]
	global_load_dwordx4 v[26:29], v183, s[54:55]
	global_load_dwordx4 v[18:21], v185, s[54:55]
	global_load_dwordx4 v[30:33], v181, s[54:55]
	v_add_u32_e32 v203, s2, v172
	ds_read_b128 v[192:195], v203
	ds_read_b128 v[198:201], v203 offset:2048
	ds_read_b128 v[206:209], v203 offset:4096
	ds_read_b128 v[210:213], v203 offset:6144
	ds_read_b128 v[214:217], v203 offset:8192
	ds_read_b128 v[218:221], v203 offset:10240
	ds_read_b128 v[222:225], v203 offset:12288
	ds_read_b128 v[226:229], v203 offset:14336
	v_add_u32_e32 v202, s2, v174
	ds_read_b128 v[230:233], v202 offset:32768
	ds_read_b128 v[234:237], v202 offset:34816
	ds_read_b128 v[238:241], v202 offset:36864
	ds_read_b128 v[242:245], v202 offset:38912
	s_waitcnt lgkmcnt(3)
	v_mfma_f32_16x16x32_bf16 v[158:161], v[230:233], v[192:195], v[158:161]
	s_waitcnt lgkmcnt(2)
	v_mfma_f32_16x16x32_bf16 v[154:157], v[234:237], v[192:195], v[154:157]
	s_waitcnt lgkmcnt(1)
	v_mfma_f32_16x16x32_bf16 v[150:153], v[238:241], v[192:195], v[150:153]
	s_waitcnt lgkmcnt(0)
	v_mfma_f32_16x16x32_bf16 v[146:149], v[242:245], v[192:195], v[146:149]
	v_mfma_f32_16x16x32_bf16 v[142:145], v[230:233], v[198:201], v[142:145]
	v_mfma_f32_16x16x32_bf16 v[138:141], v[234:237], v[198:201], v[138:141]
	v_mfma_f32_16x16x32_bf16 v[134:137], v[238:241], v[198:201], v[134:137]
	v_mfma_f32_16x16x32_bf16 v[130:133], v[242:245], v[198:201], v[130:133]
	v_mfma_f32_16x16x32_bf16 v[126:129], v[230:233], v[206:209], v[126:129]
	v_mfma_f32_16x16x32_bf16 v[122:125], v[234:237], v[206:209], v[122:125]
	v_mfma_f32_16x16x32_bf16 v[118:121], v[238:241], v[206:209], v[118:121]
	v_mfma_f32_16x16x32_bf16 v[114:117], v[242:245], v[206:209], v[114:117]
	v_mfma_f32_16x16x32_bf16 v[110:113], v[230:233], v[210:213], v[110:113]
	v_mfma_f32_16x16x32_bf16 v[106:109], v[234:237], v[210:213], v[106:109]
	v_mfma_f32_16x16x32_bf16 v[102:105], v[238:241], v[210:213], v[102:105]
	v_mfma_f32_16x16x32_bf16 v[98:101], v[242:245], v[210:213], v[98:101]
	v_mfma_f32_16x16x32_bf16 v[94:97], v[230:233], v[214:217], v[94:97]
	v_mfma_f32_16x16x32_bf16 v[90:93], v[234:237], v[214:217], v[90:93]
	v_mfma_f32_16x16x32_bf16 v[86:89], v[238:241], v[214:217], v[86:89]
	v_mfma_f32_16x16x32_bf16 v[82:85], v[242:245], v[214:217], v[82:85]
	v_mfma_f32_16x16x32_bf16 v[78:81], v[230:233], v[218:221], v[78:81]
	v_mfma_f32_16x16x32_bf16 v[74:77], v[234:237], v[218:221], v[74:77]
	v_mfma_f32_16x16x32_bf16 v[70:73], v[238:241], v[218:221], v[70:73]
	v_mfma_f32_16x16x32_bf16 v[66:69], v[242:245], v[218:221], v[66:69]
	v_mfma_f32_16x16x32_bf16 v[62:65], v[230:233], v[222:225], v[62:65]
	v_mfma_f32_16x16x32_bf16 v[58:61], v[234:237], v[222:225], v[58:61]
	v_mfma_f32_16x16x32_bf16 v[54:57], v[238:241], v[222:225], v[54:57]
	v_mfma_f32_16x16x32_bf16 v[50:53], v[242:245], v[222:225], v[50:53]
	v_mfma_f32_16x16x32_bf16 v[46:49], v[230:233], v[226:229], v[46:49]
	v_mfma_f32_16x16x32_bf16 v[42:45], v[234:237], v[226:229], v[42:45]
	v_mfma_f32_16x16x32_bf16 v[38:41], v[238:241], v[226:229], v[38:41]
	v_mfma_f32_16x16x32_bf16 v[34:37], v[242:245], v[226:229], v[34:37]
	s_waitcnt vmcnt(4)
	ds_write_b128 v191, v[14:17] offset:32768
	ds_write_b128 v191, v[2:5] offset:40960
	ds_write_b128 v191, v[6:9] offset:49152
	ds_write_b128 v191, v[10:13] offset:57344
	s_add_u32 s58, s56, s0
	s_addc_u32 s59, s57, s1
	global_load_dwordx4 v[14:17], v179, s[58:59]
	global_load_dwordx4 v[2:5], v177, s[58:59]
	global_load_dwordx4 v[6:9], v175, s[58:59]
	global_load_dwordx4 v[10:13], v173, s[58:59]
	v_add_u32_e32 v202, s2, v176
	ds_read_b128 v[192:195], v202
	ds_read_b128 v[198:201], v202 offset:2048
	ds_read_b128 v[206:209], v202 offset:4096
	ds_read_b128 v[210:213], v202 offset:6144
	ds_read_b128 v[214:217], v202 offset:8192
	ds_read_b128 v[218:221], v202 offset:10240
	ds_read_b128 v[222:225], v202 offset:12288
	ds_read_b128 v[226:229], v202 offset:14336
	v_add_u32_e32 v191, s2, v178
	ds_read_b128 v[230:233], v191 offset:32768
	ds_read_b128 v[234:237], v191 offset:34816
	ds_read_b128 v[238:241], v191 offset:36864
	ds_read_b128 v[242:245], v191 offset:38912
	s_cmp_lg_u32 s101, 0
	s_cbranch_scc1 .Lstg_778_b
; DI f32x4 mfma16(bf16x8 a, bf16x8 b, f32x4 c) { return __builtin_amdgcn_mfma_f32_16x16x32_bf16(a, b, c, 0, 0, 0); }
; #pragma unroll
;   for (int ks = KS0; ks < KS1; ++ks) {
;     bf16x8 af[8], bfr[4];
; #pragma unroll
;     for (int i = 0; i < 8; ++i) {
;       const int r = wm * 128 + i * 16 + (lane & 15);
;       af[i] = *(const bf16x8*)(S + r * 64 + (((ks * 4 + (lane >> 4)) ^ ((r >> 1) & 7)) << 3));
;     }
; #pragma unroll
;     for (int j = 0; j < 4; ++j) {
;       const int r = wn * 64 + j * 16 + (lane & 15);
;       bfr[j] = *(const bf16x8*)(S + 16384 + r * 64 + (((ks * 4 + (lane >> 4)) ^ ((r >> 1) & 7)) << 3));
;     }
;     __builtin_amdgcn_s_setprio(1);
; #pragma unroll
;     for (int i = 0; i < 8; ++i)
; #pragma unroll
;       for (int j = 0; j < 4; ++j) acc[i][j] = mfma16(bfr[j], af[i], acc[i][j]);
;     __builtin_amdgcn_s_setprio(0);
;   }
; }
; DI void gemm8_accum(f32x4 (&acc)[8][4], const bf16_t* a, size_t lda, const bf16_t* b, size_t ldb, int nkb, bf16_t* L,
;                     const bool pre, const bf16_t* an, size_t ldan, const bf16_t* bn, size_t ldbn) {
;     ...
;   for (int kb = 0; kb + 2 < nkb; ++kb) {
;     __syncthreads();
;     g8_store1(L + ((kb + 1) & 1) * 32768, ra, lrow, lch);
;     g8_load1o(ra, a + (kb + 2) * 64, offa);
;     __builtin_amdgcn_sched_barrier(0);
;     g8_compute<0, 1>(acc, L + (kb & 1) * 32768, wm, wn, lane);
;     __builtin_amdgcn_sched_barrier(0);
;     g8_store1(L + ((kb + 1) & 1) * 32768 + 16384, rb, lrow, lch);
;     g8_load1o(rb, b + (kb + 2) * 64, offb);
;     __builtin_amdgcn_sched_barrier(0);
;     g8_compute<1, 2>(acc, L + (kb & 1) * 32768, wm, wn, lane);
;   }
	s_waitcnt lgkmcnt(3)
	v_mfma_f32_16x16x32_bf16 v[158:161], v[230:233], v[192:195], v[158:161]
	s_waitcnt lgkmcnt(2)
	v_mfma_f32_16x16x32_bf16 v[154:157], v[234:237], v[192:195], v[154:157]
	s_waitcnt lgkmcnt(1)
	v_mfma_f32_16x16x32_bf16 v[150:153], v[238:241], v[192:195], v[150:153]
	s_waitcnt lgkmcnt(0)
	v_mfma_f32_16x16x32_bf16 v[146:149], v[242:245], v[192:195], v[146:149]
	v_mfma_f32_16x16x32_bf16 v[142:145], v[230:233], v[198:201], v[142:145]
	v_mfma_f32_16x16x32_bf16 v[138:141], v[234:237], v[198:201], v[138:141]
	v_mfma_f32_16x16x32_bf16 v[134:137], v[238:241], v[198:201], v[134:137]
	v_mfma_f32_16x16x32_bf16 v[130:133], v[242:245], v[198:201], v[130:133]
	v_mfma_f32_16x16x32_bf16 v[126:129], v[230:233], v[206:209], v[126:129]
	v_mfma_f32_16x16x32_bf16 v[122:125], v[234:237], v[206:209], v[122:125]
	v_mfma_f32_16x16x32_bf16 v[118:121], v[238:241], v[206:209], v[118:121]
	v_mfma_f32_16x16x32_bf16 v[114:117], v[242:245], v[206:209], v[114:117]
	v_mfma_f32_16x16x32_bf16 v[110:113], v[230:233], v[210:213], v[110:113]
	v_mfma_f32_16x16x32_bf16 v[106:109], v[234:237], v[210:213], v[106:109]
	v_mfma_f32_16x16x32_bf16 v[102:105], v[238:241], v[210:213], v[102:105]
	v_mfma_f32_16x16x32_bf16 v[98:101], v[242:245], v[210:213], v[98:101]
	v_mfma_f32_16x16x32_bf16 v[94:97], v[230:233], v[214:217], v[94:97]
	v_mfma_f32_16x16x32_bf16 v[90:93], v[234:237], v[214:217], v[90:93]
	v_mfma_f32_16x16x32_bf16 v[86:89], v[238:241], v[214:217], v[86:89]
	v_mfma_f32_16x16x32_bf16 v[82:85], v[242:245], v[214:217], v[82:85]
	v_mfma_f32_16x16x32_bf16 v[78:81], v[230:233], v[218:221], v[78:81]
	v_mfma_f32_16x16x32_bf16 v[74:77], v[234:237], v[218:221], v[74:77]
	v_mfma_f32_16x16x32_bf16 v[70:73], v[238:241], v[218:221], v[70:73]
	v_mfma_f32_16x16x32_bf16 v[66:69], v[242:245], v[218:221], v[66:69]
	v_mfma_f32_16x16x32_bf16 v[62:65], v[230:233], v[222:225], v[62:65]
	v_mfma_f32_16x16x32_bf16 v[58:61], v[234:237], v[222:225], v[58:61]
	v_mfma_f32_16x16x32_bf16 v[54:57], v[238:241], v[222:225], v[54:57]
	v_mfma_f32_16x16x32_bf16 v[50:53], v[242:245], v[222:225], v[50:53]
	v_mfma_f32_16x16x32_bf16 v[46:49], v[230:233], v[226:229], v[46:49]
	v_mfma_f32_16x16x32_bf16 v[42:45], v[234:237], v[226:229], v[42:45]
	v_mfma_f32_16x16x32_bf16 v[38:41], v[238:241], v[226:229], v[38:41]
	v_mfma_f32_16x16x32_bf16 v[34:37], v[242:245], v[226:229], v[34:37]
.Lstg_778_b:
	s_mov_b32 s100, s101
	s_xor_b32 s2, s2, 0x10000
	s_add_u32 s0, s0, 0x80
	s_addc_u32 s1, s1, 0
	s_cmpk_lg_i32 s0, 0x300
	s_cbranch_scc1 .LBB0_778
	s_cmp_eq_u32 s100, 0
	s_cbranch_scc1 .Lstg_778_c
	s_waitcnt lgkmcnt(0)
	v_mfma_f32_16x16x32_bf16 v[158:161], v[230:233], v[192:195], v[158:161]
	v_mfma_f32_16x16x32_bf16 v[154:157], v[234:237], v[192:195], v[154:157]
	v_mfma_f32_16x16x32_bf16 v[150:153], v[238:241], v[192:195], v[150:153]
	v_mfma_f32_16x16x32_bf16 v[146:149], v[242:245], v[192:195], v[146:149]
	v_mfma_f32_16x16x32_bf16 v[142:145], v[230:233], v[198:201], v[142:145]
	v_mfma_f32_16x16x32_bf16 v[138:141], v[234:237], v[198:201], v[138:141]
	v_mfma_f32_16x16x32_bf16 v[134:137], v[238:241], v[198:201], v[134:137]
	v_mfma_f32_16x16x32_bf16 v[130:133], v[242:245], v[198:201], v[130:133]
	v_mfma_f32_16x16x32_bf16 v[126:129], v[230:233], v[206:209], v[126:129]
	v_mfma_f32_16x16x32_bf16 v[122:125], v[234:237], v[206:209], v[122:125]
	v_mfma_f32_16x16x32_bf16 v[118:121], v[238:241], v[206:209], v[118:121]
	v_mfma_f32_16x16x32_bf16 v[114:117], v[242:245], v[206:209], v[114:117]
	v_mfma_f32_16x16x32_bf16 v[110:113], v[230:233], v[210:213], v[110:113]
	v_mfma_f32_16x16x32_bf16 v[106:109], v[234:237], v[210:213], v[106:109]
	v_mfma_f32_16x16x32_bf16 v[102:105], v[238:241], v[210:213], v[102:105]
	v_mfma_f32_16x16x32_bf16 v[98:101], v[242:245], v[210:213], v[98:101]
	v_mfma_f32_16x16x32_bf16 v[94:97], v[230:233], v[214:217], v[94:97]
	v_mfma_f32_16x16x32_bf16 v[90:93], v[234:237], v[214:217], v[90:93]
	v_mfma_f32_16x16x32_bf16 v[86:89], v[238:241], v[214:217], v[86:89]
	v_mfma_f32_16x16x32_bf16 v[82:85], v[242:245], v[214:217], v[82:85]
	v_mfma_f32_16x16x32_bf16 v[78:81], v[230:233], v[218:221], v[78:81]
	v_mfma_f32_16x16x32_bf16 v[74:77], v[234:237], v[218:221], v[74:77]
	v_mfma_f32_16x16x32_bf16 v[70:73], v[238:241], v[218:221], v[70:73]
	v_mfma_f32_16x16x32_bf16 v[66:69], v[242:245], v[218:221], v[66:69]
	v_mfma_f32_16x16x32_bf16 v[62:65], v[230:233], v[222:225], v[62:65]
	v_mfma_f32_16x16x32_bf16 v[58:61], v[234:237], v[222:225], v[58:61]
	v_mfma_f32_16x16x32_bf16 v[54:57], v[238:241], v[222:225], v[54:57]
	v_mfma_f32_16x16x32_bf16 v[50:53], v[242:245], v[222:225], v[50:53]
	v_mfma_f32_16x16x32_bf16 v[46:49], v[230:233], v[226:229], v[46:49]
	v_mfma_f32_16x16x32_bf16 v[42:45], v[234:237], v[226:229], v[42:45]
	v_mfma_f32_16x16x32_bf16 v[38:41], v[238:241], v[226:229], v[38:41]
	v_mfma_f32_16x16x32_bf16 v[34:37], v[242:245], v[226:229], v[34:37]
	s_mov_b32 s100, 0
; DI void gemm8_accum(f32x4 (&acc)[8][4], const bf16_t* a, size_t lda, const bf16_t* b, size_t ldb, int nkb, bf16_t* L,
;                     const bool pre, const bf16_t* an, size_t ldan, const bf16_t* bn, size_t ldbn) {
;     ...
;   __syncthreads();
;   g8_store1(L + 32768, ra, lrow, lch);
;   g8_load1(ra, an, ldan, 0, lrow, lch);
;   __builtin_amdgcn_sched_barrier(0);
;   g8_compute<0, 1>(acc, L, wm, wn, lane);
;   __builtin_amdgcn_sched_barrier(0);
;   g8_store1(L + 32768 + 16384, rb, lrow, lch);
;   g8_load1(rb, bn, ldbn, 0, lrow, lch);
;   __builtin_amdgcn_sched_barrier(0);
;   g8_compute<1, 2>(acc, L, wm, wn, lane);
;   __syncthreads();
;   g8_store1(L, ra, lrow, lch);
;   __builtin_amdgcn_sched_barrier(0);
;   g8_compute<0, 1>(acc, L + 32768, wm, wn, lane);
;   __builtin_amdgcn_sched_barrier(0);
;   g8_store1(L + 16384, rb, lrow, lch);
;   __builtin_amdgcn_sched_barrier(0);
;   g8_compute<1, 2>(acc, L + 32768, wm, wn, lane);
;   __syncthreads();
; }
.Lstg_778_c:
	s_mul_i32 s0, s13, 0x2a30
	s_movk_i32 s25, 0x1518
	s_add_u32 s2, s16, s0
	v_mad_u64_u32 v[180:181], s[0:1], v190, s25, v[170:171]
	s_addc_u32 s3, s17, 0
	v_mov_b32_e32 v181, v1
	v_lshl_add_u64 v[172:173], v[180:181], 1, s[2:3]
	v_add_u32_e32 v174, 0x54600, v180
	v_mov_b32_e32 v175, v1
	v_add_u32_e32 v182, 0xa8c00, v180
	v_mov_b32_e32 v183, v1
	v_add_u32_e32 v180, 0xfd200, v180
	v_lshl_add_u64 v[176:177], v[174:175], 1, s[2:3]
	v_lshl_add_u64 v[182:183], v[182:183], 1, s[2:3]
	v_lshl_add_u64 v[184:185], v[180:181], 1, s[2:3]
	s_barrier
	global_load_dwordx4 v[172:175], v[172:173], off offset:2608
	s_nop 0
	global_load_dwordx4 v[176:179], v[176:177], off offset:2608
	s_nop 0
	global_load_dwordx4 v[180:183], v[182:183], off offset:2608
	s_nop 0
	global_load_dwordx4 v[184:187], v[184:185], off offset:2608
	s_mul_i32 s0, s7, 0x2a3000
	s_lshl_b32 s1, s6, 1
	v_readlane_b32 s6, v252, 1
	v_readlane_b32 s7, v252, 2
	s_add_u32 s6, s6, s1
	s_addc_u32 s7, s7, 0
	s_add_i32 s20, 0, 0x10000
	v_add3_u32 v170, s20, v165, v167
	s_waitcnt vmcnt(11)
	ds_write_b128 v170, v[22:25]
	s_waitcnt vmcnt(9)
	ds_write_b128 v170, v[18:21] offset:8192
	ds_write_b128 v170, v[26:29] offset:16384
	s_waitcnt vmcnt(8)
	ds_write_b128 v170, v[30:33] offset:24576
	v_lshlrev_b32_e32 v170, 1, v169
	v_add_u32_e32 v169, 0, v170
	v_add_u32_e32 v194, v169, v188
	ds_read_b128 v[18:21], v194
	ds_read_b128 v[22:25], v194 offset:2048
	ds_read_b128 v[26:29], v194 offset:4096
	ds_read_b128 v[30:33], v194 offset:6144
	ds_read_b128 v[190:193], v194 offset:8192
	ds_read_b128 v[198:201], v194 offset:10240
	ds_read_b128 v[206:209], v194 offset:12288
	ds_read_b128 v[210:213], v194 offset:14336
	v_add_u32_e32 v169, v169, v171
	ds_read_b128 v[214:217], v169 offset:32768
	ds_read_b128 v[218:221], v169 offset:34816
	ds_read_b128 v[222:225], v169 offset:36864
	ds_read_b128 v[226:229], v169 offset:38912
	s_waitcnt lgkmcnt(3)
	v_mfma_f32_16x16x32_bf16 v[158:161], v[214:217], v[18:21], v[158:161]
	s_waitcnt lgkmcnt(2)
	v_mfma_f32_16x16x32_bf16 v[154:157], v[218:221], v[18:21], v[154:157]
	s_waitcnt lgkmcnt(1)
	v_mfma_f32_16x16x32_bf16 v[150:153], v[222:225], v[18:21], v[150:153]
	s_waitcnt lgkmcnt(0)
	v_mfma_f32_16x16x32_bf16 v[18:21], v[226:229], v[18:21], v[146:149]
	v_mfma_f32_16x16x32_bf16 v[142:145], v[214:217], v[22:25], v[142:145]
	v_mfma_f32_16x16x32_bf16 v[138:141], v[218:221], v[22:25], v[138:141]
	v_mfma_f32_16x16x32_bf16 v[134:137], v[222:225], v[22:25], v[134:137]
	v_mfma_f32_16x16x32_bf16 v[22:25], v[226:229], v[22:25], v[130:133]
	v_mfma_f32_16x16x32_bf16 v[126:129], v[214:217], v[26:29], v[126:129]
	v_mfma_f32_16x16x32_bf16 v[122:125], v[218:221], v[26:29], v[122:125]
	v_mfma_f32_16x16x32_bf16 v[118:121], v[222:225], v[26:29], v[118:121]
	v_mfma_f32_16x16x32_bf16 v[26:29], v[226:229], v[26:29], v[114:117]
	v_mfma_f32_16x16x32_bf16 v[110:113], v[214:217], v[30:33], v[110:113]
	v_mfma_f32_16x16x32_bf16 v[106:109], v[218:221], v[30:33], v[106:109]
	v_mfma_f32_16x16x32_bf16 v[102:105], v[222:225], v[30:33], v[102:105]
	v_mfma_f32_16x16x32_bf16 v[30:33], v[226:229], v[30:33], v[98:101]
	v_mfma_f32_16x16x32_bf16 v[94:97], v[214:217], v[190:193], v[94:97]
	v_mfma_f32_16x16x32_bf16 v[90:93], v[218:221], v[190:193], v[90:93]
	v_mfma_f32_16x16x32_bf16 v[86:89], v[222:225], v[190:193], v[86:89]
	v_mfma_f32_16x16x32_bf16 v[82:85], v[226:229], v[190:193], v[82:85]
	v_mfma_f32_16x16x32_bf16 v[78:81], v[214:217], v[198:201], v[78:81]
	v_mfma_f32_16x16x32_bf16 v[74:77], v[218:221], v[198:201], v[74:77]
	v_mfma_f32_16x16x32_bf16 v[70:73], v[222:225], v[198:201], v[70:73]
	v_mfma_f32_16x16x32_bf16 v[66:69], v[226:229], v[198:201], v[66:69]
	v_mfma_f32_16x16x32_bf16 v[62:65], v[214:217], v[206:209], v[62:65]
	v_mfma_f32_16x16x32_bf16 v[58:61], v[218:221], v[206:209], v[58:61]
	v_mfma_f32_16x16x32_bf16 v[54:57], v[222:225], v[206:209], v[54:57]
	v_mfma_f32_16x16x32_bf16 v[50:53], v[226:229], v[206:209], v[50:53]
	v_mfma_f32_16x16x32_bf16 v[46:49], v[214:217], v[210:213], v[46:49]
	v_mfma_f32_16x16x32_bf16 v[42:45], v[218:221], v[210:213], v[42:45]
	v_mfma_f32_16x16x32_bf16 v[38:41], v[222:225], v[210:213], v[38:41]
	v_mfma_f32_16x16x32_bf16 v[34:37], v[226:229], v[210:213], v[34:37]
	v_readlane_b32 s1, v254, 36
	v_mov_b32_e32 v169, v1
	s_nop 0
	v_add3_u32 v98, s1, v165, v167
	v_mov_b32_e32 v167, v1
	v_mov_b32_e32 v165, v1
	s_waitcnt vmcnt(7)
	ds_write_b128 v98, v[14:17]
	s_waitcnt vmcnt(6)
	ds_write_b128 v98, v[2:5] offset:8192
	s_waitcnt vmcnt(5)
	ds_write_b128 v98, v[6:9] offset:16384
	s_waitcnt vmcnt(4)
	ds_write_b128 v98, v[10:13] offset:24576
	v_lshl_add_u64 v[2:3], v[0:1], 1, s[6:7]
	v_lshl_add_u64 v[6:7], v[168:169], 1, s[6:7]
	v_lshl_add_u64 v[10:11], v[166:167], 1, s[6:7]
	v_lshl_add_u64 v[14:15], v[164:165], 1, s[6:7]
	global_load_dwordx4 v[2:5], v[2:3], off
	s_nop 0
	global_load_dwordx4 v[6:9], v[6:7], off
	s_nop 0
	global_load_dwordx4 v[10:13], v[10:11], off
	s_nop 0
	global_load_dwordx4 v[14:17], v[14:15], off
	v_lshlrev_b32_e32 v0, 1, v189
	v_add_u32_e32 v168, 0, v0
	v_add_u32_e32 v169, v168, v188
	ds_read_b128 v[98:101], v169
	ds_read_b128 v[114:117], v169 offset:2048
	ds_read_b128 v[130:133], v169 offset:4096
	ds_read_b128 v[146:149], v169 offset:6144
	ds_read_b128 v[164:167], v169 offset:8192
	ds_read_b128 v[190:193], v169 offset:10240
	ds_read_b128 v[198:201], v169 offset:12288
	ds_read_b128 v[206:209], v169 offset:14336
	v_add_u32_e32 v168, v168, v171
	ds_read_b128 v[210:213], v168 offset:32768
	ds_read_b128 v[214:217], v168 offset:34816
	ds_read_b128 v[218:221], v168 offset:36864
	ds_read_b128 v[222:225], v168 offset:38912
	s_waitcnt lgkmcnt(3)
; DI void gemm8_accum(f32x4 (&acc)[8][4], const bf16_t* a, size_t lda, const bf16_t* b, size_t ldb, int nkb, bf16_t* L,
;                     const bool pre, const bf16_t* an, size_t ldan, const bf16_t* bn, size_t ldbn) {
;     ...
;   __syncthreads();
;   g8_store1(L + 32768, ra, lrow, lch);
;   g8_load1(ra, an, ldan, 0, lrow, lch);
;   __builtin_amdgcn_sched_barrier(0);
;   g8_compute<0, 1>(acc, L, wm, wn, lane);
;   __builtin_amdgcn_sched_barrier(0);
;   g8_store1(L + 32768 + 16384, rb, lrow, lch);
;   g8_load1(rb, bn, ldbn, 0, lrow, lch);
;   __builtin_amdgcn_sched_barrier(0);
;   g8_compute<1, 2>(acc, L, wm, wn, lane);
;   __syncthreads();
;   g8_store1(L, ra, lrow, lch);
;   __builtin_amdgcn_sched_barrier(0);
;   g8_compute<0, 1>(acc, L + 32768, wm, wn, lane);
;   __builtin_amdgcn_sched_barrier(0);
;   g8_store1(L + 16384, rb, lrow, lch);
;   __builtin_amdgcn_sched_barrier(0);
;   g8_compute<1, 2>(acc, L + 32768, wm, wn, lane);
;   __syncthreads();
; }
	v_mfma_f32_16x16x32_bf16 v[158:161], v[210:213], v[98:101], v[158:161]
	s_waitcnt lgkmcnt(2)
	v_mfma_f32_16x16x32_bf16 v[154:157], v[214:217], v[98:101], v[154:157]
	s_waitcnt lgkmcnt(1)
	v_mfma_f32_16x16x32_bf16 v[150:153], v[218:221], v[98:101], v[150:153]
	s_waitcnt lgkmcnt(0)
	v_mfma_f32_16x16x32_bf16 v[18:21], v[222:225], v[98:101], v[18:21]
	v_mfma_f32_16x16x32_bf16 v[98:101], v[210:213], v[114:117], v[142:145]
	v_mfma_f32_16x16x32_bf16 v[138:141], v[214:217], v[114:117], v[138:141]
	v_mfma_f32_16x16x32_bf16 v[134:137], v[218:221], v[114:117], v[134:137]
	v_mfma_f32_16x16x32_bf16 v[22:25], v[222:225], v[114:117], v[22:25]
	v_mfma_f32_16x16x32_bf16 v[114:117], v[210:213], v[130:133], v[126:129]
	v_mfma_f32_16x16x32_bf16 v[122:125], v[214:217], v[130:133], v[122:125]
	v_mfma_f32_16x16x32_bf16 v[118:121], v[218:221], v[130:133], v[118:121]
	v_mfma_f32_16x16x32_bf16 v[26:29], v[222:225], v[130:133], v[26:29]
	v_mfma_f32_16x16x32_bf16 v[110:113], v[210:213], v[146:149], v[110:113]
	v_mfma_f32_16x16x32_bf16 v[106:109], v[214:217], v[146:149], v[106:109]
	v_mfma_f32_16x16x32_bf16 v[102:105], v[218:221], v[146:149], v[102:105]
	v_mfma_f32_16x16x32_bf16 v[30:33], v[222:225], v[146:149], v[30:33]
	v_mfma_f32_16x16x32_bf16 v[94:97], v[210:213], v[164:167], v[94:97]
	v_mfma_f32_16x16x32_bf16 v[90:93], v[214:217], v[164:167], v[90:93]
	v_mfma_f32_16x16x32_bf16 v[86:89], v[218:221], v[164:167], v[86:89]
	v_mfma_f32_16x16x32_bf16 v[82:85], v[222:225], v[164:167], v[82:85]
	v_mfma_f32_16x16x32_bf16 v[78:81], v[210:213], v[190:193], v[78:81]
	v_mfma_f32_16x16x32_bf16 v[74:77], v[214:217], v[190:193], v[74:77]
	v_mfma_f32_16x16x32_bf16 v[70:73], v[218:221], v[190:193], v[70:73]
	v_mfma_f32_16x16x32_bf16 v[66:69], v[222:225], v[190:193], v[66:69]
	v_mfma_f32_16x16x32_bf16 v[62:65], v[210:213], v[198:201], v[62:65]
	v_mfma_f32_16x16x32_bf16 v[58:61], v[214:217], v[198:201], v[58:61]
	v_mfma_f32_16x16x32_bf16 v[54:57], v[218:221], v[198:201], v[54:57]
	v_mfma_f32_16x16x32_bf16 v[50:53], v[222:225], v[198:201], v[50:53]
	v_mfma_f32_16x16x32_bf16 v[46:49], v[210:213], v[206:209], v[46:49]
	v_mfma_f32_16x16x32_bf16 v[42:45], v[214:217], v[206:209], v[42:45]
	v_mfma_f32_16x16x32_bf16 v[38:41], v[218:221], v[206:209], v[38:41]
	v_mfma_f32_16x16x32_bf16 v[34:37], v[222:225], v[206:209], v[34:37]
	s_barrier
	s_waitcnt vmcnt(7)
	ds_write_b128 v163, v[172:175]
	s_waitcnt vmcnt(6)
	ds_write_b128 v163, v[176:179] offset:8192
	s_waitcnt vmcnt(5)
	ds_write_b128 v163, v[180:183] offset:16384
	s_waitcnt vmcnt(4)
	ds_write_b128 v163, v[184:187] offset:24576
	v_add3_u32 v168, s20, v170, v188
	ds_read_b128 v[126:129], v168
	ds_read_b128 v[130:133], v168 offset:2048
	ds_read_b128 v[142:145], v168 offset:4096
	ds_read_b128 v[146:149], v168 offset:6144
	ds_read_b128 v[164:167], v168 offset:8192
	ds_read_b128 v[172:175], v168 offset:10240
	ds_read_b128 v[176:179], v168 offset:12288
	ds_read_b128 v[180:183], v168 offset:14336
	v_add3_u32 v168, s1, v170, v171
	ds_read_b128 v[184:187], v168
	ds_read_b128 v[190:193], v168 offset:2048
	ds_read_b128 v[198:201], v168 offset:4096
	ds_read_b128 v[206:209], v168 offset:6144
	s_waitcnt lgkmcnt(3)
	v_mfma_f32_16x16x32_bf16 v[158:161], v[184:187], v[126:129], v[158:161]
	s_waitcnt lgkmcnt(2)
	v_mfma_f32_16x16x32_bf16 v[154:157], v[190:193], v[126:129], v[154:157]
	s_waitcnt lgkmcnt(1)
	v_mfma_f32_16x16x32_bf16 v[150:153], v[198:201], v[126:129], v[150:153]
	s_waitcnt lgkmcnt(0)
	v_mfma_f32_16x16x32_bf16 v[18:21], v[206:209], v[126:129], v[18:21]
	v_mfma_f32_16x16x32_bf16 v[98:101], v[184:187], v[130:133], v[98:101]
	v_mfma_f32_16x16x32_bf16 v[126:129], v[190:193], v[130:133], v[138:141]
	v_mfma_f32_16x16x32_bf16 v[134:137], v[198:201], v[130:133], v[134:137]
	v_mfma_f32_16x16x32_bf16 v[130:133], v[206:209], v[130:133], v[22:25]
	v_mfma_f32_16x16x32_bf16 v[114:117], v[184:187], v[142:145], v[114:117]
	v_mfma_f32_16x16x32_bf16 v[122:125], v[190:193], v[142:145], v[122:125]
	v_mfma_f32_16x16x32_bf16 v[118:121], v[198:201], v[142:145], v[118:121]
	v_mfma_f32_16x16x32_bf16 v[26:29], v[206:209], v[142:145], v[26:29]
	v_mfma_f32_16x16x32_bf16 v[110:113], v[184:187], v[146:149], v[110:113]
	v_mfma_f32_16x16x32_bf16 v[106:109], v[190:193], v[146:149], v[106:109]
	v_mfma_f32_16x16x32_bf16 v[102:105], v[198:201], v[146:149], v[102:105]
	v_mfma_f32_16x16x32_bf16 v[138:141], v[206:209], v[146:149], v[30:33]
	v_mfma_f32_16x16x32_bf16 v[142:145], v[184:187], v[164:167], v[94:97]
	v_mfma_f32_16x16x32_bf16 v[90:93], v[190:193], v[164:167], v[90:93]
	v_mfma_f32_16x16x32_bf16 v[146:149], v[198:201], v[164:167], v[86:89]
	v_mfma_f32_16x16x32_bf16 v[82:85], v[206:209], v[164:167], v[82:85]
	v_mfma_f32_16x16x32_bf16 v[164:167], v[184:187], v[172:175], v[78:81]
	v_mfma_f32_16x16x32_bf16 v[74:77], v[190:193], v[172:175], v[74:77]
	v_mfma_f32_16x16x32_bf16 v[210:213], v[198:201], v[172:175], v[70:73]
	v_mfma_f32_16x16x32_bf16 v[66:69], v[206:209], v[172:175], v[66:69]
	v_mfma_f32_16x16x32_bf16 v[172:175], v[184:187], v[176:179], v[62:65]
	v_mfma_f32_16x16x32_bf16 v[58:61], v[190:193], v[176:179], v[58:61]
	v_mfma_f32_16x16x32_bf16 v[214:217], v[198:201], v[176:179], v[54:57]
	v_mfma_f32_16x16x32_bf16 v[50:53], v[206:209], v[176:179], v[50:53]
	v_mfma_f32_16x16x32_bf16 v[176:179], v[184:187], v[180:183], v[46:49]
	v_mfma_f32_16x16x32_bf16 v[184:187], v[190:193], v[180:183], v[42:45]
	v_mfma_f32_16x16x32_bf16 v[190:193], v[198:201], v[180:183], v[38:41]
	v_mfma_f32_16x16x32_bf16 v[180:183], v[206:209], v[180:183], v[34:37]
	s_waitcnt vmcnt(3)
	ds_write_b128 v163, v[2:5] offset:32768
	s_waitcnt vmcnt(2)
	ds_write_b128 v163, v[6:9] offset:40960
	s_waitcnt vmcnt(1)
; DI float bflo(unsigned u) { return __uint_as_float(u << 16); }
; DI float bfhi(unsigned u) { return __uint_as_float(u & 0xffff0000u); }
; DI float sigmoidf(float x) { return __builtin_amdgcn_rcpf(1.f + __expf(-x)); }
; DI float inv_sigmoidf(float x) { return 1.f + __expf(-x); }
; DI void gemm8_accum(f32x4 (&acc)[8][4], const bf16_t* a, size_t lda, const bf16_t* b, size_t ldb, int nkb, bf16_t* L,
;                     const bool pre, const bf16_t* an, size_t ldan, const bf16_t* bn, size_t ldbn) {
;     ...
;   g8_compute<1, 2>(acc, L, wm, wn, lane);
;   __syncthreads();
;   g8_store1(L, ra, lrow, lch);
;   __builtin_amdgcn_sched_barrier(0);
;   g8_compute<0, 1>(acc, L + 32768, wm, wn, lane);
;   __builtin_amdgcn_sched_barrier(0);
;   g8_store1(L + 16384, rb, lrow, lch);
;   __builtin_amdgcn_sched_barrier(0);
;   g8_compute<1, 2>(acc, L + 32768, wm, wn, lane);
;   __syncthreads();
; __global__ void __launch_bounds__(512, 2) mega(Params p) {
;     ...
;       gemm8_epi(acc8, m0, n0, [&](int m, int n, f32x4& a) {
;         uint2 ua = *(const uint2*)(z + (size_t)m * ZS + C_MA + n);
;         uint2 ub = *(const uint2*)(z + (size_t)m * ZS + C_MB + n);
;         a[0] *= sigmoidf(bflo(ua.x)) * inv_sigmoidf(bflo(ub.x));
;         a[1] *= sigmoidf(bfhi(ua.x)) * inv_sigmoidf(bfhi(ub.x));
;         a[2] *= sigmoidf(bflo(ua.y)) * inv_sigmoidf(bflo(ub.y));
;         a[3] *= sigmoidf(bfhi(ua.y)) * inv_sigmoidf(bfhi(ub.y));
;       });
	ds_write_b128 v163, v[10:13] offset:49152
	s_waitcnt vmcnt(0)
	ds_write_b128 v163, v[14:17] offset:57344
	v_add3_u32 v6, s20, v0, v188
	ds_read_b128 v[2:5], v6
	ds_read_b128 v[34:37], v6 offset:2048
	ds_read_b128 v[42:45], v6 offset:4096
	ds_read_b128 v[198:201], v6 offset:6144
	ds_read_b128 v[206:209], v6 offset:8192
	ds_read_b128 v[218:221], v6 offset:10240
	ds_read_b128 v[222:225], v6 offset:12288
	ds_read_b128 v[226:229], v6 offset:14336
	v_add3_u32 v0, s1, v0, v171
	ds_read_b128 v[168:171], v0
	ds_read_b128 v[230:233], v0 offset:2048
	ds_read_b128 v[234:237], v0 offset:4096
	ds_read_b128 v[238:241], v0 offset:6144
	s_waitcnt lgkmcnt(3)
	v_mfma_f32_16x16x32_bf16 v[158:161], v[168:171], v[2:5], v[158:161]
	s_waitcnt lgkmcnt(2)
	v_mfma_f32_16x16x32_bf16 v[6:9], v[230:233], v[2:5], v[154:157]
	s_waitcnt lgkmcnt(1)
	v_mfma_f32_16x16x32_bf16 v[10:13], v[234:237], v[2:5], v[150:153]
	s_waitcnt lgkmcnt(0)
	v_mfma_f32_16x16x32_bf16 v[14:17], v[238:241], v[2:5], v[18:21]
	v_mfma_f32_16x16x32_bf16 v[22:25], v[168:171], v[34:37], v[98:101]
	v_mfma_f32_16x16x32_bf16 v[30:33], v[230:233], v[34:37], v[126:129]
	v_mfma_f32_16x16x32_bf16 v[38:41], v[234:237], v[34:37], v[134:137]
	v_mfma_f32_16x16x32_bf16 v[46:49], v[238:241], v[34:37], v[130:133]
	v_mfma_f32_16x16x32_bf16 v[54:57], v[168:171], v[42:45], v[114:117]
	v_mfma_f32_16x16x32_bf16 v[62:65], v[230:233], v[42:45], v[122:125]
	v_mfma_f32_16x16x32_bf16 v[70:73], v[234:237], v[42:45], v[118:121]
	v_mfma_f32_16x16x32_bf16 v[78:81], v[238:241], v[42:45], v[26:29]
	v_mfma_f32_16x16x32_bf16 v[86:89], v[168:171], v[198:201], v[110:113]
	v_mfma_f32_16x16x32_bf16 v[94:97], v[230:233], v[198:201], v[106:109]
	v_mfma_f32_16x16x32_bf16 v[102:105], v[234:237], v[198:201], v[102:105]
	v_mfma_f32_16x16x32_bf16 v[110:113], v[238:241], v[198:201], v[138:141]
	v_mfma_f32_16x16x32_bf16 v[118:121], v[168:171], v[206:209], v[142:145]
	v_mfma_f32_16x16x32_bf16 v[126:129], v[230:233], v[206:209], v[90:93]
	v_mfma_f32_16x16x32_bf16 v[122:125], v[234:237], v[206:209], v[146:149]
	v_mfma_f32_16x16x32_bf16 v[114:117], v[238:241], v[206:209], v[82:85]
	v_mfma_f32_16x16x32_bf16 v[106:109], v[168:171], v[218:221], v[164:167]
	v_mfma_f32_16x16x32_bf16 v[98:101], v[230:233], v[218:221], v[74:77]
	v_mfma_f32_16x16x32_bf16 v[90:93], v[234:237], v[218:221], v[210:213]
	v_mfma_f32_16x16x32_bf16 v[82:85], v[238:241], v[218:221], v[66:69]
	v_mfma_f32_16x16x32_bf16 v[74:77], v[168:171], v[222:225], v[172:175]
	v_mfma_f32_16x16x32_bf16 v[66:69], v[230:233], v[222:225], v[58:61]
	v_mfma_f32_16x16x32_bf16 v[58:61], v[234:237], v[222:225], v[214:217]
	v_mfma_f32_16x16x32_bf16 v[50:53], v[238:241], v[222:225], v[50:53]
	v_mfma_f32_16x16x32_bf16 v[42:45], v[168:171], v[226:229], v[176:179]
	v_mfma_f32_16x16x32_bf16 v[34:37], v[230:233], v[226:229], v[184:187]
	v_mfma_f32_16x16x32_bf16 v[26:29], v[234:237], v[226:229], v[190:193]
	v_mfma_f32_16x16x32_bf16 v[18:21], v[238:241], v[226:229], v[180:183]
	v_mov_b32_e32 v0, v196
	s_barrier
	v_mov_b64_e32 v[136:137], s[16:17]
	v_ashrrev_i32_e32 v3, 1, v0
	v_and_b32_e32 v2, 0xc0, v0
	v_and_b32_e32 v3, 0xffffff80, v3
	v_and_or_b32 v4, v0, 15, s13
	v_lshrrev_b32_e32 v0, 2, v0
	v_add_u32_e32 v142, v4, v3
	v_and_b32_e32 v0, 12, v0
	v_or3_b32 v0, v2, v0, s12
	v_mad_i64_i32 v[2:3], s[26:27], v142, s35, v[136:137]
	s_mov_b64 s[30:31], 0x1a30
	s_mov_b64 s[42:43], 0x2230
	v_lshl_add_u64 v[138:139], v[2:3], 0, s[30:31]
	v_lshlrev_b32_e32 v0, 1, v0
	v_lshl_add_u64 v[140:141], v[2:3], 0, s[42:43]
	v_lshl_add_u64 v[4:5], v[138:139], 0, v[0:1]
	v_lshl_add_u64 v[2:3], v[140:141], 0, v[0:1]
	s_mov_b32 s88, 0x2a300
	s_mov_b32 s89, 0
	v_mov_b64_e32 v[246:247], v[4:5]
	global_load_dwordx2 v[198:199], v[246:247], off
	global_load_dwordx2 v[200:201], v[246:247], off offset:2048
	global_load_dwordx2 v[202:203], v[246:247], off offset:32
	global_load_dwordx2 v[204:205], v[246:247], off offset:2080
	global_load_dwordx2 v[206:207], v[246:247], off offset:64
	global_load_dwordx2 v[208:209], v[246:247], off offset:2112
	global_load_dwordx2 v[210:211], v[246:247], off offset:96
	global_load_dwordx2 v[212:213], v[246:247], off offset:2144
	v_lshl_add_u64 v[246:247], v[246:247], 0, s[88:89]
	global_load_dwordx2 v[214:215], v[246:247], off
	global_load_dwordx2 v[216:217], v[246:247], off offset:2048
	global_load_dwordx2 v[218:219], v[246:247], off offset:32
	global_load_dwordx2 v[220:221], v[246:247], off offset:2080
	global_load_dwordx2 v[222:223], v[246:247], off offset:64
	global_load_dwordx2 v[224:225], v[246:247], off offset:2112
	global_load_dwordx2 v[226:227], v[246:247], off offset:96
	global_load_dwordx2 v[228:229], v[246:247], off offset:2144
	v_lshl_add_u64 v[246:247], v[246:247], 0, s[88:89]
	global_load_dwordx2 v[230:231], v[246:247], off
	global_load_dwordx2 v[232:233], v[246:247], off offset:2048
	global_load_dwordx2 v[234:235], v[246:247], off offset:32
	global_load_dwordx2 v[236:237], v[246:247], off offset:2080
	global_load_dwordx2 v[238:239], v[246:247], off offset:64
	global_load_dwordx2 v[240:241], v[246:247], off offset:2112
	global_load_dwordx2 v[242:243], v[246:247], off offset:96
	global_load_dwordx2 v[244:245], v[246:247], off offset:2144
	s_waitcnt vmcnt(23)
	v_mov_b64_e32 v[4:5], v[198:199]
	v_lshl_add_u64 v[246:247], v[246:247], 0, s[88:89]
	global_load_dwordx2 v[198:199], v[246:247], off
	v_or_b32_e32 v134, 32, v0
	s_waitcnt vmcnt(23)
; DI float bflo(unsigned u) { return __uint_as_float(u << 16); }
; DI float bfhi(unsigned u) { return __uint_as_float(u & 0xffff0000u); }
; DI float sigmoidf(float x) { return __builtin_amdgcn_rcpf(1.f + __expf(-x)); }
; DI float inv_sigmoidf(float x) { return 1.f + __expf(-x); }
; DI int TID8() { int t = threadIdx.x; asm volatile("" : "+v"(t)); return t; }
; template <class E>
; DI void gemm8_epi(f32x4 (&acc)[8][4], int m0, int n0, E e) {
;   const int tid = TID8(), lane = tid & 63, w = tid >> 6;
;   const int wm = w >> 2, wn = w & 3;
; #pragma unroll
;   for (int i = 0; i < 8; ++i)
; #pragma unroll
;     for (int j = 0; j < 4; ++j) {
;       const int m = m0 + wm * 128 + i * 16 + (lane & 15);
;       const int n = n0 + wn * 64 + j * 16 + (lane >> 4) * 4;
;       e(m, n, acc[i][j]);
;     }
; }
; __global__ void __launch_bounds__(512, 2) mega(Params p) {
;     ...
;       gemm8_epi(acc8, m0, n0, [&](int m, int n, f32x4& a) {
;         uint2 ua = *(const uint2*)(z + (size_t)m * ZS + C_MA + n);
;         uint2 ub = *(const uint2*)(z + (size_t)m * ZS + C_MB + n);
;         a[0] *= sigmoidf(bflo(ua.x)) * inv_sigmoidf(bflo(ub.x));
;         a[1] *= sigmoidf(bfhi(ua.x)) * inv_sigmoidf(bfhi(ub.x));
;         a[2] *= sigmoidf(bflo(ua.y)) * inv_sigmoidf(bflo(ub.y));
;         a[3] *= sigmoidf(bfhi(ua.y)) * inv_sigmoidf(bfhi(ub.y));
;       });
	v_mov_b64_e32 v[2:3], v[200:201]
	global_load_dwordx2 v[200:201], v[246:247], off offset:2048
	v_mov_b32_e32 v135, v1
	v_mov_b32_e32 v172, v196
	s_movk_i32 s1, 0x3c0
	s_movk_i32 s96, 0x1518
	s_nop 0
	v_lshlrev_b32_e32 v130, 16, v4
	v_and_b32_e32 v4, 0xffff0000, v4
	s_nop 0
	v_lshlrev_b32_e32 v131, 16, v2
	v_and_b32_e32 v2, 0xffff0000, v2
	v_mul_f32_e32 v2, 0xbfb8aa3b, v2
	v_exp_f32_e32 v133, v2
	v_lshlrev_b32_e32 v2, 16, v5
	v_mul_f32_e32 v4, 0xbfb8aa3b, v4
	v_mul_f32_e32 v2, 0xbfb8aa3b, v2
	v_exp_f32_e32 v4, v4
	v_exp_f32_e32 v2, v2
	v_and_b32_e32 v5, 0xffff0000, v5
	v_mul_f32_e32 v130, 0xbfb8aa3b, v130
	v_mul_f32_e32 v5, 0xbfb8aa3b, v5
	v_exp_f32_e32 v130, v130
	v_exp_f32_e32 v5, v5
	v_mul_f32_e32 v131, 0xbfb8aa3b, v131
	v_add_f32_e32 v4, 1.0, v4
	v_add_f32_e32 v2, 1.0, v2
	v_exp_f32_e32 v132, v131
	v_rcp_f32_e32 v131, v4
	v_rcp_f32_e32 v4, v2
	v_lshlrev_b32_e32 v2, 16, v3
	v_and_b32_e32 v3, 0xffff0000, v3
	v_mul_f32_e32 v2, 0xbfb8aa3b, v2
	v_mul_f32_e32 v3, 0xbfb8aa3b, v3
	v_add_f32_e32 v130, 1.0, v130
	v_exp_f32_e32 v2, v2
	v_add_f32_e32 v5, 1.0, v5
	v_exp_f32_e32 v3, v3
	v_rcp_f32_e32 v130, v130
	v_rcp_f32_e32 v5, v5
	v_pk_add_f32 v[132:133], v[132:133], 1.0 op_sel_hi:[1,0]
	v_pk_add_f32 v[2:3], v[2:3], 1.0 op_sel_hi:[1,0]
	v_pk_mul_f32 v[130:131], v[130:131], v[132:133]
	v_pk_mul_f32 v[2:3], v[4:5], v[2:3]
	v_lshl_add_u64 v[132:133], v[140:141], 0, v[134:135]
	v_pk_mul_f32 v[4:5], v[160:161], v[2:3]
	v_pk_mul_f32 v[2:3], v[158:159], v[130:131]
	v_lshl_add_u64 v[130:131], v[138:139], 0, v[134:135]
	s_waitcnt vmcnt(23)
	v_mov_b64_e32 v[130:131], v[202:203]
	global_load_dwordx2 v[202:203], v[246:247], off offset:32
	s_nop 0
	s_waitcnt vmcnt(23)
	v_mov_b64_e32 v[132:133], v[204:205]
	global_load_dwordx2 v[204:205], v[246:247], off offset:2080
	s_nop 0
	v_lshlrev_b32_e32 v143, 16, v130
	v_and_b32_e32 v130, 0xffff0000, v130
	v_mul_f32_e32 v130, 0xbfb8aa3b, v130
	v_exp_f32_e32 v130, v130
	v_mul_f32_e32 v143, 0xbfb8aa3b, v143
	v_exp_f32_e32 v143, v143
	v_add_f32_e32 v130, 1.0, v130
	v_rcp_f32_e32 v145, v130
	s_nop 0
	v_and_b32_e32 v130, 0xffff0000, v132
	v_mul_f32_e32 v130, 0xbfb8aa3b, v130
	v_exp_f32_e32 v147, v130
	v_lshlrev_b32_e32 v130, 16, v131
	v_and_b32_e32 v131, 0xffff0000, v131
	v_mul_f32_e32 v130, 0xbfb8aa3b, v130
	v_mul_f32_e32 v131, 0xbfb8aa3b, v131
	v_exp_f32_e32 v130, v130
	v_exp_f32_e32 v131, v131
	v_add_f32_e32 v143, 1.0, v143
	v_rcp_f32_e32 v144, v143
	v_lshlrev_b32_e32 v143, 16, v132
	v_lshlrev_b32_e32 v132, 16, v133
	v_and_b32_e32 v133, 0xffff0000, v133
	v_mul_f32_e32 v132, 0xbfb8aa3b, v132
	v_mul_f32_e32 v133, 0xbfb8aa3b, v133
	v_add_f32_e32 v130, 1.0, v130
	v_exp_f32_e32 v132, v132
	v_add_f32_e32 v131, 1.0, v131
	v_exp_f32_e32 v133, v133
	v_rcp_f32_e32 v130, v130
	v_rcp_f32_e32 v131, v131
	v_mul_f32_e32 v143, 0xbfb8aa3b, v143
	v_pk_add_f32 v[132:133], v[132:133], 1.0 op_sel_hi:[1,0]
	v_exp_f32_e32 v146, v143
	v_pk_mul_f32 v[130:131], v[130:131], v[132:133]
	v_or_b32_e32 v132, 64, v0
	v_mov_b32_e32 v133, v1
	v_pk_mul_f32 v[8:9], v[8:9], v[130:131]
	v_lshl_add_u64 v[130:131], v[138:139], 0, v[132:133]
	s_waitcnt vmcnt(23)
	v_mov_b64_e32 v[130:131], v[206:207]
	global_load_dwordx2 v[206:207], v[246:247], off offset:64
	v_pk_add_f32 v[146:147], v[146:147], 1.0 op_sel_hi:[1,0]
	s_nop 0
	v_pk_mul_f32 v[144:145], v[144:145], v[146:147]
	s_nop 0
	v_pk_mul_f32 v[6:7], v[6:7], v[144:145]
	v_lshl_add_u64 v[144:145], v[140:141], 0, v[132:133]
	s_waitcnt vmcnt(23)
	v_mov_b64_e32 v[144:145], v[208:209]
	global_load_dwordx2 v[208:209], v[246:247], off offset:2112
	s_nop 0
	v_lshlrev_b32_e32 v143, 16, v130
	v_and_b32_e32 v130, 0xffff0000, v130
	v_mul_f32_e32 v130, 0xbfb8aa3b, v130
	v_exp_f32_e32 v130, v130
	v_mul_f32_e32 v143, 0xbfb8aa3b, v143
	v_exp_f32_e32 v143, v143
	v_add_f32_e32 v130, 1.0, v130
	v_rcp_f32_e32 v147, v130
	s_nop 0
	v_and_b32_e32 v130, 0xffff0000, v144
	v_add_f32_e32 v143, 1.0, v143
	v_mul_f32_e32 v130, 0xbfb8aa3b, v130
	v_rcp_f32_e32 v146, v143
	v_lshlrev_b32_e32 v143, 16, v144
	v_exp_f32_e32 v149, v130
	v_lshlrev_b32_e32 v130, 16, v131
	v_and_b32_e32 v131, 0xffff0000, v131
	v_mul_f32_e32 v143, 0xbfb8aa3b, v143
	v_mul_f32_e32 v130, 0xbfb8aa3b, v130
	v_mul_f32_e32 v131, 0xbfb8aa3b, v131
	v_exp_f32_e32 v148, v143
	v_exp_f32_e32 v130, v130
	v_lshlrev_b32_e32 v143, 16, v145
	v_exp_f32_e32 v131, v131
	v_mul_f32_e32 v143, 0xbfb8aa3b, v143
	v_exp_f32_e32 v144, v143
	v_and_b32_e32 v143, 0xffff0000, v145
	v_mul_f32_e32 v143, 0xbfb8aa3b, v143
	v_add_f32_e32 v130, 1.0, v130
	v_add_f32_e32 v131, 1.0, v131
	v_exp_f32_e32 v145, v143
	v_rcp_f32_e32 v130, v130
	v_rcp_f32_e32 v131, v131
	v_pk_add_f32 v[148:149], v[148:149], 1.0 op_sel_hi:[1,0]
	v_pk_add_f32 v[144:145], v[144:145], 1.0 op_sel_hi:[1,0]
	v_pk_mul_f32 v[146:147], v[146:147], v[148:149]
	v_pk_mul_f32 v[130:131], v[130:131], v[144:145]
	v_pk_mul_f32 v[10:11], v[10:11], v[146:147]
	v_pk_mul_f32 v[12:13], v[12:13], v[130:131]
	v_or_b32_e32 v130, 0x60, v0
	v_mov_b32_e32 v131, v1
	v_lshl_add_u64 v[138:139], v[138:139], 0, v[130:131]
	s_waitcnt vmcnt(23)
	v_mov_b64_e32 v[138:139], v[210:211]
	global_load_dwordx2 v[210:211], v[246:247], off offset:96
	v_lshl_add_u64 v[140:141], v[140:141], 0, v[130:131]
	s_waitcnt vmcnt(23)
; DI float bflo(unsigned u) { return __uint_as_float(u << 16); }
; DI float bfhi(unsigned u) { return __uint_as_float(u & 0xffff0000u); }
; DI float sigmoidf(float x) { return __builtin_amdgcn_rcpf(1.f + __expf(-x)); }
; DI float inv_sigmoidf(float x) { return 1.f + __expf(-x); }
; DI int TID8() { int t = threadIdx.x; asm volatile("" : "+v"(t)); return t; }
; template <class E>
; DI void gemm8_epi(f32x4 (&acc)[8][4], int m0, int n0, E e) {
;   const int tid = TID8(), lane = tid & 63, w = tid >> 6;
;   const int wm = w >> 2, wn = w & 3;
; #pragma unroll
;   for (int i = 0; i < 8; ++i)
; #pragma unroll
;     for (int j = 0; j < 4; ++j) {
;       const int m = m0 + wm * 128 + i * 16 + (lane & 15);
;       const int n = n0 + wn * 64 + j * 16 + (lane >> 4) * 4;
;       e(m, n, acc[i][j]);
;     }
; }
; __global__ void __launch_bounds__(512, 2) mega(Params p) {
;     ...
;       gemm8_epi(acc8, m0, n0, [&](int m, int n, f32x4& a) {
;         uint2 ua = *(const uint2*)(z + (size_t)m * ZS + C_MA + n);
;         uint2 ub = *(const uint2*)(z + (size_t)m * ZS + C_MB + n);
;         a[0] *= sigmoidf(bflo(ua.x)) * inv_sigmoidf(bflo(ub.x));
;         a[1] *= sigmoidf(bfhi(ua.x)) * inv_sigmoidf(bfhi(ub.x));
;         a[2] *= sigmoidf(bflo(ua.y)) * inv_sigmoidf(bflo(ub.y));
;         a[3] *= sigmoidf(bfhi(ua.y)) * inv_sigmoidf(bfhi(ub.y));
;       });
	v_mov_b64_e32 v[140:141], v[212:213]
	global_load_dwordx2 v[212:213], v[246:247], off offset:2144
	s_nop 0
	v_lshlrev_b32_e32 v143, 16, v138
	v_and_b32_e32 v138, 0xffff0000, v138
	v_mul_f32_e32 v138, 0xbfb8aa3b, v138
	v_exp_f32_e32 v138, v138
	v_mul_f32_e32 v143, 0xbfb8aa3b, v143
	v_exp_f32_e32 v143, v143
	v_add_f32_e32 v138, 1.0, v138
	v_rcp_f32_e32 v145, v138
	s_nop 0
	v_and_b32_e32 v138, 0xffff0000, v140
	v_mul_f32_e32 v138, 0xbfb8aa3b, v138
	v_exp_f32_e32 v147, v138
	v_lshlrev_b32_e32 v138, 16, v139
	v_and_b32_e32 v139, 0xffff0000, v139
	v_mul_f32_e32 v138, 0xbfb8aa3b, v138
	v_mul_f32_e32 v139, 0xbfb8aa3b, v139
	v_exp_f32_e32 v138, v138
	v_exp_f32_e32 v139, v139
	v_add_f32_e32 v143, 1.0, v143
	v_rcp_f32_e32 v144, v143
	v_lshlrev_b32_e32 v143, 16, v140
	v_lshlrev_b32_e32 v140, 16, v141
	v_and_b32_e32 v141, 0xffff0000, v141
	v_mul_f32_e32 v140, 0xbfb8aa3b, v140
	v_mul_f32_e32 v141, 0xbfb8aa3b, v141
	v_add_f32_e32 v138, 1.0, v138
	v_exp_f32_e32 v140, v140
	v_add_f32_e32 v139, 1.0, v139
	v_exp_f32_e32 v141, v141
	v_rcp_f32_e32 v138, v138
	v_rcp_f32_e32 v139, v139
	v_mul_f32_e32 v143, 0xbfb8aa3b, v143
	v_exp_f32_e32 v146, v143
	v_pk_add_f32 v[140:141], v[140:141], 1.0 op_sel_hi:[1,0]
	v_pk_add_f32 v[146:147], v[146:147], 1.0 op_sel_hi:[1,0]
	v_pk_mul_f32 v[138:139], v[138:139], v[140:141]
	v_pk_mul_f32 v[144:145], v[144:145], v[146:147]
	v_pk_mul_f32 v[16:17], v[16:17], v[138:139]
	v_or_b32_e32 v138, 16, v142
	v_mad_i64_i32 v[140:141], s[26:27], v138, s35, v[136:137]
	v_lshl_add_u64 v[138:139], v[140:141], 0, s[30:31]
	v_pk_mul_f32 v[14:15], v[14:15], v[144:145]
	v_lshl_add_u64 v[144:145], v[138:139], 0, v[0:1]
	s_waitcnt vmcnt(23)
	v_mov_b64_e32 v[144:145], v[214:215]
	v_lshl_add_u64 v[246:247], v[246:247], 0, s[88:89]
	global_load_dwordx2 v[214:215], v[246:247], off
	v_lshl_add_u64 v[140:141], v[140:141], 0, s[42:43]
	v_lshl_add_u64 v[146:147], v[140:141], 0, v[0:1]
	s_waitcnt vmcnt(23)
	v_mov_b64_e32 v[146:147], v[216:217]
	global_load_dwordx2 v[216:217], v[246:247], off offset:2048
	s_nop 0
	v_lshlrev_b32_e32 v143, 16, v144
	v_mul_f32_e32 v143, 0xbfb8aa3b, v143
	v_exp_f32_e32 v143, v143
	s_nop 0
	v_add_f32_e32 v143, 1.0, v143
	v_rcp_f32_e32 v148, v143
	s_nop 0
	v_lshlrev_b32_e32 v143, 16, v146
	v_mul_f32_e32 v143, 0xbfb8aa3b, v143
	v_exp_f32_e32 v150, v143
	v_and_b32_e32 v143, 0xffff0000, v144
	v_mul_f32_e32 v143, 0xbfb8aa3b, v143
	v_exp_f32_e32 v143, v143
	s_nop 0
	v_add_f32_e32 v143, 1.0, v143
	v_rcp_f32_e32 v149, v143
	v_and_b32_e32 v143, 0xffff0000, v146
	v_mul_f32_e32 v143, 0xbfb8aa3b, v143
	v_exp_f32_e32 v151, v143
	v_lshlrev_b32_e32 v143, 16, v145
	v_mul_f32_e32 v143, 0xbfb8aa3b, v143
	v_exp_f32_e32 v143, v143
	v_pk_add_f32 v[150:151], v[150:151], 1.0 op_sel_hi:[1,0]
	v_add_f32_e32 v143, 1.0, v143
	v_rcp_f32_e32 v144, v143
	v_lshlrev_b32_e32 v143, 16, v147
	v_mul_f32_e32 v143, 0xbfb8aa3b, v143
	v_exp_f32_e32 v146, v143
	v_and_b32_e32 v143, 0xffff0000, v145
	v_mul_f32_e32 v143, 0xbfb8aa3b, v143
	v_exp_f32_e32 v143, v143
	v_pk_mul_f32 v[148:149], v[148:149], v[150:151]
	v_add_f32_e32 v143, 1.0, v143
	v_rcp_f32_e32 v145, v143
	v_and_b32_e32 v143, 0xffff0000, v147
	v_mul_f32_e32 v143, 0xbfb8aa3b, v143
	v_exp_f32_e32 v147, v143
	v_pk_mul_f32 v[22:23], v[22:23], v[148:149]
	v_pk_add_f32 v[146:147], v[146:147], 1.0 op_sel_hi:[1,0]
	s_nop 0
	v_pk_mul_f32 v[144:145], v[144:145], v[146:147]
	v_lshl_add_u64 v[146:147], v[140:141], 0, v[134:135]
	v_pk_mul_f32 v[24:25], v[24:25], v[144:145]
	v_lshl_add_u64 v[144:145], v[138:139], 0, v[134:135]
	s_waitcnt vmcnt(23)
	v_mov_b64_e32 v[144:145], v[218:219]
	global_load_dwordx2 v[218:219], v[246:247], off offset:32
	s_nop 0
	s_waitcnt vmcnt(23)
	v_mov_b64_e32 v[146:147], v[220:221]
	global_load_dwordx2 v[220:221], v[246:247], off offset:2080
	s_nop 0
	v_lshlrev_b32_e32 v143, 16, v144
	v_mul_f32_e32 v143, 0xbfb8aa3b, v143
	v_exp_f32_e32 v143, v143
	s_nop 0
	v_add_f32_e32 v143, 1.0, v143
	v_rcp_f32_e32 v148, v143
	s_nop 0
	v_lshlrev_b32_e32 v143, 16, v146
	v_mul_f32_e32 v143, 0xbfb8aa3b, v143
	v_exp_f32_e32 v150, v143
	v_and_b32_e32 v143, 0xffff0000, v144
	v_mul_f32_e32 v143, 0xbfb8aa3b, v143
	v_exp_f32_e32 v143, v143
	s_nop 0
	v_add_f32_e32 v143, 1.0, v143
	v_rcp_f32_e32 v149, v143
	v_and_b32_e32 v143, 0xffff0000, v146
	v_mul_f32_e32 v143, 0xbfb8aa3b, v143
	v_exp_f32_e32 v151, v143
	v_lshlrev_b32_e32 v143, 16, v145
	v_mul_f32_e32 v143, 0xbfb8aa3b, v143
	v_exp_f32_e32 v143, v143
	v_pk_add_f32 v[150:151], v[150:151], 1.0 op_sel_hi:[1,0]
	v_add_f32_e32 v143, 1.0, v143
	v_rcp_f32_e32 v144, v143
	v_lshlrev_b32_e32 v143, 16, v147
	v_mul_f32_e32 v143, 0xbfb8aa3b, v143
	v_exp_f32_e32 v146, v143
	v_and_b32_e32 v143, 0xffff0000, v145
	v_mul_f32_e32 v143, 0xbfb8aa3b, v143
	v_exp_f32_e32 v143, v143
	v_pk_mul_f32 v[148:149], v[148:149], v[150:151]
	v_add_f32_e32 v143, 1.0, v143
	v_rcp_f32_e32 v145, v143
	v_and_b32_e32 v143, 0xffff0000, v147
	v_mul_f32_e32 v143, 0xbfb8aa3b, v143
	v_exp_f32_e32 v147, v143
	v_pk_mul_f32 v[30:31], v[30:31], v[148:149]
	v_pk_add_f32 v[146:147], v[146:147], 1.0 op_sel_hi:[1,0]
	s_nop 0
	v_pk_mul_f32 v[144:145], v[144:145], v[146:147]
	v_lshl_add_u64 v[146:147], v[140:141], 0, v[132:133]
	v_pk_mul_f32 v[32:33], v[32:33], v[144:145]
	v_lshl_add_u64 v[144:145], v[138:139], 0, v[132:133]
	s_waitcnt vmcnt(23)
	v_mov_b64_e32 v[144:145], v[222:223]
	global_load_dwordx2 v[222:223], v[246:247], off offset:64
	v_lshl_add_u64 v[138:139], v[138:139], 0, v[130:131]
	s_waitcnt vmcnt(23)
	v_mov_b64_e32 v[146:147], v[224:225]
	global_load_dwordx2 v[224:225], v[246:247], off offset:2112
	v_lshl_add_u64 v[140:141], v[140:141], 0, v[130:131]
	s_waitcnt vmcnt(23)
; DI float bflo(unsigned u) { return __uint_as_float(u << 16); }
; DI float bfhi(unsigned u) { return __uint_as_float(u & 0xffff0000u); }
; DI float sigmoidf(float x) { return __builtin_amdgcn_rcpf(1.f + __expf(-x)); }
; DI float inv_sigmoidf(float x) { return 1.f + __expf(-x); }
; DI int TID8() { int t = threadIdx.x; asm volatile("" : "+v"(t)); return t; }
; template <class E>
; DI void gemm8_epi(f32x4 (&acc)[8][4], int m0, int n0, E e) {
;   const int tid = TID8(), lane = tid & 63, w = tid >> 6;
;   const int wm = w >> 2, wn = w & 3;
; #pragma unroll
;   for (int i = 0; i < 8; ++i)
; #pragma unroll
;     for (int j = 0; j < 4; ++j) {
;       const int m = m0 + wm * 128 + i * 16 + (lane & 15);
;       const int n = n0 + wn * 64 + j * 16 + (lane >> 4) * 4;
;       e(m, n, acc[i][j]);
;     }
; }
; __global__ void __launch_bounds__(512, 2) mega(Params p) {
;     ...
;       gemm8_epi(acc8, m0, n0, [&](int m, int n, f32x4& a) {
;         uint2 ua = *(const uint2*)(z + (size_t)m * ZS + C_MA + n);
;         uint2 ub = *(const uint2*)(z + (size_t)m * ZS + C_MB + n);
;         a[0] *= sigmoidf(bflo(ua.x)) * inv_sigmoidf(bflo(ub.x));
;         a[1] *= sigmoidf(bfhi(ua.x)) * inv_sigmoidf(bfhi(ub.x));
;         a[2] *= sigmoidf(bflo(ua.y)) * inv_sigmoidf(bflo(ub.y));
;         a[3] *= sigmoidf(bfhi(ua.y)) * inv_sigmoidf(bfhi(ub.y));
;       });
	v_mov_b64_e32 v[138:139], v[226:227]
	global_load_dwordx2 v[226:227], v[246:247], off offset:96
	s_nop 0
	s_waitcnt vmcnt(23)
	v_mov_b64_e32 v[140:141], v[228:229]
	global_load_dwordx2 v[228:229], v[246:247], off offset:2144
	s_nop 0
	v_lshlrev_b32_e32 v143, 16, v144
	v_mul_f32_e32 v143, 0xbfb8aa3b, v143
	v_exp_f32_e32 v143, v143
	s_nop 0
	v_add_f32_e32 v143, 1.0, v143
	v_rcp_f32_e32 v148, v143
	s_nop 0
	v_lshlrev_b32_e32 v143, 16, v146
	v_mul_f32_e32 v143, 0xbfb8aa3b, v143
	v_exp_f32_e32 v150, v143
	v_and_b32_e32 v143, 0xffff0000, v144
	v_mul_f32_e32 v143, 0xbfb8aa3b, v143
	v_exp_f32_e32 v143, v143
	s_nop 0
	v_add_f32_e32 v143, 1.0, v143
	v_rcp_f32_e32 v149, v143
	v_and_b32_e32 v143, 0xffff0000, v146
	v_mul_f32_e32 v143, 0xbfb8aa3b, v143
	v_exp_f32_e32 v151, v143
	v_lshlrev_b32_e32 v143, 16, v145
	v_mul_f32_e32 v143, 0xbfb8aa3b, v143
	v_exp_f32_e32 v143, v143
	v_pk_add_f32 v[150:151], v[150:151], 1.0 op_sel_hi:[1,0]
	v_add_f32_e32 v143, 1.0, v143
	v_rcp_f32_e32 v144, v143
	v_lshlrev_b32_e32 v143, 16, v147
	v_mul_f32_e32 v143, 0xbfb8aa3b, v143
	v_exp_f32_e32 v146, v143
	v_and_b32_e32 v143, 0xffff0000, v145
	v_mul_f32_e32 v143, 0xbfb8aa3b, v143
	v_exp_f32_e32 v143, v143
	v_pk_mul_f32 v[148:149], v[148:149], v[150:151]
	v_add_f32_e32 v143, 1.0, v143
	v_rcp_f32_e32 v145, v143
	v_and_b32_e32 v143, 0xffff0000, v147
	v_mul_f32_e32 v143, 0xbfb8aa3b, v143
	v_exp_f32_e32 v147, v143
	s_nop 0
	v_lshlrev_b32_e32 v143, 16, v138
	v_and_b32_e32 v138, 0xffff0000, v138
	v_mul_f32_e32 v138, 0xbfb8aa3b, v138
	v_exp_f32_e32 v138, v138
	v_pk_add_f32 v[146:147], v[146:147], 1.0 op_sel_hi:[1,0]
	v_mul_f32_e32 v143, 0xbfb8aa3b, v143
	v_pk_mul_f32 v[144:145], v[144:145], v[146:147]
	v_add_f32_e32 v138, 1.0, v138
	v_pk_mul_f32 v[40:41], v[40:41], v[144:145]
	v_rcp_f32_e32 v145, v138
	s_nop 0
	v_and_b32_e32 v138, 0xffff0000, v140
	v_exp_f32_e32 v143, v143
	v_mul_f32_e32 v138, 0xbfb8aa3b, v138
	v_exp_f32_e32 v147, v138
	v_lshlrev_b32_e32 v138, 16, v139
	v_and_b32_e32 v139, 0xffff0000, v139
	v_mul_f32_e32 v138, 0xbfb8aa3b, v138
	v_mul_f32_e32 v139, 0xbfb8aa3b, v139
	v_exp_f32_e32 v138, v138
	v_exp_f32_e32 v139, v139
	v_add_f32_e32 v143, 1.0, v143
	v_rcp_f32_e32 v144, v143
	v_lshlrev_b32_e32 v143, 16, v140
	v_lshlrev_b32_e32 v140, 16, v141
	v_and_b32_e32 v141, 0xffff0000, v141
	v_mul_f32_e32 v140, 0xbfb8aa3b, v140
	v_mul_f32_e32 v141, 0xbfb8aa3b, v141
	v_add_f32_e32 v138, 1.0, v138
	v_exp_f32_e32 v140, v140
	v_add_f32_e32 v139, 1.0, v139
	v_exp_f32_e32 v141, v141
	v_rcp_f32_e32 v138, v138
	v_rcp_f32_e32 v139, v139
	v_mul_f32_e32 v143, 0xbfb8aa3b, v143
	v_exp_f32_e32 v146, v143
	v_pk_add_f32 v[140:141], v[140:141], 1.0 op_sel_hi:[1,0]
	v_pk_mul_f32 v[38:39], v[38:39], v[148:149]
	v_pk_mul_f32 v[138:139], v[138:139], v[140:141]
	v_pk_add_f32 v[146:147], v[146:147], 1.0 op_sel_hi:[1,0]
	v_pk_mul_f32 v[48:49], v[48:49], v[138:139]
	v_or_b32_e32 v138, 32, v142
	v_mad_i64_i32 v[140:141], s[26:27], v138, s35, v[136:137]
	v_pk_mul_f32 v[144:145], v[144:145], v[146:147]
	v_lshl_add_u64 v[138:139], v[140:141], 0, s[30:31]
	v_pk_mul_f32 v[46:47], v[46:47], v[144:145]
	v_lshl_add_u64 v[144:145], v[138:139], 0, v[0:1]
	s_waitcnt vmcnt(23)
	v_mov_b64_e32 v[144:145], v[230:231]
	v_lshl_add_u64 v[246:247], v[246:247], 0, s[88:89]
	global_load_dwordx2 v[230:231], v[246:247], off
	v_lshl_add_u64 v[140:141], v[140:141], 0, s[42:43]
	v_lshl_add_u64 v[146:147], v[140:141], 0, v[0:1]
	s_waitcnt vmcnt(23)
	v_mov_b64_e32 v[146:147], v[232:233]
	global_load_dwordx2 v[232:233], v[246:247], off offset:2048
	s_nop 0
	v_lshlrev_b32_e32 v143, 16, v144
	v_mul_f32_e32 v143, 0xbfb8aa3b, v143
	v_exp_f32_e32 v143, v143
	s_nop 0
	v_add_f32_e32 v143, 1.0, v143
	v_rcp_f32_e32 v148, v143
	s_nop 0
	v_lshlrev_b32_e32 v143, 16, v146
	v_mul_f32_e32 v143, 0xbfb8aa3b, v143
	v_exp_f32_e32 v150, v143
	v_and_b32_e32 v143, 0xffff0000, v144
	v_mul_f32_e32 v143, 0xbfb8aa3b, v143
	v_exp_f32_e32 v143, v143
	s_nop 0
	v_add_f32_e32 v143, 1.0, v143
	v_rcp_f32_e32 v149, v143
	v_and_b32_e32 v143, 0xffff0000, v146
	v_mul_f32_e32 v143, 0xbfb8aa3b, v143
	v_exp_f32_e32 v151, v143
	v_lshlrev_b32_e32 v143, 16, v145
	v_mul_f32_e32 v143, 0xbfb8aa3b, v143
	v_exp_f32_e32 v143, v143
	v_pk_add_f32 v[150:151], v[150:151], 1.0 op_sel_hi:[1,0]
	v_add_f32_e32 v143, 1.0, v143
	v_rcp_f32_e32 v144, v143
	v_lshlrev_b32_e32 v143, 16, v147
	v_mul_f32_e32 v143, 0xbfb8aa3b, v143
	v_exp_f32_e32 v146, v143
	v_and_b32_e32 v143, 0xffff0000, v145
	v_mul_f32_e32 v143, 0xbfb8aa3b, v143
	v_exp_f32_e32 v143, v143
	v_pk_mul_f32 v[148:149], v[148:149], v[150:151]
	v_add_f32_e32 v143, 1.0, v143
	v_rcp_f32_e32 v145, v143
	v_and_b32_e32 v143, 0xffff0000, v147
	v_mul_f32_e32 v143, 0xbfb8aa3b, v143
	v_exp_f32_e32 v147, v143
	v_pk_mul_f32 v[54:55], v[54:55], v[148:149]
	v_pk_add_f32 v[146:147], v[146:147], 1.0 op_sel_hi:[1,0]
	s_nop 0
	v_pk_mul_f32 v[144:145], v[144:145], v[146:147]
	v_lshl_add_u64 v[146:147], v[140:141], 0, v[134:135]
	v_pk_mul_f32 v[56:57], v[56:57], v[144:145]
	v_lshl_add_u64 v[144:145], v[138:139], 0, v[134:135]
	s_waitcnt vmcnt(23)
	v_mov_b64_e32 v[144:145], v[234:235]
	global_load_dwordx2 v[234:235], v[246:247], off offset:32
	s_nop 0
	s_waitcnt vmcnt(23)
; DI float bflo(unsigned u) { return __uint_as_float(u << 16); }
; DI float bfhi(unsigned u) { return __uint_as_float(u & 0xffff0000u); }
; DI float sigmoidf(float x) { return __builtin_amdgcn_rcpf(1.f + __expf(-x)); }
; DI float inv_sigmoidf(float x) { return 1.f + __expf(-x); }
; DI int TID8() { int t = threadIdx.x; asm volatile("" : "+v"(t)); return t; }
; template <class E>
; DI void gemm8_epi(f32x4 (&acc)[8][4], int m0, int n0, E e) {
;   const int tid = TID8(), lane = tid & 63, w = tid >> 6;
;   const int wm = w >> 2, wn = w & 3;
; #pragma unroll
;   for (int i = 0; i < 8; ++i)
; #pragma unroll
;     for (int j = 0; j < 4; ++j) {
;       const int m = m0 + wm * 128 + i * 16 + (lane & 15);
;       const int n = n0 + wn * 64 + j * 16 + (lane >> 4) * 4;
;       e(m, n, acc[i][j]);
;     }
; }
; __global__ void __launch_bounds__(512, 2) mega(Params p) {
;     ...
;       gemm8_epi(acc8, m0, n0, [&](int m, int n, f32x4& a) {
;         uint2 ua = *(const uint2*)(z + (size_t)m * ZS + C_MA + n);
;         uint2 ub = *(const uint2*)(z + (size_t)m * ZS + C_MB + n);
;         a[0] *= sigmoidf(bflo(ua.x)) * inv_sigmoidf(bflo(ub.x));
;         a[1] *= sigmoidf(bfhi(ua.x)) * inv_sigmoidf(bfhi(ub.x));
;         a[2] *= sigmoidf(bflo(ua.y)) * inv_sigmoidf(bflo(ub.y));
;         a[3] *= sigmoidf(bfhi(ua.y)) * inv_sigmoidf(bfhi(ub.y));
;       });
	v_mov_b64_e32 v[146:147], v[236:237]
	global_load_dwordx2 v[236:237], v[246:247], off offset:2080
	s_nop 0
	v_lshlrev_b32_e32 v143, 16, v144
	v_mul_f32_e32 v143, 0xbfb8aa3b, v143
	v_exp_f32_e32 v143, v143
	s_nop 0
	v_add_f32_e32 v143, 1.0, v143
	v_rcp_f32_e32 v148, v143
	s_nop 0
	v_lshlrev_b32_e32 v143, 16, v146
	v_mul_f32_e32 v143, 0xbfb8aa3b, v143
	v_exp_f32_e32 v150, v143
	v_and_b32_e32 v143, 0xffff0000, v144
	v_mul_f32_e32 v143, 0xbfb8aa3b, v143
	v_exp_f32_e32 v143, v143
	s_nop 0
	v_add_f32_e32 v143, 1.0, v143
	v_rcp_f32_e32 v149, v143
	v_and_b32_e32 v143, 0xffff0000, v146
	v_mul_f32_e32 v143, 0xbfb8aa3b, v143
	v_exp_f32_e32 v151, v143
	v_lshlrev_b32_e32 v143, 16, v145
	v_mul_f32_e32 v143, 0xbfb8aa3b, v143
	v_exp_f32_e32 v143, v143
	v_pk_add_f32 v[150:151], v[150:151], 1.0 op_sel_hi:[1,0]
	v_add_f32_e32 v143, 1.0, v143
	v_rcp_f32_e32 v144, v143
	v_lshlrev_b32_e32 v143, 16, v147
	v_mul_f32_e32 v143, 0xbfb8aa3b, v143
	v_exp_f32_e32 v146, v143
	v_and_b32_e32 v143, 0xffff0000, v145
	v_mul_f32_e32 v143, 0xbfb8aa3b, v143
	v_exp_f32_e32 v143, v143
	v_pk_mul_f32 v[148:149], v[148:149], v[150:151]
	v_add_f32_e32 v143, 1.0, v143
	v_rcp_f32_e32 v145, v143
	v_and_b32_e32 v143, 0xffff0000, v147
	v_mul_f32_e32 v143, 0xbfb8aa3b, v143
	v_exp_f32_e32 v147, v143
	v_pk_mul_f32 v[62:63], v[62:63], v[148:149]
	v_pk_add_f32 v[146:147], v[146:147], 1.0 op_sel_hi:[1,0]
	s_nop 0
	v_pk_mul_f32 v[144:145], v[144:145], v[146:147]
	v_lshl_add_u64 v[146:147], v[140:141], 0, v[132:133]
	v_pk_mul_f32 v[64:65], v[64:65], v[144:145]
	v_lshl_add_u64 v[144:145], v[138:139], 0, v[132:133]
	s_waitcnt vmcnt(23)
	v_mov_b64_e32 v[144:145], v[238:239]
	global_load_dwordx2 v[238:239], v[246:247], off offset:64
	v_lshl_add_u64 v[138:139], v[138:139], 0, v[130:131]
	s_waitcnt vmcnt(23)
	v_mov_b64_e32 v[146:147], v[240:241]
	global_load_dwordx2 v[240:241], v[246:247], off offset:2112
	v_lshl_add_u64 v[140:141], v[140:141], 0, v[130:131]
	s_waitcnt vmcnt(23)
	v_mov_b64_e32 v[138:139], v[242:243]
	global_load_dwordx2 v[242:243], v[246:247], off offset:96
	s_nop 0
	s_waitcnt vmcnt(23)
	v_mov_b64_e32 v[140:141], v[244:245]
	global_load_dwordx2 v[244:245], v[246:247], off offset:2144
	s_nop 0
	v_lshlrev_b32_e32 v143, 16, v144
	v_mul_f32_e32 v143, 0xbfb8aa3b, v143
	v_exp_f32_e32 v143, v143
	s_nop 0
	v_add_f32_e32 v143, 1.0, v143
	v_rcp_f32_e32 v148, v143
	s_nop 0
	v_lshlrev_b32_e32 v143, 16, v146
	v_mul_f32_e32 v143, 0xbfb8aa3b, v143
	v_exp_f32_e32 v150, v143
	v_and_b32_e32 v143, 0xffff0000, v144
	v_mul_f32_e32 v143, 0xbfb8aa3b, v143
	v_exp_f32_e32 v143, v143
	s_nop 0
	v_add_f32_e32 v143, 1.0, v143
	v_rcp_f32_e32 v149, v143
	v_and_b32_e32 v143, 0xffff0000, v146
	v_mul_f32_e32 v143, 0xbfb8aa3b, v143
	v_exp_f32_e32 v151, v143
	v_lshlrev_b32_e32 v143, 16, v145
	v_mul_f32_e32 v143, 0xbfb8aa3b, v143
	v_exp_f32_e32 v143, v143
	v_pk_add_f32 v[150:151], v[150:151], 1.0 op_sel_hi:[1,0]
	v_add_f32_e32 v143, 1.0, v143
	v_rcp_f32_e32 v144, v143
	v_lshlrev_b32_e32 v143, 16, v147
	v_mul_f32_e32 v143, 0xbfb8aa3b, v143
	v_exp_f32_e32 v146, v143
	v_and_b32_e32 v143, 0xffff0000, v145
	v_mul_f32_e32 v143, 0xbfb8aa3b, v143
	v_exp_f32_e32 v143, v143
	v_pk_mul_f32 v[148:149], v[148:149], v[150:151]
	v_add_f32_e32 v143, 1.0, v143
	v_rcp_f32_e32 v145, v143
	v_and_b32_e32 v143, 0xffff0000, v147
	v_mul_f32_e32 v143, 0xbfb8aa3b, v143
	v_exp_f32_e32 v147, v143
	s_nop 0
	v_lshlrev_b32_e32 v143, 16, v138
	v_and_b32_e32 v138, 0xffff0000, v138
	v_mul_f32_e32 v138, 0xbfb8aa3b, v138
	v_exp_f32_e32 v138, v138
	v_pk_add_f32 v[146:147], v[146:147], 1.0 op_sel_hi:[1,0]
	v_mul_f32_e32 v143, 0xbfb8aa3b, v143
	v_pk_mul_f32 v[144:145], v[144:145], v[146:147]
	v_add_f32_e32 v138, 1.0, v138
	v_pk_mul_f32 v[72:73], v[72:73], v[144:145]
	v_rcp_f32_e32 v145, v138
	s_nop 0
	v_and_b32_e32 v138, 0xffff0000, v140
	v_exp_f32_e32 v143, v143
	v_mul_f32_e32 v138, 0xbfb8aa3b, v138
	v_exp_f32_e32 v147, v138
	v_lshlrev_b32_e32 v138, 16, v139
	v_and_b32_e32 v139, 0xffff0000, v139
	v_mul_f32_e32 v138, 0xbfb8aa3b, v138
	v_mul_f32_e32 v139, 0xbfb8aa3b, v139
	v_exp_f32_e32 v138, v138
	v_exp_f32_e32 v139, v139
	v_add_f32_e32 v143, 1.0, v143
	v_rcp_f32_e32 v144, v143
	v_lshlrev_b32_e32 v143, 16, v140
	v_lshlrev_b32_e32 v140, 16, v141
	v_and_b32_e32 v141, 0xffff0000, v141
	v_mul_f32_e32 v140, 0xbfb8aa3b, v140
	v_mul_f32_e32 v141, 0xbfb8aa3b, v141
	v_add_f32_e32 v138, 1.0, v138
	v_exp_f32_e32 v140, v140
	v_add_f32_e32 v139, 1.0, v139
	v_exp_f32_e32 v141, v141
	v_rcp_f32_e32 v138, v138
	v_rcp_f32_e32 v139, v139
	v_mul_f32_e32 v143, 0xbfb8aa3b, v143
	v_exp_f32_e32 v146, v143
	v_pk_add_f32 v[140:141], v[140:141], 1.0 op_sel_hi:[1,0]
	v_pk_mul_f32 v[70:71], v[70:71], v[148:149]
	v_pk_mul_f32 v[138:139], v[138:139], v[140:141]
	v_pk_add_f32 v[146:147], v[146:147], 1.0 op_sel_hi:[1,0]
	v_pk_mul_f32 v[80:81], v[80:81], v[138:139]
	v_or_b32_e32 v138, 48, v142
	v_mad_i64_i32 v[140:141], s[26:27], v138, s35, v[136:137]
	v_pk_mul_f32 v[144:145], v[144:145], v[146:147]
	v_lshl_add_u64 v[138:139], v[140:141], 0, s[30:31]
	v_pk_mul_f32 v[78:79], v[78:79], v[144:145]
	v_lshl_add_u64 v[144:145], v[138:139], 0, v[0:1]
	s_waitcnt vmcnt(23)
	v_mov_b64_e32 v[144:145], v[198:199]
	v_lshl_add_u64 v[246:247], v[246:247], 0, s[88:89]
	global_load_dwordx2 v[198:199], v[246:247], off
	v_lshl_add_u64 v[140:141], v[140:141], 0, s[42:43]
	v_lshl_add_u64 v[146:147], v[140:141], 0, v[0:1]
	s_waitcnt vmcnt(23)
; DI float bflo(unsigned u) { return __uint_as_float(u << 16); }
; DI float bfhi(unsigned u) { return __uint_as_float(u & 0xffff0000u); }
; DI float sigmoidf(float x) { return __builtin_amdgcn_rcpf(1.f + __expf(-x)); }
; DI float inv_sigmoidf(float x) { return 1.f + __expf(-x); }
; DI int TID8() { int t = threadIdx.x; asm volatile("" : "+v"(t)); return t; }
; template <class E>
; DI void gemm8_epi(f32x4 (&acc)[8][4], int m0, int n0, E e) {
;   const int tid = TID8(), lane = tid & 63, w = tid >> 6;
;   const int wm = w >> 2, wn = w & 3;
; #pragma unroll
;   for (int i = 0; i < 8; ++i)
; #pragma unroll
;     for (int j = 0; j < 4; ++j) {
;       const int m = m0 + wm * 128 + i * 16 + (lane & 15);
;       const int n = n0 + wn * 64 + j * 16 + (lane >> 4) * 4;
;       e(m, n, acc[i][j]);
;     }
; }
; __global__ void __launch_bounds__(512, 2) mega(Params p) {
;     ...
;       gemm8_epi(acc8, m0, n0, [&](int m, int n, f32x4& a) {
;         uint2 ua = *(const uint2*)(z + (size_t)m * ZS + C_MA + n);
;         uint2 ub = *(const uint2*)(z + (size_t)m * ZS + C_MB + n);
;         a[0] *= sigmoidf(bflo(ua.x)) * inv_sigmoidf(bflo(ub.x));
;         a[1] *= sigmoidf(bfhi(ua.x)) * inv_sigmoidf(bfhi(ub.x));
;         a[2] *= sigmoidf(bflo(ua.y)) * inv_sigmoidf(bflo(ub.y));
;         a[3] *= sigmoidf(bfhi(ua.y)) * inv_sigmoidf(bfhi(ub.y));
;       });
	v_mov_b64_e32 v[146:147], v[200:201]
	global_load_dwordx2 v[200:201], v[246:247], off offset:2048
	s_nop 0
	v_lshlrev_b32_e32 v143, 16, v144
	v_mul_f32_e32 v143, 0xbfb8aa3b, v143
	v_exp_f32_e32 v143, v143
	s_nop 0
	v_add_f32_e32 v143, 1.0, v143
	v_rcp_f32_e32 v148, v143
	s_nop 0
	v_lshlrev_b32_e32 v143, 16, v146
	v_mul_f32_e32 v143, 0xbfb8aa3b, v143
	v_exp_f32_e32 v150, v143
	v_and_b32_e32 v143, 0xffff0000, v144
	v_mul_f32_e32 v143, 0xbfb8aa3b, v143
	v_exp_f32_e32 v143, v143
	s_nop 0
	v_add_f32_e32 v143, 1.0, v143
	v_rcp_f32_e32 v149, v143
	v_and_b32_e32 v143, 0xffff0000, v146
	v_mul_f32_e32 v143, 0xbfb8aa3b, v143
	v_exp_f32_e32 v151, v143
	v_lshlrev_b32_e32 v143, 16, v145
	v_mul_f32_e32 v143, 0xbfb8aa3b, v143
	v_exp_f32_e32 v143, v143
	v_pk_add_f32 v[150:151], v[150:151], 1.0 op_sel_hi:[1,0]
	v_add_f32_e32 v143, 1.0, v143
	v_rcp_f32_e32 v144, v143
	v_lshlrev_b32_e32 v143, 16, v147
	v_mul_f32_e32 v143, 0xbfb8aa3b, v143
	v_exp_f32_e32 v146, v143
	v_and_b32_e32 v143, 0xffff0000, v145
	v_mul_f32_e32 v143, 0xbfb8aa3b, v143
	v_exp_f32_e32 v143, v143
	v_pk_mul_f32 v[148:149], v[148:149], v[150:151]
	v_add_f32_e32 v143, 1.0, v143
	v_rcp_f32_e32 v145, v143
	v_and_b32_e32 v143, 0xffff0000, v147
	v_mul_f32_e32 v143, 0xbfb8aa3b, v143
	v_exp_f32_e32 v147, v143
	v_pk_mul_f32 v[86:87], v[86:87], v[148:149]
	v_pk_add_f32 v[146:147], v[146:147], 1.0 op_sel_hi:[1,0]
	s_nop 0
	v_pk_mul_f32 v[144:145], v[144:145], v[146:147]
	v_lshl_add_u64 v[146:147], v[140:141], 0, v[134:135]
	v_pk_mul_f32 v[88:89], v[88:89], v[144:145]
	v_lshl_add_u64 v[144:145], v[138:139], 0, v[134:135]
	s_waitcnt vmcnt(23)
	v_mov_b64_e32 v[144:145], v[202:203]
	global_load_dwordx2 v[202:203], v[246:247], off offset:32
	s_nop 0
	s_waitcnt vmcnt(23)
	v_mov_b64_e32 v[146:147], v[204:205]
	global_load_dwordx2 v[204:205], v[246:247], off offset:2080
	s_nop 0
	v_lshlrev_b32_e32 v143, 16, v144
	v_mul_f32_e32 v143, 0xbfb8aa3b, v143
	v_exp_f32_e32 v143, v143
	s_nop 0
	v_add_f32_e32 v143, 1.0, v143
	v_rcp_f32_e32 v148, v143
	s_nop 0
	v_lshlrev_b32_e32 v143, 16, v146
	v_mul_f32_e32 v143, 0xbfb8aa3b, v143
	v_exp_f32_e32 v150, v143
	v_and_b32_e32 v143, 0xffff0000, v144
	v_mul_f32_e32 v143, 0xbfb8aa3b, v143
	v_exp_f32_e32 v143, v143
	s_nop 0
	v_add_f32_e32 v143, 1.0, v143
	v_rcp_f32_e32 v149, v143
	v_and_b32_e32 v143, 0xffff0000, v146
	v_mul_f32_e32 v143, 0xbfb8aa3b, v143
	v_exp_f32_e32 v151, v143
	v_lshlrev_b32_e32 v143, 16, v145
	v_mul_f32_e32 v143, 0xbfb8aa3b, v143
	v_exp_f32_e32 v143, v143
	v_pk_add_f32 v[150:151], v[150:151], 1.0 op_sel_hi:[1,0]
	v_add_f32_e32 v143, 1.0, v143
	v_rcp_f32_e32 v144, v143
	v_lshlrev_b32_e32 v143, 16, v147
	v_mul_f32_e32 v143, 0xbfb8aa3b, v143
	v_exp_f32_e32 v146, v143
	v_and_b32_e32 v143, 0xffff0000, v145
	v_mul_f32_e32 v143, 0xbfb8aa3b, v143
	v_exp_f32_e32 v143, v143
	v_pk_mul_f32 v[148:149], v[148:149], v[150:151]
	v_add_f32_e32 v143, 1.0, v143
	v_rcp_f32_e32 v145, v143
	v_and_b32_e32 v143, 0xffff0000, v147
	v_mul_f32_e32 v143, 0xbfb8aa3b, v143
	v_exp_f32_e32 v147, v143
	v_pk_mul_f32 v[94:95], v[94:95], v[148:149]
	v_pk_add_f32 v[146:147], v[146:147], 1.0 op_sel_hi:[1,0]
	s_nop 0
	v_pk_mul_f32 v[144:145], v[144:145], v[146:147]
	v_lshl_add_u64 v[146:147], v[140:141], 0, v[132:133]
	v_pk_mul_f32 v[96:97], v[96:97], v[144:145]
	v_lshl_add_u64 v[144:145], v[138:139], 0, v[132:133]
	s_waitcnt vmcnt(23)
	v_mov_b64_e32 v[144:145], v[206:207]
	global_load_dwordx2 v[206:207], v[246:247], off offset:64
	v_lshl_add_u64 v[138:139], v[138:139], 0, v[130:131]
	s_waitcnt vmcnt(23)
	v_mov_b64_e32 v[146:147], v[208:209]
	global_load_dwordx2 v[208:209], v[246:247], off offset:2112
	v_lshl_add_u64 v[140:141], v[140:141], 0, v[130:131]
	s_waitcnt vmcnt(23)
	v_mov_b64_e32 v[138:139], v[210:211]
	global_load_dwordx2 v[210:211], v[246:247], off offset:96
	s_nop 0
	s_waitcnt vmcnt(23)
	v_mov_b64_e32 v[140:141], v[212:213]
	global_load_dwordx2 v[212:213], v[246:247], off offset:2144
	s_nop 0
	v_lshlrev_b32_e32 v143, 16, v144
	v_mul_f32_e32 v143, 0xbfb8aa3b, v143
	v_exp_f32_e32 v143, v143
	s_nop 0
	v_add_f32_e32 v143, 1.0, v143
	v_rcp_f32_e32 v148, v143
	s_nop 0
	v_lshlrev_b32_e32 v143, 16, v146
	v_mul_f32_e32 v143, 0xbfb8aa3b, v143
	v_exp_f32_e32 v150, v143
	v_and_b32_e32 v143, 0xffff0000, v144
	v_mul_f32_e32 v143, 0xbfb8aa3b, v143
	v_exp_f32_e32 v143, v143
	s_nop 0
	v_add_f32_e32 v143, 1.0, v143
	v_rcp_f32_e32 v149, v143
	v_and_b32_e32 v143, 0xffff0000, v146
	v_mul_f32_e32 v143, 0xbfb8aa3b, v143
	v_exp_f32_e32 v151, v143
	v_lshlrev_b32_e32 v143, 16, v145
	v_mul_f32_e32 v143, 0xbfb8aa3b, v143
	v_exp_f32_e32 v143, v143
	v_pk_add_f32 v[150:151], v[150:151], 1.0 op_sel_hi:[1,0]
	v_add_f32_e32 v143, 1.0, v143
	v_rcp_f32_e32 v144, v143
	v_lshlrev_b32_e32 v143, 16, v147
	v_mul_f32_e32 v143, 0xbfb8aa3b, v143
	v_exp_f32_e32 v146, v143
	v_and_b32_e32 v143, 0xffff0000, v145
	v_mul_f32_e32 v143, 0xbfb8aa3b, v143
	v_exp_f32_e32 v143, v143
	v_pk_mul_f32 v[148:149], v[148:149], v[150:151]
	v_add_f32_e32 v143, 1.0, v143
	v_rcp_f32_e32 v145, v143
	v_and_b32_e32 v143, 0xffff0000, v147
	v_mul_f32_e32 v143, 0xbfb8aa3b, v143
	v_exp_f32_e32 v147, v143
	s_nop 0
	v_lshlrev_b32_e32 v143, 16, v138
	v_and_b32_e32 v138, 0xffff0000, v138
	v_mul_f32_e32 v138, 0xbfb8aa3b, v138
	v_exp_f32_e32 v138, v138
	v_pk_add_f32 v[146:147], v[146:147], 1.0 op_sel_hi:[1,0]
	v_mul_f32_e32 v143, 0xbfb8aa3b, v143
	v_pk_mul_f32 v[144:145], v[144:145], v[146:147]
	v_add_f32_e32 v138, 1.0, v138
	v_pk_mul_f32 v[104:105], v[104:105], v[144:145]
	v_rcp_f32_e32 v145, v138
	s_nop 0
	v_and_b32_e32 v138, 0xffff0000, v140
	v_exp_f32_e32 v143, v143
	v_mul_f32_e32 v138, 0xbfb8aa3b, v138
	v_exp_f32_e32 v147, v138
	v_lshlrev_b32_e32 v138, 16, v139
	v_and_b32_e32 v139, 0xffff0000, v139
	v_mul_f32_e32 v138, 0xbfb8aa3b, v138
	v_mul_f32_e32 v139, 0xbfb8aa3b, v139
	v_exp_f32_e32 v138, v138
	v_exp_f32_e32 v139, v139
	v_add_f32_e32 v143, 1.0, v143
	v_rcp_f32_e32 v144, v143
	v_lshlrev_b32_e32 v143, 16, v140
	v_lshlrev_b32_e32 v140, 16, v141
	v_and_b32_e32 v141, 0xffff0000, v141
	v_mul_f32_e32 v140, 0xbfb8aa3b, v140
	v_mul_f32_e32 v141, 0xbfb8aa3b, v141
	v_add_f32_e32 v138, 1.0, v138
	v_exp_f32_e32 v140, v140
	v_add_f32_e32 v139, 1.0, v139
	v_exp_f32_e32 v141, v141
	v_rcp_f32_e32 v138, v138
	v_rcp_f32_e32 v139, v139
	v_mul_f32_e32 v143, 0xbfb8aa3b, v143
	v_exp_f32_e32 v146, v143
	v_pk_add_f32 v[140:141], v[140:141], 1.0 op_sel_hi:[1,0]
	v_pk_mul_f32 v[102:103], v[102:103], v[148:149]
	v_pk_mul_f32 v[138:139], v[138:139], v[140:141]
	v_pk_add_f32 v[146:147], v[146:147], 1.0 op_sel_hi:[1,0]
	v_pk_mul_f32 v[112:113], v[112:113], v[138:139]
	v_or_b32_e32 v138, 64, v142
	v_mad_i64_i32 v[140:141], s[26:27], v138, s35, v[136:137]
	v_pk_mul_f32 v[144:145], v[144:145], v[146:147]
	v_lshl_add_u64 v[138:139], v[140:141], 0, s[30:31]
	v_pk_mul_f32 v[110:111], v[110:111], v[144:145]
	v_lshl_add_u64 v[144:145], v[138:139], 0, v[0:1]
	s_waitcnt vmcnt(23)
; DI float bflo(unsigned u) { return __uint_as_float(u << 16); }
; DI float bfhi(unsigned u) { return __uint_as_float(u & 0xffff0000u); }
; DI float sigmoidf(float x) { return __builtin_amdgcn_rcpf(1.f + __expf(-x)); }
; DI float inv_sigmoidf(float x) { return 1.f + __expf(-x); }
; DI int TID8() { int t = threadIdx.x; asm volatile("" : "+v"(t)); return t; }
; template <class E>
; DI void gemm8_epi(f32x4 (&acc)[8][4], int m0, int n0, E e) {
;   const int tid = TID8(), lane = tid & 63, w = tid >> 6;
;   const int wm = w >> 2, wn = w & 3;
; #pragma unroll
;   for (int i = 0; i < 8; ++i)
; #pragma unroll
;     for (int j = 0; j < 4; ++j) {
;       const int m = m0 + wm * 128 + i * 16 + (lane & 15);
;       const int n = n0 + wn * 64 + j * 16 + (lane >> 4) * 4;
;       e(m, n, acc[i][j]);
;     }
; }
; __global__ void __launch_bounds__(512, 2) mega(Params p) {
;     ...
;       gemm8_epi(acc8, m0, n0, [&](int m, int n, f32x4& a) {
;         uint2 ua = *(const uint2*)(z + (size_t)m * ZS + C_MA + n);
;         uint2 ub = *(const uint2*)(z + (size_t)m * ZS + C_MB + n);
;         a[0] *= sigmoidf(bflo(ua.x)) * inv_sigmoidf(bflo(ub.x));
;         a[1] *= sigmoidf(bfhi(ua.x)) * inv_sigmoidf(bfhi(ub.x));
;         a[2] *= sigmoidf(bflo(ua.y)) * inv_sigmoidf(bflo(ub.y));
;         a[3] *= sigmoidf(bfhi(ua.y)) * inv_sigmoidf(bfhi(ub.y));
;       });
	v_mov_b64_e32 v[144:145], v[214:215]
	v_lshl_add_u64 v[246:247], v[246:247], 0, s[88:89]
	global_load_dwordx2 v[214:215], v[246:247], off
	v_lshl_add_u64 v[140:141], v[140:141], 0, s[42:43]
	v_lshl_add_u64 v[146:147], v[140:141], 0, v[0:1]
	s_waitcnt vmcnt(23)
	v_mov_b64_e32 v[146:147], v[216:217]
	global_load_dwordx2 v[216:217], v[246:247], off offset:2048
	s_nop 0
	v_lshlrev_b32_e32 v143, 16, v144
	v_mul_f32_e32 v143, 0xbfb8aa3b, v143
	v_exp_f32_e32 v143, v143
	s_nop 0
	v_add_f32_e32 v143, 1.0, v143
	v_rcp_f32_e32 v148, v143
	s_nop 0
	v_lshlrev_b32_e32 v143, 16, v146
	v_mul_f32_e32 v143, 0xbfb8aa3b, v143
	v_exp_f32_e32 v150, v143
	v_and_b32_e32 v143, 0xffff0000, v144
	v_mul_f32_e32 v143, 0xbfb8aa3b, v143
	v_exp_f32_e32 v143, v143
	s_nop 0
	v_add_f32_e32 v143, 1.0, v143
	v_rcp_f32_e32 v149, v143
	v_and_b32_e32 v143, 0xffff0000, v146
	v_mul_f32_e32 v143, 0xbfb8aa3b, v143
	v_exp_f32_e32 v151, v143
	v_lshlrev_b32_e32 v143, 16, v145
	v_mul_f32_e32 v143, 0xbfb8aa3b, v143
	v_exp_f32_e32 v143, v143
	v_pk_add_f32 v[150:151], v[150:151], 1.0 op_sel_hi:[1,0]
	v_add_f32_e32 v143, 1.0, v143
	v_rcp_f32_e32 v144, v143
	v_lshlrev_b32_e32 v143, 16, v147
	v_mul_f32_e32 v143, 0xbfb8aa3b, v143
	v_exp_f32_e32 v146, v143
	v_and_b32_e32 v143, 0xffff0000, v145
	v_mul_f32_e32 v143, 0xbfb8aa3b, v143
	v_exp_f32_e32 v143, v143
	v_pk_mul_f32 v[148:149], v[148:149], v[150:151]
	v_add_f32_e32 v143, 1.0, v143
	v_rcp_f32_e32 v145, v143
	v_and_b32_e32 v143, 0xffff0000, v147
	v_mul_f32_e32 v143, 0xbfb8aa3b, v143
	v_exp_f32_e32 v147, v143
	v_pk_mul_f32 v[118:119], v[118:119], v[148:149]
	v_pk_add_f32 v[146:147], v[146:147], 1.0 op_sel_hi:[1,0]
	s_nop 0
	v_pk_mul_f32 v[144:145], v[144:145], v[146:147]
	v_lshl_add_u64 v[146:147], v[140:141], 0, v[134:135]
	v_pk_mul_f32 v[120:121], v[120:121], v[144:145]
	v_lshl_add_u64 v[144:145], v[138:139], 0, v[134:135]
	s_waitcnt vmcnt(23)
	v_mov_b64_e32 v[144:145], v[218:219]
	global_load_dwordx2 v[218:219], v[246:247], off offset:32
	s_nop 0
	s_waitcnt vmcnt(23)
	v_mov_b64_e32 v[146:147], v[220:221]
	global_load_dwordx2 v[220:221], v[246:247], off offset:2080
	s_nop 0
	v_lshlrev_b32_e32 v143, 16, v144
	v_mul_f32_e32 v143, 0xbfb8aa3b, v143
	v_exp_f32_e32 v143, v143
	s_nop 0
	v_add_f32_e32 v143, 1.0, v143
	v_rcp_f32_e32 v148, v143
	s_nop 0
	v_lshlrev_b32_e32 v143, 16, v146
	v_mul_f32_e32 v143, 0xbfb8aa3b, v143
	v_exp_f32_e32 v150, v143
	v_and_b32_e32 v143, 0xffff0000, v144
	v_mul_f32_e32 v143, 0xbfb8aa3b, v143
	v_exp_f32_e32 v143, v143
	s_nop 0
	v_add_f32_e32 v143, 1.0, v143
	v_rcp_f32_e32 v149, v143
	v_and_b32_e32 v143, 0xffff0000, v146
	v_mul_f32_e32 v143, 0xbfb8aa3b, v143
	v_exp_f32_e32 v151, v143
	v_lshlrev_b32_e32 v143, 16, v145
	v_mul_f32_e32 v143, 0xbfb8aa3b, v143
	v_exp_f32_e32 v143, v143
	v_pk_add_f32 v[150:151], v[150:151], 1.0 op_sel_hi:[1,0]
	v_add_f32_e32 v143, 1.0, v143
	v_rcp_f32_e32 v144, v143
	v_lshlrev_b32_e32 v143, 16, v147
	v_mul_f32_e32 v143, 0xbfb8aa3b, v143
	v_exp_f32_e32 v146, v143
	v_and_b32_e32 v143, 0xffff0000, v145
	v_mul_f32_e32 v143, 0xbfb8aa3b, v143
	v_exp_f32_e32 v143, v143
	v_pk_mul_f32 v[148:149], v[148:149], v[150:151]
	v_add_f32_e32 v143, 1.0, v143
	v_rcp_f32_e32 v145, v143
	v_and_b32_e32 v143, 0xffff0000, v147
	v_mul_f32_e32 v143, 0xbfb8aa3b, v143
	v_exp_f32_e32 v147, v143
	v_pk_mul_f32 v[126:127], v[126:127], v[148:149]
	v_pk_add_f32 v[146:147], v[146:147], 1.0 op_sel_hi:[1,0]
	s_nop 0
	v_pk_mul_f32 v[144:145], v[144:145], v[146:147]
	v_lshl_add_u64 v[146:147], v[140:141], 0, v[132:133]
	v_pk_mul_f32 v[128:129], v[128:129], v[144:145]
	v_lshl_add_u64 v[144:145], v[138:139], 0, v[132:133]
	s_waitcnt vmcnt(23)
	v_mov_b64_e32 v[144:145], v[222:223]
	global_load_dwordx2 v[222:223], v[246:247], off offset:64
	v_lshl_add_u64 v[138:139], v[138:139], 0, v[130:131]
	s_waitcnt vmcnt(23)
	v_mov_b64_e32 v[146:147], v[224:225]
	global_load_dwordx2 v[224:225], v[246:247], off offset:2112
	v_lshl_add_u64 v[140:141], v[140:141], 0, v[130:131]
	s_waitcnt vmcnt(23)
	v_mov_b64_e32 v[138:139], v[226:227]
	global_load_dwordx2 v[226:227], v[246:247], off offset:96
	s_nop 0
	s_waitcnt vmcnt(23)
	v_mov_b64_e32 v[140:141], v[228:229]
	global_load_dwordx2 v[228:229], v[246:247], off offset:2144
	s_nop 0
	v_lshlrev_b32_e32 v143, 16, v144
	v_mul_f32_e32 v143, 0xbfb8aa3b, v143
	v_exp_f32_e32 v143, v143
	s_nop 0
	v_add_f32_e32 v143, 1.0, v143
	v_rcp_f32_e32 v148, v143
	s_nop 0
	v_lshlrev_b32_e32 v143, 16, v146
	v_mul_f32_e32 v143, 0xbfb8aa3b, v143
	v_exp_f32_e32 v150, v143
	v_and_b32_e32 v143, 0xffff0000, v144
	v_mul_f32_e32 v143, 0xbfb8aa3b, v143
	v_exp_f32_e32 v143, v143
	s_nop 0
	v_add_f32_e32 v143, 1.0, v143
	v_rcp_f32_e32 v149, v143
	v_and_b32_e32 v143, 0xffff0000, v146
	v_mul_f32_e32 v143, 0xbfb8aa3b, v143
	v_exp_f32_e32 v151, v143
	v_lshlrev_b32_e32 v143, 16, v145
	v_mul_f32_e32 v143, 0xbfb8aa3b, v143
	v_exp_f32_e32 v143, v143
	v_pk_add_f32 v[150:151], v[150:151], 1.0 op_sel_hi:[1,0]
	v_add_f32_e32 v143, 1.0, v143
	v_rcp_f32_e32 v144, v143
	v_lshlrev_b32_e32 v143, 16, v147
	v_mul_f32_e32 v143, 0xbfb8aa3b, v143
	v_exp_f32_e32 v146, v143
	v_and_b32_e32 v143, 0xffff0000, v145
	v_mul_f32_e32 v143, 0xbfb8aa3b, v143
	v_exp_f32_e32 v143, v143
	v_pk_mul_f32 v[148:149], v[148:149], v[150:151]
	v_add_f32_e32 v143, 1.0, v143
	v_rcp_f32_e32 v145, v143
	v_and_b32_e32 v143, 0xffff0000, v147
	v_mul_f32_e32 v143, 0xbfb8aa3b, v143
	v_exp_f32_e32 v147, v143
	s_nop 0
	v_lshlrev_b32_e32 v143, 16, v138
	v_and_b32_e32 v138, 0xffff0000, v138
	v_mul_f32_e32 v138, 0xbfb8aa3b, v138
	v_exp_f32_e32 v138, v138
	v_pk_add_f32 v[146:147], v[146:147], 1.0 op_sel_hi:[1,0]
	v_mul_f32_e32 v143, 0xbfb8aa3b, v143
	v_pk_mul_f32 v[144:145], v[144:145], v[146:147]
; DI float bflo(unsigned u) { return __uint_as_float(u << 16); }
; DI float bfhi(unsigned u) { return __uint_as_float(u & 0xffff0000u); }
; DI float sigmoidf(float x) { return __builtin_amdgcn_rcpf(1.f + __expf(-x)); }
; DI float inv_sigmoidf(float x) { return 1.f + __expf(-x); }
; DI int TID8() { int t = threadIdx.x; asm volatile("" : "+v"(t)); return t; }
; template <class E>
; DI void gemm8_epi(f32x4 (&acc)[8][4], int m0, int n0, E e) {
;   const int tid = TID8(), lane = tid & 63, w = tid >> 6;
;   const int wm = w >> 2, wn = w & 3;
; #pragma unroll
;   for (int i = 0; i < 8; ++i)
; #pragma unroll
;     for (int j = 0; j < 4; ++j) {
;       const int m = m0 + wm * 128 + i * 16 + (lane & 15);
;       const int n = n0 + wn * 64 + j * 16 + (lane >> 4) * 4;
;       e(m, n, acc[i][j]);
;     }
; }
; __global__ void __launch_bounds__(512, 2) mega(Params p) {
;     ...
;       gemm8_epi(acc8, m0, n0, [&](int m, int n, f32x4& a) {
;         uint2 ua = *(const uint2*)(z + (size_t)m * ZS + C_MA + n);
;         uint2 ub = *(const uint2*)(z + (size_t)m * ZS + C_MB + n);
;         a[0] *= sigmoidf(bflo(ua.x)) * inv_sigmoidf(bflo(ub.x));
;         a[1] *= sigmoidf(bfhi(ua.x)) * inv_sigmoidf(bfhi(ub.x));
;         a[2] *= sigmoidf(bflo(ua.y)) * inv_sigmoidf(bflo(ub.y));
;         a[3] *= sigmoidf(bfhi(ua.y)) * inv_sigmoidf(bfhi(ub.y));
;       });
	v_add_f32_e32 v138, 1.0, v138
	v_pk_mul_f32 v[124:125], v[124:125], v[144:145]
	v_rcp_f32_e32 v145, v138
	s_nop 0
	v_and_b32_e32 v138, 0xffff0000, v140
	v_exp_f32_e32 v143, v143
	v_mul_f32_e32 v138, 0xbfb8aa3b, v138
	v_exp_f32_e32 v147, v138
	v_lshlrev_b32_e32 v138, 16, v139
	v_and_b32_e32 v139, 0xffff0000, v139
	v_mul_f32_e32 v138, 0xbfb8aa3b, v138
	v_mul_f32_e32 v139, 0xbfb8aa3b, v139
	v_exp_f32_e32 v138, v138
	v_exp_f32_e32 v139, v139
	v_add_f32_e32 v143, 1.0, v143
	v_rcp_f32_e32 v144, v143
	v_lshlrev_b32_e32 v143, 16, v140
	v_lshlrev_b32_e32 v140, 16, v141
	v_and_b32_e32 v141, 0xffff0000, v141
	v_mul_f32_e32 v140, 0xbfb8aa3b, v140
	v_mul_f32_e32 v141, 0xbfb8aa3b, v141
	v_add_f32_e32 v138, 1.0, v138
	v_exp_f32_e32 v140, v140
	v_add_f32_e32 v139, 1.0, v139
	v_exp_f32_e32 v141, v141
	v_rcp_f32_e32 v138, v138
	v_rcp_f32_e32 v139, v139
	v_mul_f32_e32 v143, 0xbfb8aa3b, v143
	v_exp_f32_e32 v146, v143
	v_pk_add_f32 v[140:141], v[140:141], 1.0 op_sel_hi:[1,0]
	v_pk_mul_f32 v[122:123], v[122:123], v[148:149]
	v_pk_mul_f32 v[138:139], v[138:139], v[140:141]
	v_pk_add_f32 v[146:147], v[146:147], 1.0 op_sel_hi:[1,0]
	v_pk_mul_f32 v[116:117], v[116:117], v[138:139]
	v_or_b32_e32 v138, 0x50, v142
	v_mad_i64_i32 v[140:141], s[26:27], v138, s35, v[136:137]
	v_pk_mul_f32 v[144:145], v[144:145], v[146:147]
	v_lshl_add_u64 v[138:139], v[140:141], 0, s[30:31]
	v_pk_mul_f32 v[114:115], v[114:115], v[144:145]
	v_lshl_add_u64 v[144:145], v[138:139], 0, v[0:1]
	s_waitcnt vmcnt(23)
	v_mov_b64_e32 v[144:145], v[230:231]
	v_lshl_add_u64 v[140:141], v[140:141], 0, s[42:43]
	v_lshl_add_u64 v[146:147], v[140:141], 0, v[0:1]
	s_waitcnt vmcnt(22)
	v_mov_b64_e32 v[146:147], v[232:233]
	s_nop 0
	v_lshlrev_b32_e32 v143, 16, v144
	v_mul_f32_e32 v143, 0xbfb8aa3b, v143
	v_exp_f32_e32 v143, v143
	s_nop 0
	v_add_f32_e32 v143, 1.0, v143
	v_rcp_f32_e32 v148, v143
	s_nop 0
	v_lshlrev_b32_e32 v143, 16, v146
	v_mul_f32_e32 v143, 0xbfb8aa3b, v143
	v_exp_f32_e32 v150, v143
	v_and_b32_e32 v143, 0xffff0000, v144
	v_mul_f32_e32 v143, 0xbfb8aa3b, v143
	v_exp_f32_e32 v143, v143
	s_nop 0
	v_add_f32_e32 v143, 1.0, v143
	v_rcp_f32_e32 v149, v143
	v_and_b32_e32 v143, 0xffff0000, v146
	v_mul_f32_e32 v143, 0xbfb8aa3b, v143
	v_exp_f32_e32 v151, v143
	v_lshlrev_b32_e32 v143, 16, v145
	v_mul_f32_e32 v143, 0xbfb8aa3b, v143
	v_exp_f32_e32 v143, v143
	v_pk_add_f32 v[150:151], v[150:151], 1.0 op_sel_hi:[1,0]
	v_add_f32_e32 v143, 1.0, v143
	v_rcp_f32_e32 v144, v143
	v_lshlrev_b32_e32 v143, 16, v147
	v_mul_f32_e32 v143, 0xbfb8aa3b, v143
	v_exp_f32_e32 v146, v143
	v_and_b32_e32 v143, 0xffff0000, v145
	v_mul_f32_e32 v143, 0xbfb8aa3b, v143
	v_exp_f32_e32 v143, v143
	v_pk_mul_f32 v[148:149], v[148:149], v[150:151]
	v_add_f32_e32 v143, 1.0, v143
	v_rcp_f32_e32 v145, v143
	v_and_b32_e32 v143, 0xffff0000, v147
	v_mul_f32_e32 v143, 0xbfb8aa3b, v143
	v_exp_f32_e32 v147, v143
	v_pk_mul_f32 v[106:107], v[106:107], v[148:149]
	v_pk_add_f32 v[146:147], v[146:147], 1.0 op_sel_hi:[1,0]
	s_nop 0
	v_pk_mul_f32 v[144:145], v[144:145], v[146:147]
	v_lshl_add_u64 v[146:147], v[140:141], 0, v[134:135]
	v_pk_mul_f32 v[108:109], v[108:109], v[144:145]
	v_lshl_add_u64 v[144:145], v[138:139], 0, v[134:135]
	s_waitcnt vmcnt(21)
	v_mov_b64_e32 v[144:145], v[234:235]
	s_nop 0
	s_waitcnt vmcnt(20)
	v_mov_b64_e32 v[146:147], v[236:237]
	s_nop 0
	v_lshlrev_b32_e32 v143, 16, v144
	v_mul_f32_e32 v143, 0xbfb8aa3b, v143
	v_exp_f32_e32 v143, v143
	s_nop 0
	v_add_f32_e32 v143, 1.0, v143
	v_rcp_f32_e32 v148, v143
	s_nop 0
	v_lshlrev_b32_e32 v143, 16, v146
	v_mul_f32_e32 v143, 0xbfb8aa3b, v143
	v_exp_f32_e32 v150, v143
	v_and_b32_e32 v143, 0xffff0000, v144
	v_mul_f32_e32 v143, 0xbfb8aa3b, v143
	v_exp_f32_e32 v143, v143
	s_nop 0
	v_add_f32_e32 v143, 1.0, v143
	v_rcp_f32_e32 v149, v143
	v_and_b32_e32 v143, 0xffff0000, v146
	v_mul_f32_e32 v143, 0xbfb8aa3b, v143
	v_exp_f32_e32 v151, v143
	v_lshlrev_b32_e32 v143, 16, v145
	v_mul_f32_e32 v143, 0xbfb8aa3b, v143
	v_exp_f32_e32 v143, v143
	v_pk_add_f32 v[150:151], v[150:151], 1.0 op_sel_hi:[1,0]
	v_add_f32_e32 v143, 1.0, v143
	v_rcp_f32_e32 v144, v143
	v_lshlrev_b32_e32 v143, 16, v147
	v_mul_f32_e32 v143, 0xbfb8aa3b, v143
	v_exp_f32_e32 v146, v143
	v_and_b32_e32 v143, 0xffff0000, v145
	v_mul_f32_e32 v143, 0xbfb8aa3b, v143
	v_exp_f32_e32 v143, v143
	v_pk_mul_f32 v[148:149], v[148:149], v[150:151]
	v_add_f32_e32 v143, 1.0, v143
	v_rcp_f32_e32 v145, v143
	v_and_b32_e32 v143, 0xffff0000, v147
	v_mul_f32_e32 v143, 0xbfb8aa3b, v143
	v_exp_f32_e32 v147, v143
	v_pk_mul_f32 v[98:99], v[98:99], v[148:149]
	v_pk_add_f32 v[146:147], v[146:147], 1.0 op_sel_hi:[1,0]
	s_nop 0
	v_pk_mul_f32 v[144:145], v[144:145], v[146:147]
	v_lshl_add_u64 v[146:147], v[140:141], 0, v[132:133]
	v_pk_mul_f32 v[100:101], v[100:101], v[144:145]
	v_lshl_add_u64 v[144:145], v[138:139], 0, v[132:133]
	s_waitcnt vmcnt(19)
	v_mov_b64_e32 v[144:145], v[238:239]
	v_lshl_add_u64 v[138:139], v[138:139], 0, v[130:131]
	s_waitcnt vmcnt(18)
	v_mov_b64_e32 v[146:147], v[240:241]
	v_lshl_add_u64 v[140:141], v[140:141], 0, v[130:131]
	s_waitcnt vmcnt(17)
	v_mov_b64_e32 v[138:139], v[242:243]
	s_nop 0
	s_waitcnt vmcnt(16)
; DI float bflo(unsigned u) { return __uint_as_float(u << 16); }
; DI float bfhi(unsigned u) { return __uint_as_float(u & 0xffff0000u); }
; DI float sigmoidf(float x) { return __builtin_amdgcn_rcpf(1.f + __expf(-x)); }
; DI float inv_sigmoidf(float x) { return 1.f + __expf(-x); }
; DI int TID8() { int t = threadIdx.x; asm volatile("" : "+v"(t)); return t; }
; template <class E>
; DI void gemm8_epi(f32x4 (&acc)[8][4], int m0, int n0, E e) {
;   const int tid = TID8(), lane = tid & 63, w = tid >> 6;
;   const int wm = w >> 2, wn = w & 3;
; #pragma unroll
;   for (int i = 0; i < 8; ++i)
; #pragma unroll
;     for (int j = 0; j < 4; ++j) {
;       const int m = m0 + wm * 128 + i * 16 + (lane & 15);
;       const int n = n0 + wn * 64 + j * 16 + (lane >> 4) * 4;
;       e(m, n, acc[i][j]);
;     }
; }
; __global__ void __launch_bounds__(512, 2) mega(Params p) {
;     ...
;       gemm8_epi(acc8, m0, n0, [&](int m, int n, f32x4& a) {
;         uint2 ua = *(const uint2*)(z + (size_t)m * ZS + C_MA + n);
;         uint2 ub = *(const uint2*)(z + (size_t)m * ZS + C_MB + n);
;         a[0] *= sigmoidf(bflo(ua.x)) * inv_sigmoidf(bflo(ub.x));
;         a[1] *= sigmoidf(bfhi(ua.x)) * inv_sigmoidf(bfhi(ub.x));
;         a[2] *= sigmoidf(bflo(ua.y)) * inv_sigmoidf(bflo(ub.y));
;         a[3] *= sigmoidf(bfhi(ua.y)) * inv_sigmoidf(bfhi(ub.y));
;       });
	v_mov_b64_e32 v[140:141], v[244:245]
	s_nop 0
	v_lshlrev_b32_e32 v143, 16, v144
	v_mul_f32_e32 v143, 0xbfb8aa3b, v143
	v_exp_f32_e32 v143, v143
	s_nop 0
	v_add_f32_e32 v143, 1.0, v143
	v_rcp_f32_e32 v148, v143
	s_nop 0
	v_lshlrev_b32_e32 v143, 16, v146
	v_mul_f32_e32 v143, 0xbfb8aa3b, v143
	v_exp_f32_e32 v150, v143
	v_and_b32_e32 v143, 0xffff0000, v144
	v_mul_f32_e32 v143, 0xbfb8aa3b, v143
	v_exp_f32_e32 v143, v143
	s_nop 0
	v_add_f32_e32 v143, 1.0, v143
	v_rcp_f32_e32 v149, v143
	v_and_b32_e32 v143, 0xffff0000, v146
	v_mul_f32_e32 v143, 0xbfb8aa3b, v143
	v_exp_f32_e32 v151, v143
	v_lshlrev_b32_e32 v143, 16, v145
	v_mul_f32_e32 v143, 0xbfb8aa3b, v143
	v_exp_f32_e32 v143, v143
	v_pk_add_f32 v[150:151], v[150:151], 1.0 op_sel_hi:[1,0]
	v_add_f32_e32 v143, 1.0, v143
	v_rcp_f32_e32 v144, v143
	v_lshlrev_b32_e32 v143, 16, v147
	v_mul_f32_e32 v143, 0xbfb8aa3b, v143
	v_exp_f32_e32 v146, v143
	v_and_b32_e32 v143, 0xffff0000, v145
	v_mul_f32_e32 v143, 0xbfb8aa3b, v143
	v_exp_f32_e32 v143, v143
	v_pk_mul_f32 v[148:149], v[148:149], v[150:151]
	v_add_f32_e32 v143, 1.0, v143
	v_rcp_f32_e32 v145, v143
	v_and_b32_e32 v143, 0xffff0000, v147
	v_mul_f32_e32 v143, 0xbfb8aa3b, v143
	v_exp_f32_e32 v147, v143
	s_nop 0
	v_lshlrev_b32_e32 v143, 16, v138
	v_and_b32_e32 v138, 0xffff0000, v138
	v_mul_f32_e32 v138, 0xbfb8aa3b, v138
	v_exp_f32_e32 v138, v138
	v_pk_add_f32 v[146:147], v[146:147], 1.0 op_sel_hi:[1,0]
	v_mul_f32_e32 v143, 0xbfb8aa3b, v143
	v_pk_mul_f32 v[144:145], v[144:145], v[146:147]
	v_add_f32_e32 v138, 1.0, v138
	v_pk_mul_f32 v[92:93], v[92:93], v[144:145]
	v_rcp_f32_e32 v145, v138
	s_nop 0
	v_and_b32_e32 v138, 0xffff0000, v140
	v_exp_f32_e32 v143, v143
	v_mul_f32_e32 v138, 0xbfb8aa3b, v138
	v_exp_f32_e32 v147, v138
	v_lshlrev_b32_e32 v138, 16, v139
	v_and_b32_e32 v139, 0xffff0000, v139
	v_mul_f32_e32 v138, 0xbfb8aa3b, v138
	v_mul_f32_e32 v139, 0xbfb8aa3b, v139
	v_exp_f32_e32 v138, v138
	v_exp_f32_e32 v139, v139
	v_add_f32_e32 v143, 1.0, v143
	v_rcp_f32_e32 v144, v143
	v_lshlrev_b32_e32 v143, 16, v140
	v_lshlrev_b32_e32 v140, 16, v141
	v_and_b32_e32 v141, 0xffff0000, v141
	v_mul_f32_e32 v140, 0xbfb8aa3b, v140
	v_mul_f32_e32 v141, 0xbfb8aa3b, v141
	v_add_f32_e32 v138, 1.0, v138
	v_exp_f32_e32 v140, v140
	v_add_f32_e32 v139, 1.0, v139
	v_exp_f32_e32 v141, v141
	v_rcp_f32_e32 v138, v138
	v_rcp_f32_e32 v139, v139
	v_mul_f32_e32 v143, 0xbfb8aa3b, v143
	v_exp_f32_e32 v146, v143
	v_pk_add_f32 v[140:141], v[140:141], 1.0 op_sel_hi:[1,0]
	v_pk_mul_f32 v[90:91], v[90:91], v[148:149]
	v_pk_mul_f32 v[138:139], v[138:139], v[140:141]
	v_pk_add_f32 v[146:147], v[146:147], 1.0 op_sel_hi:[1,0]
	v_pk_mul_f32 v[84:85], v[84:85], v[138:139]
	v_or_b32_e32 v138, 0x60, v142
	v_mad_i64_i32 v[140:141], s[26:27], v138, s35, v[136:137]
	v_pk_mul_f32 v[144:145], v[144:145], v[146:147]
	v_lshl_add_u64 v[138:139], v[140:141], 0, s[30:31]
	v_pk_mul_f32 v[82:83], v[82:83], v[144:145]
	v_lshl_add_u64 v[144:145], v[138:139], 0, v[0:1]
	s_waitcnt vmcnt(15)
	v_mov_b64_e32 v[144:145], v[198:199]
	v_lshl_add_u64 v[140:141], v[140:141], 0, s[42:43]
	v_lshl_add_u64 v[146:147], v[140:141], 0, v[0:1]
	s_waitcnt vmcnt(14)
	v_mov_b64_e32 v[146:147], v[200:201]
	s_nop 0
	v_lshlrev_b32_e32 v143, 16, v144
	v_mul_f32_e32 v143, 0xbfb8aa3b, v143
	v_exp_f32_e32 v143, v143
	s_nop 0
	v_add_f32_e32 v143, 1.0, v143
	v_rcp_f32_e32 v148, v143
	s_nop 0
	v_lshlrev_b32_e32 v143, 16, v146
	v_mul_f32_e32 v143, 0xbfb8aa3b, v143
	v_exp_f32_e32 v150, v143
	v_and_b32_e32 v143, 0xffff0000, v144
	v_mul_f32_e32 v143, 0xbfb8aa3b, v143
	v_exp_f32_e32 v143, v143
	s_nop 0
	v_add_f32_e32 v143, 1.0, v143
	v_rcp_f32_e32 v149, v143
	v_and_b32_e32 v143, 0xffff0000, v146
	v_mul_f32_e32 v143, 0xbfb8aa3b, v143
	v_exp_f32_e32 v151, v143
	v_lshlrev_b32_e32 v143, 16, v145
	v_mul_f32_e32 v143, 0xbfb8aa3b, v143
	v_exp_f32_e32 v143, v143
	v_pk_add_f32 v[150:151], v[150:151], 1.0 op_sel_hi:[1,0]
	v_add_f32_e32 v143, 1.0, v143
	v_rcp_f32_e32 v144, v143
	v_lshlrev_b32_e32 v143, 16, v147
	v_mul_f32_e32 v143, 0xbfb8aa3b, v143
	v_exp_f32_e32 v146, v143
	v_and_b32_e32 v143, 0xffff0000, v145
	v_mul_f32_e32 v143, 0xbfb8aa3b, v143
	v_exp_f32_e32 v143, v143
	v_pk_mul_f32 v[148:149], v[148:149], v[150:151]
	v_add_f32_e32 v143, 1.0, v143
	v_rcp_f32_e32 v145, v143
	v_and_b32_e32 v143, 0xffff0000, v147
	v_mul_f32_e32 v143, 0xbfb8aa3b, v143
	v_exp_f32_e32 v147, v143
	v_pk_mul_f32 v[74:75], v[74:75], v[148:149]
	v_pk_add_f32 v[146:147], v[146:147], 1.0 op_sel_hi:[1,0]
	s_nop 0
	v_pk_mul_f32 v[144:145], v[144:145], v[146:147]
	v_lshl_add_u64 v[146:147], v[140:141], 0, v[134:135]
	v_pk_mul_f32 v[76:77], v[76:77], v[144:145]
	v_lshl_add_u64 v[144:145], v[138:139], 0, v[134:135]
	s_waitcnt vmcnt(13)
	v_mov_b64_e32 v[144:145], v[202:203]
	s_nop 0
	s_waitcnt vmcnt(12)
	v_mov_b64_e32 v[146:147], v[204:205]
	s_nop 0
	v_lshlrev_b32_e32 v143, 16, v144
	v_mul_f32_e32 v143, 0xbfb8aa3b, v143
	v_exp_f32_e32 v143, v143
	s_nop 0
	v_add_f32_e32 v143, 1.0, v143
	v_rcp_f32_e32 v148, v143
	s_nop 0
	v_lshlrev_b32_e32 v143, 16, v146
	v_mul_f32_e32 v143, 0xbfb8aa3b, v143
	v_exp_f32_e32 v150, v143
	v_and_b32_e32 v143, 0xffff0000, v144
	v_mul_f32_e32 v143, 0xbfb8aa3b, v143
	v_exp_f32_e32 v143, v143
	s_nop 0
	v_add_f32_e32 v143, 1.0, v143
	v_rcp_f32_e32 v149, v143
	v_and_b32_e32 v143, 0xffff0000, v146
	v_mul_f32_e32 v143, 0xbfb8aa3b, v143
	v_exp_f32_e32 v151, v143
	v_lshlrev_b32_e32 v143, 16, v145
	v_mul_f32_e32 v143, 0xbfb8aa3b, v143
	v_exp_f32_e32 v143, v143
	v_pk_add_f32 v[150:151], v[150:151], 1.0 op_sel_hi:[1,0]
	v_add_f32_e32 v143, 1.0, v143
	v_rcp_f32_e32 v144, v143
	v_lshlrev_b32_e32 v143, 16, v147
	v_mul_f32_e32 v143, 0xbfb8aa3b, v143
	v_exp_f32_e32 v146, v143
	v_and_b32_e32 v143, 0xffff0000, v145
	v_mul_f32_e32 v143, 0xbfb8aa3b, v143
	v_exp_f32_e32 v143, v143
	v_pk_mul_f32 v[148:149], v[148:149], v[150:151]
	v_add_f32_e32 v143, 1.0, v143
	v_rcp_f32_e32 v145, v143
	v_and_b32_e32 v143, 0xffff0000, v147
	v_mul_f32_e32 v143, 0xbfb8aa3b, v143
	v_exp_f32_e32 v147, v143
	v_pk_mul_f32 v[66:67], v[66:67], v[148:149]
	v_pk_add_f32 v[146:147], v[146:147], 1.0 op_sel_hi:[1,0]
	s_nop 0
	v_pk_mul_f32 v[144:145], v[144:145], v[146:147]
	v_lshl_add_u64 v[146:147], v[140:141], 0, v[132:133]
	v_pk_mul_f32 v[68:69], v[68:69], v[144:145]
	v_lshl_add_u64 v[144:145], v[138:139], 0, v[132:133]
	s_waitcnt vmcnt(11)
; DI float bflo(unsigned u) { return __uint_as_float(u << 16); }
; DI float bfhi(unsigned u) { return __uint_as_float(u & 0xffff0000u); }
; DI float sigmoidf(float x) { return __builtin_amdgcn_rcpf(1.f + __expf(-x)); }
; DI float inv_sigmoidf(float x) { return 1.f + __expf(-x); }
; DI int TID8() { int t = threadIdx.x; asm volatile("" : "+v"(t)); return t; }
; template <class E>
; DI void gemm8_epi(f32x4 (&acc)[8][4], int m0, int n0, E e) {
;   const int tid = TID8(), lane = tid & 63, w = tid >> 6;
;   const int wm = w >> 2, wn = w & 3;
; #pragma unroll
;   for (int i = 0; i < 8; ++i)
; #pragma unroll
;     for (int j = 0; j < 4; ++j) {
;       const int m = m0 + wm * 128 + i * 16 + (lane & 15);
;       const int n = n0 + wn * 64 + j * 16 + (lane >> 4) * 4;
;       e(m, n, acc[i][j]);
;     }
; }
; __global__ void __launch_bounds__(512, 2) mega(Params p) {
;     ...
;       gemm8_epi(acc8, m0, n0, [&](int m, int n, f32x4& a) {
;         uint2 ua = *(const uint2*)(z + (size_t)m * ZS + C_MA + n);
;         uint2 ub = *(const uint2*)(z + (size_t)m * ZS + C_MB + n);
;         a[0] *= sigmoidf(bflo(ua.x)) * inv_sigmoidf(bflo(ub.x));
;         a[1] *= sigmoidf(bfhi(ua.x)) * inv_sigmoidf(bfhi(ub.x));
;         a[2] *= sigmoidf(bflo(ua.y)) * inv_sigmoidf(bflo(ub.y));
;         a[3] *= sigmoidf(bfhi(ua.y)) * inv_sigmoidf(bfhi(ub.y));
;       });
	v_mov_b64_e32 v[144:145], v[206:207]
	v_lshl_add_u64 v[138:139], v[138:139], 0, v[130:131]
	s_waitcnt vmcnt(10)
	v_mov_b64_e32 v[146:147], v[208:209]
	v_lshl_add_u64 v[140:141], v[140:141], 0, v[130:131]
	s_waitcnt vmcnt(9)
	v_mov_b64_e32 v[138:139], v[210:211]
	s_nop 0
	s_waitcnt vmcnt(8)
	v_mov_b64_e32 v[140:141], v[212:213]
	s_nop 0
	v_lshlrev_b32_e32 v143, 16, v144
	v_mul_f32_e32 v143, 0xbfb8aa3b, v143
	v_exp_f32_e32 v143, v143
	s_nop 0
	v_add_f32_e32 v143, 1.0, v143
	v_rcp_f32_e32 v148, v143
	s_nop 0
	v_lshlrev_b32_e32 v143, 16, v146
	v_mul_f32_e32 v143, 0xbfb8aa3b, v143
	v_exp_f32_e32 v150, v143
	v_and_b32_e32 v143, 0xffff0000, v144
	v_mul_f32_e32 v143, 0xbfb8aa3b, v143
	v_exp_f32_e32 v143, v143
	s_nop 0
	v_add_f32_e32 v143, 1.0, v143
	v_rcp_f32_e32 v149, v143
	v_and_b32_e32 v143, 0xffff0000, v146
	v_mul_f32_e32 v143, 0xbfb8aa3b, v143
	v_exp_f32_e32 v151, v143
	v_lshlrev_b32_e32 v143, 16, v145
	v_mul_f32_e32 v143, 0xbfb8aa3b, v143
	v_exp_f32_e32 v143, v143
	v_pk_add_f32 v[150:151], v[150:151], 1.0 op_sel_hi:[1,0]
	v_add_f32_e32 v143, 1.0, v143
	v_rcp_f32_e32 v144, v143
	v_lshlrev_b32_e32 v143, 16, v147
	v_mul_f32_e32 v143, 0xbfb8aa3b, v143
	v_exp_f32_e32 v146, v143
	v_and_b32_e32 v143, 0xffff0000, v145
	v_mul_f32_e32 v143, 0xbfb8aa3b, v143
	v_exp_f32_e32 v143, v143
	v_pk_mul_f32 v[148:149], v[148:149], v[150:151]
	v_add_f32_e32 v143, 1.0, v143
	v_rcp_f32_e32 v145, v143
	v_and_b32_e32 v143, 0xffff0000, v147
	v_mul_f32_e32 v143, 0xbfb8aa3b, v143
	v_exp_f32_e32 v147, v143
	s_nop 0
	v_lshlrev_b32_e32 v143, 16, v138
	v_and_b32_e32 v138, 0xffff0000, v138
	v_mul_f32_e32 v138, 0xbfb8aa3b, v138
	v_exp_f32_e32 v138, v138
	v_pk_add_f32 v[146:147], v[146:147], 1.0 op_sel_hi:[1,0]
	v_mul_f32_e32 v143, 0xbfb8aa3b, v143
	v_pk_mul_f32 v[144:145], v[144:145], v[146:147]
	v_add_f32_e32 v138, 1.0, v138
	v_pk_mul_f32 v[60:61], v[60:61], v[144:145]
	v_rcp_f32_e32 v145, v138
	s_nop 0
	v_and_b32_e32 v138, 0xffff0000, v140
	v_exp_f32_e32 v143, v143
	v_mul_f32_e32 v138, 0xbfb8aa3b, v138
	v_exp_f32_e32 v147, v138
	v_lshlrev_b32_e32 v138, 16, v139
	v_and_b32_e32 v139, 0xffff0000, v139
	v_mul_f32_e32 v138, 0xbfb8aa3b, v138
	v_mul_f32_e32 v139, 0xbfb8aa3b, v139
	v_exp_f32_e32 v138, v138
	v_exp_f32_e32 v139, v139
	v_add_f32_e32 v143, 1.0, v143
	v_rcp_f32_e32 v144, v143
	v_lshlrev_b32_e32 v143, 16, v140
	v_lshlrev_b32_e32 v140, 16, v141
	v_and_b32_e32 v141, 0xffff0000, v141
	v_mul_f32_e32 v140, 0xbfb8aa3b, v140
	v_mul_f32_e32 v141, 0xbfb8aa3b, v141
	v_add_f32_e32 v138, 1.0, v138
	v_exp_f32_e32 v140, v140
	v_add_f32_e32 v139, 1.0, v139
	v_exp_f32_e32 v141, v141
	v_rcp_f32_e32 v138, v138
	v_rcp_f32_e32 v139, v139
	v_mul_f32_e32 v143, 0xbfb8aa3b, v143
	v_pk_add_f32 v[140:141], v[140:141], 1.0 op_sel_hi:[1,0]
	v_exp_f32_e32 v146, v143
	v_pk_mul_f32 v[138:139], v[138:139], v[140:141]
	v_pk_mul_f32 v[58:59], v[58:59], v[148:149]
	v_pk_mul_f32 v[52:53], v[52:53], v[138:139]
	v_or_b32_e32 v138, 0x70, v142
	v_mad_i64_i32 v[138:139], s[26:27], v138, s35, v[136:137]
	v_lshl_add_u64 v[136:137], v[138:139], 0, s[30:31]
	v_lshl_add_u64 v[140:141], v[136:137], 0, v[0:1]
	s_waitcnt vmcnt(7)
	v_mov_b64_e32 v[140:141], v[214:215]
	v_lshl_add_u64 v[138:139], v[138:139], 0, s[42:43]
	v_lshl_add_u64 v[142:143], v[138:139], 0, v[0:1]
	s_waitcnt vmcnt(6)
	v_mov_b64_e32 v[142:143], v[216:217]
	v_pk_add_f32 v[146:147], v[146:147], 1.0 op_sel_hi:[1,0]
	s_nop 0
	v_lshlrev_b32_e32 v0, 16, v140
	v_mul_f32_e32 v0, 0xbfb8aa3b, v0
	v_exp_f32_e32 v0, v0
	v_pk_mul_f32 v[144:145], v[144:145], v[146:147]
	v_add_f32_e32 v0, 1.0, v0
	v_pk_mul_f32 v[50:51], v[50:51], v[144:145]
	v_rcp_f32_e32 v144, v0
	s_nop 0
	v_lshlrev_b32_e32 v0, 16, v142
	v_mul_f32_e32 v0, 0xbfb8aa3b, v0
	v_exp_f32_e32 v146, v0
	v_and_b32_e32 v0, 0xffff0000, v140
	v_mul_f32_e32 v0, 0xbfb8aa3b, v0
	v_exp_f32_e32 v0, v0
	s_nop 0
	v_add_f32_e32 v0, 1.0, v0
	v_rcp_f32_e32 v145, v0
	v_and_b32_e32 v0, 0xffff0000, v142
	v_mul_f32_e32 v0, 0xbfb8aa3b, v0
	v_exp_f32_e32 v147, v0
	v_lshlrev_b32_e32 v0, 16, v141
	v_mul_f32_e32 v0, 0xbfb8aa3b, v0
	v_exp_f32_e32 v0, v0
	v_pk_add_f32 v[146:147], v[146:147], 1.0 op_sel_hi:[1,0]
	v_add_f32_e32 v0, 1.0, v0
	v_rcp_f32_e32 v140, v0
	v_lshlrev_b32_e32 v0, 16, v143
	v_mul_f32_e32 v0, 0xbfb8aa3b, v0
	v_exp_f32_e32 v142, v0
	v_and_b32_e32 v0, 0xffff0000, v141
	v_mul_f32_e32 v0, 0xbfb8aa3b, v0
	v_exp_f32_e32 v0, v0
	v_pk_mul_f32 v[144:145], v[144:145], v[146:147]
	v_add_f32_e32 v0, 1.0, v0
	v_rcp_f32_e32 v141, v0
	v_and_b32_e32 v0, 0xffff0000, v143
	v_mul_f32_e32 v0, 0xbfb8aa3b, v0
	v_exp_f32_e32 v143, v0
	v_pk_mul_f32 v[42:43], v[42:43], v[144:145]
	v_pk_add_f32 v[142:143], v[142:143], 1.0 op_sel_hi:[1,0]
	s_nop 0
	v_pk_mul_f32 v[140:141], v[140:141], v[142:143]
	s_nop 0
	v_pk_mul_f32 v[44:45], v[44:45], v[140:141]
	v_lshl_add_u64 v[140:141], v[136:137], 0, v[134:135]
	s_waitcnt vmcnt(5)
	v_mov_b64_e32 v[140:141], v[218:219]
	v_lshl_add_u64 v[134:135], v[138:139], 0, v[134:135]
	s_waitcnt vmcnt(4)
; DI float bflo(unsigned u) { return __uint_as_float(u << 16); }
; DI float bfhi(unsigned u) { return __uint_as_float(u & 0xffff0000u); }
; DI float sigmoidf(float x) { return __builtin_amdgcn_rcpf(1.f + __expf(-x)); }
; DI float inv_sigmoidf(float x) { return 1.f + __expf(-x); }
; DI int TID8() { int t = threadIdx.x; asm volatile("" : "+v"(t)); return t; }
; DI void gemm8_accum(f32x4 (&acc)[8][4], const bf16_t* a, size_t lda, const bf16_t* b, size_t ldb, int nkb, bf16_t* L,
;                     const bool pre, const bf16_t* an, size_t ldan, const bf16_t* bn, size_t ldbn) {
;   const int tid = TID8(), lane = tid & 63, w = tid >> 6;
;   const int wm = w >> 2, wn = w & 3;
;   const int lrow = tid >> 3, lch = tid & 7;
;   u32x4 ra[4], rb[4];
;   unsigned offa[4], offb[4];
; #pragma unroll
;   for (int i = 0; i < 4; ++i) {
;     offa[i] = (unsigned)(lrow + 64 * i) * (unsigned)lda + (unsigned)(lch * 8);
;     offb[i] = (unsigned)(lrow + 64 * i) * (unsigned)ldb + (unsigned)(lch * 8);
;   }
;   if (!pre) {
;     g8_load1o(ra, a, offa);
;     g8_load1o(rb, b, offb);
;     __syncthreads();
;     g8_store(L, ra, rb, lrow, lch);
;   }
;   g8_load1o(ra, a + 64, offa);
;   g8_load1o(rb, b + 64, offb);
; __global__ void __launch_bounds__(512, 2) mega(Params p) {
;     ...
;       gemm8_epi(acc8, m0, n0, [&](int m, int n, f32x4& a) {
;         uint2 ua = *(const uint2*)(z + (size_t)m * ZS + C_MA + n);
;         uint2 ub = *(const uint2*)(z + (size_t)m * ZS + C_MB + n);
;         a[0] *= sigmoidf(bflo(ua.x)) * inv_sigmoidf(bflo(ub.x));
;         a[1] *= sigmoidf(bfhi(ua.x)) * inv_sigmoidf(bfhi(ub.x));
;         a[2] *= sigmoidf(bflo(ua.y)) * inv_sigmoidf(bflo(ub.y));
;         a[3] *= sigmoidf(bfhi(ua.y)) * inv_sigmoidf(bfhi(ub.y));
;       });
	v_mov_b64_e32 v[134:135], v[220:221]
	s_nop 0
	v_lshlrev_b32_e32 v0, 16, v140
	v_mul_f32_e32 v0, 0xbfb8aa3b, v0
	v_exp_f32_e32 v0, v0
	s_nop 0
	v_add_f32_e32 v0, 1.0, v0
	v_rcp_f32_e32 v142, v0
	s_nop 0
	v_lshlrev_b32_e32 v0, 16, v134
	v_mul_f32_e32 v0, 0xbfb8aa3b, v0
	v_exp_f32_e32 v144, v0
	v_and_b32_e32 v0, 0xffff0000, v140
	v_mul_f32_e32 v0, 0xbfb8aa3b, v0
	v_exp_f32_e32 v0, v0
	s_nop 0
	v_add_f32_e32 v0, 1.0, v0
	v_rcp_f32_e32 v143, v0
	v_and_b32_e32 v0, 0xffff0000, v134
	v_mul_f32_e32 v0, 0xbfb8aa3b, v0
	v_exp_f32_e32 v145, v0
	v_lshlrev_b32_e32 v0, 16, v141
	v_mul_f32_e32 v0, 0xbfb8aa3b, v0
	v_exp_f32_e32 v0, v0
	v_pk_add_f32 v[144:145], v[144:145], 1.0 op_sel_hi:[1,0]
	v_add_f32_e32 v0, 1.0, v0
	v_rcp_f32_e32 v140, v0
	v_lshlrev_b32_e32 v0, 16, v135
	v_mul_f32_e32 v0, 0xbfb8aa3b, v0
	v_exp_f32_e32 v134, v0
	v_and_b32_e32 v0, 0xffff0000, v141
	v_mul_f32_e32 v0, 0xbfb8aa3b, v0
	v_exp_f32_e32 v0, v0
	v_pk_mul_f32 v[142:143], v[142:143], v[144:145]
	v_mov_b32_e32 v145, v1
	v_pk_mul_f32 v[34:35], v[34:35], v[142:143]
	v_add_f32_e32 v0, 1.0, v0
	v_rcp_f32_e32 v141, v0
	v_and_b32_e32 v0, 0xffff0000, v135
	v_mul_f32_e32 v0, 0xbfb8aa3b, v0
	v_exp_f32_e32 v135, v0
	s_nop 0
	v_pk_add_f32 v[134:135], v[134:135], 1.0 op_sel_hi:[1,0]
	s_nop 0
	v_pk_mul_f32 v[134:135], v[140:141], v[134:135]
	s_nop 0
	v_pk_mul_f32 v[36:37], v[36:37], v[134:135]
	v_lshl_add_u64 v[134:135], v[136:137], 0, v[132:133]
	s_waitcnt vmcnt(3)
	v_mov_b64_e32 v[134:135], v[222:223]
	v_lshl_add_u64 v[132:133], v[138:139], 0, v[132:133]
	s_waitcnt vmcnt(2)
	v_mov_b64_e32 v[132:133], v[224:225]
	s_nop 0
	v_lshlrev_b32_e32 v0, 16, v134
	v_mul_f32_e32 v0, 0xbfb8aa3b, v0
	v_exp_f32_e32 v0, v0
	s_nop 0
	v_add_f32_e32 v0, 1.0, v0
	v_rcp_f32_e32 v140, v0
	s_nop 0
	v_lshlrev_b32_e32 v0, 16, v132
	v_mul_f32_e32 v0, 0xbfb8aa3b, v0
	v_exp_f32_e32 v142, v0
	v_and_b32_e32 v0, 0xffff0000, v134
	v_mul_f32_e32 v0, 0xbfb8aa3b, v0
	v_exp_f32_e32 v0, v0
	s_nop 0
	v_add_f32_e32 v0, 1.0, v0
	v_rcp_f32_e32 v141, v0
	v_and_b32_e32 v0, 0xffff0000, v132
	v_mul_f32_e32 v0, 0xbfb8aa3b, v0
	v_exp_f32_e32 v143, v0
	v_lshlrev_b32_e32 v0, 16, v135
	v_mul_f32_e32 v0, 0xbfb8aa3b, v0
	v_exp_f32_e32 v0, v0
	v_pk_add_f32 v[142:143], v[142:143], 1.0 op_sel_hi:[1,0]
	v_add_f32_e32 v0, 1.0, v0
	v_rcp_f32_e32 v134, v0
	v_lshlrev_b32_e32 v0, 16, v133
	v_mul_f32_e32 v0, 0xbfb8aa3b, v0
	v_exp_f32_e32 v132, v0
	v_and_b32_e32 v0, 0xffff0000, v135
	v_mul_f32_e32 v0, 0xbfb8aa3b, v0
	v_exp_f32_e32 v0, v0
	v_pk_mul_f32 v[140:141], v[140:141], v[142:143]
	v_mov_b32_e32 v143, v1
	v_pk_mul_f32 v[26:27], v[26:27], v[140:141]
	v_add_f32_e32 v0, 1.0, v0
	v_rcp_f32_e32 v135, v0
	v_and_b32_e32 v0, 0xffff0000, v133
	v_mul_f32_e32 v0, 0xbfb8aa3b, v0
	v_exp_f32_e32 v133, v0
	s_nop 0
	v_pk_add_f32 v[132:133], v[132:133], 1.0 op_sel_hi:[1,0]
	s_nop 0
	v_pk_mul_f32 v[132:133], v[134:135], v[132:133]
	s_nop 0
	v_pk_mul_f32 v[28:29], v[28:29], v[132:133]
	v_lshl_add_u64 v[132:133], v[136:137], 0, v[130:131]
	s_waitcnt vmcnt(1)
	v_mov_b64_e32 v[132:133], v[226:227]
	v_lshl_add_u64 v[130:131], v[138:139], 0, v[130:131]
	s_waitcnt vmcnt(0)
	v_mov_b64_e32 v[130:131], v[228:229]
	v_mov_b32_e32 v139, v1
	v_ashrrev_i32_e32 v173, 3, v172
	v_lshrrev_b32_e32 v140, 1, v173
	v_xor_b32_e32 v140, v140, v172
	v_lshlrev_b32_e32 v140, 3, v140
	v_and_b32_e32 v174, 56, v140
	v_lshrrev_b32_e32 v175, 1, v172
	v_bfe_u32 v176, v172, 1, 3
	v_lshlrev_b32_e32 v191, 1, v174
	v_lshlrev_b32_e32 v163, 6, v173
	s_nop 0
	v_lshlrev_b32_e32 v0, 16, v132
	v_mul_f32_e32 v0, 0xbfb8aa3b, v0
	v_exp_f32_e32 v0, v0
	s_nop 0
	v_add_f32_e32 v0, 1.0, v0
	v_rcp_f32_e32 v134, v0
	s_nop 0
	v_lshlrev_b32_e32 v0, 16, v130
	v_mul_f32_e32 v0, 0xbfb8aa3b, v0
	v_exp_f32_e32 v136, v0
	v_and_b32_e32 v0, 0xffff0000, v132
	v_mul_f32_e32 v0, 0xbfb8aa3b, v0
	v_exp_f32_e32 v0, v0
	s_nop 0
	v_add_f32_e32 v0, 1.0, v0
	v_rcp_f32_e32 v135, v0
	v_and_b32_e32 v0, 0xffff0000, v130
	v_mul_f32_e32 v0, 0xbfb8aa3b, v0
	v_exp_f32_e32 v137, v0
	v_lshlrev_b32_e32 v0, 16, v133
	v_mul_f32_e32 v0, 0xbfb8aa3b, v0
	v_exp_f32_e32 v0, v0
	v_pk_add_f32 v[136:137], v[136:137], 1.0 op_sel_hi:[1,0]
	v_add_f32_e32 v0, 1.0, v0
	v_rcp_f32_e32 v132, v0
	v_lshlrev_b32_e32 v0, 16, v131
	v_mul_f32_e32 v0, 0xbfb8aa3b, v0
	v_exp_f32_e32 v130, v0
	v_and_b32_e32 v0, 0xffff0000, v133
	v_mul_f32_e32 v0, 0xbfb8aa3b, v0
	v_exp_f32_e32 v0, v0
	v_pk_mul_f32 v[134:135], v[134:135], v[136:137]
	v_mov_b32_e32 v137, v1
	v_pk_mul_f32 v[18:19], v[18:19], v[134:135]
	v_add_f32_e32 v0, 1.0, v0
	v_rcp_f32_e32 v133, v0
	v_and_b32_e32 v0, 0xffff0000, v131
	v_mul_f32_e32 v0, 0xbfb8aa3b, v0
	v_exp_f32_e32 v131, v0
	v_lshlrev_b32_e32 v0, 3, v172
	v_and_b32_e32 v0, 56, v0
	v_mov_b32_e32 v135, v1
	v_pk_add_f32 v[130:131], v[130:131], 1.0 op_sel_hi:[1,0]
	s_nop 0
	v_pk_mul_f32 v[130:131], v[132:133], v[130:131]
	v_lshl_or_b32 v132, v173, 9, v0
	v_pk_mul_f32 v[20:21], v[20:21], v[130:131]
	v_mad_u64_u32 v[130:131], s[26:27], v173, s25, v[0:1]
	v_mov_b32_e32 v131, v1
	v_add_u32_e32 v144, 0x18000, v132
	v_add_u32_e32 v0, 0x54600, v130
	v_add_u32_e32 v142, 0x10000, v132
	v_lshlrev_b64 v[186:187], 1, v[130:131]
	v_lshlrev_b64 v[170:171], 1, v[144:145]
	v_add_u32_e32 v136, 0xa8c00, v130
	v_add_u32_e32 v138, 0xfd200, v130
	v_lshl_add_u64 v[130:131], s[2:3], 0, v[186:187]
	v_lshlrev_b64 v[184:185], 1, v[0:1]
	v_lshlrev_b64 v[168:169], 1, v[142:143]
	v_lshl_add_u64 v[142:143], s[6:7], 0, v[170:171]
	global_load_dwordx4 v[146:149], v[130:131], off offset:2736
	v_lshlrev_b64 v[182:183], 1, v[136:137]
	global_load_dwordx4 v[142:145], v[142:143], off offset:128
	v_lshl_add_u64 v[130:131], s[2:3], 0, v[184:185]
	v_add_u32_e32 v134, 0x8000, v132
	v_mov_b32_e32 v133, v1
; DI int TID8() { int t = threadIdx.x; asm volatile("" : "+v"(t)); return t; }
; DI void gemm8_accum(f32x4 (&acc)[8][4], const bf16_t* a, size_t lda, const bf16_t* b, size_t ldb, int nkb, bf16_t* L,
;                     const bool pre, const bf16_t* an, size_t ldan, const bf16_t* bn, size_t ldbn) {
;   const int tid = TID8(), lane = tid & 63, w = tid >> 6;
;   const int wm = w >> 2, wn = w & 3;
;   const int lrow = tid >> 3, lch = tid & 7;
;   u32x4 ra[4], rb[4];
;   unsigned offa[4], offb[4];
; #pragma unroll
;   for (int i = 0; i < 4; ++i) {
;     offa[i] = (unsigned)(lrow + 64 * i) * (unsigned)lda + (unsigned)(lch * 8);
;     offb[i] = (unsigned)(lrow + 64 * i) * (unsigned)ldb + (unsigned)(lch * 8);
;   }
;   if (!pre) {
;     g8_load1o(ra, a, offa);
;     g8_load1o(rb, b, offb);
;     __syncthreads();
;     g8_store(L, ra, rb, lrow, lch);
;   }
;   g8_load1o(ra, a + 64, offa);
;   g8_load1o(rb, b + 64, offb);
;   for (int kb = 0; kb + 2 < nkb; ++kb) {
;     __syncthreads();
;     g8_store1(L + ((kb + 1) & 1) * 32768, ra, lrow, lch);
;     g8_load1o(ra, a + (kb + 2) * 64, offa);
;     __builtin_amdgcn_sched_barrier(0);
;     g8_compute<0, 1>(acc, L + (kb & 1) * 32768, wm, wn, lane);
;     __builtin_amdgcn_sched_barrier(0);
;     g8_store1(L + ((kb + 1) & 1) * 32768 + 16384, rb, lrow, lch);
;     g8_load1o(rb, b + (kb + 2) * 64, offb);
;     __builtin_amdgcn_sched_barrier(0);
;     g8_compute<1, 2>(acc, L + (kb & 1) * 32768, wm, wn, lane);
	global_load_dwordx4 v[150:153], v[130:131], off offset:2736
	v_lshl_add_u64 v[130:131], s[2:3], 0, v[182:183]
	v_lshlrev_b64 v[180:181], 1, v[138:139]
	global_load_dwordx4 v[154:157], v[130:131], off offset:2736
	v_lshl_add_u64 v[130:131], s[2:3], 0, v[180:181]
	v_lshlrev_b64 v[164:165], 1, v[132:133]
	v_lshlrev_b64 v[166:167], 1, v[134:135]
	global_load_dwordx4 v[158:161], v[130:131], off offset:2736
	v_lshl_add_u64 v[130:131], s[6:7], 0, v[164:165]
	v_lshl_add_u64 v[134:135], s[6:7], 0, v[166:167]
	global_load_dwordx4 v[130:133], v[130:131], off offset:128
	v_bfe_u32 v0, v172, 4, 2
	global_load_dwordx4 v[138:141], v[134:135], off offset:128
	v_lshl_add_u64 v[134:135], s[6:7], 0, v[168:169]
	global_load_dwordx4 v[134:137], v[134:135], off offset:128
	v_bitop3_b32 v175, v175, v0, 7 bitop3:0x6c
	v_lshlrev_b32_e32 v192, 3, v175
	v_lshlrev_b32_e32 v175, 5, v172
	v_and_b32_e32 v175, 0xffffe000, v175
	v_lshlrev_b32_e32 v172, 6, v172
	v_and_or_b32 v188, v172, s1, v175
	v_readlane_b32 s1, v254, 20
	s_add_u32 s2, s1, s21
	v_readlane_b32 s1, v254, 21
	s_addc_u32 s3, s1, 0
	v_readlane_b32 s1, v254, 22
	v_bitop3_b32 v0, v0, v176, 4 bitop3:0x36
	s_add_u32 s0, s1, s0
	v_readlane_b32 s1, v254, 23
	v_and_b32_e32 v193, 0x33c0, v172
	v_lshlrev_b32_e32 v190, 3, v0
	v_lshlrev_b32_e32 v0, 7, v173
	s_addc_u32 s1, s1, 0
	v_add3_u32 v0, 0, v191, v0
	v_lshl_add_u64 v[172:173], s[2:3], 0, v[170:171]
	v_lshl_add_u64 v[174:175], s[2:3], 0, v[168:169]
	v_lshl_add_u64 v[176:177], s[2:3], 0, v[166:167]
	v_lshl_add_u64 v[178:179], s[2:3], 0, v[164:165]
	v_lshl_add_u64 v[180:181], s[0:1], 0, v[180:181]
	v_lshl_add_u64 v[182:183], s[0:1], 0, v[182:183]
	v_lshl_add_u64 v[184:185], s[0:1], 0, v[184:185]
	v_lshl_add_u64 v[186:187], s[0:1], 0, v[186:187]
	s_mov_b64 s[0:1], 0
	s_mov_b32 s2, 0
	v_lshlrev_b32_e32 v189, 1, v188
	v_lshlrev_b32_e32 v188, 1, v193
	v_readfirstlane_b32 s52, v186
	v_readfirstlane_b32 s53, v187
	s_sub_u32 s52, s52, 0x40000000
	s_subb_u32 s53, s53, 0
	v_readfirstlane_b32 s56, v178
	v_readfirstlane_b32 s57, v179
	s_sub_u32 s56, s56, 0x40000000
	s_subb_u32 s57, s57, 0
	v_subrev_u32_e32 v187, s52, v186
	v_subrev_u32_e32 v185, s52, v184
	v_subrev_u32_e32 v183, s52, v182
	v_subrev_u32_e32 v181, s52, v180
	v_subrev_u32_e32 v179, s56, v178
	v_subrev_u32_e32 v177, s56, v176
	v_subrev_u32_e32 v175, s56, v174
	v_subrev_u32_e32 v173, s56, v172
	v_lshl_add_u32 v172, v192, 1, v189
	v_lshl_add_u32 v174, v192, 1, v188
	v_lshl_add_u32 v176, v190, 1, v189
	v_lshl_add_u32 v178, v190, 1, v188
.LBB0_780:
	s_xor_b32 s6, s2, 0x10000
	v_add_u32_e32 v193, s6, v0
	s_waitcnt lgkmcnt(0)
	s_barrier
	s_cmp_eq_u32 s100, 0
	s_cbranch_scc1 .Lstg_780_a
	v_mfma_f32_16x16x32_bf16 v[2:5], v[234:237], v[198:201], v[2:5]
	v_mfma_f32_16x16x32_bf16 v[6:9], v[238:241], v[198:201], v[6:9]
	v_mfma_f32_16x16x32_bf16 v[10:13], v[242:245], v[198:201], v[10:13]
	v_mfma_f32_16x16x32_bf16 v[14:17], v[246:249], v[198:201], v[14:17]
	v_mfma_f32_16x16x32_bf16 v[22:25], v[234:237], v[206:209], v[22:25]
	v_mfma_f32_16x16x32_bf16 v[30:33], v[238:241], v[206:209], v[30:33]
	v_mfma_f32_16x16x32_bf16 v[38:41], v[242:245], v[206:209], v[38:41]
	v_mfma_f32_16x16x32_bf16 v[46:49], v[246:249], v[206:209], v[46:49]
	v_mfma_f32_16x16x32_bf16 v[54:57], v[234:237], v[210:213], v[54:57]
	v_mfma_f32_16x16x32_bf16 v[62:65], v[238:241], v[210:213], v[62:65]
	v_mfma_f32_16x16x32_bf16 v[70:73], v[242:245], v[210:213], v[70:73]
	v_mfma_f32_16x16x32_bf16 v[78:81], v[246:249], v[210:213], v[78:81]
	v_mfma_f32_16x16x32_bf16 v[86:89], v[234:237], v[214:217], v[86:89]
	v_mfma_f32_16x16x32_bf16 v[94:97], v[238:241], v[214:217], v[94:97]
	v_mfma_f32_16x16x32_bf16 v[102:105], v[242:245], v[214:217], v[102:105]
	v_mfma_f32_16x16x32_bf16 v[110:113], v[246:249], v[214:217], v[110:113]
	v_mfma_f32_16x16x32_bf16 v[118:121], v[234:237], v[218:221], v[118:121]
	v_mfma_f32_16x16x32_bf16 v[126:129], v[238:241], v[218:221], v[126:129]
	v_mfma_f32_16x16x32_bf16 v[122:125], v[242:245], v[218:221], v[122:125]
	v_mfma_f32_16x16x32_bf16 v[114:117], v[246:249], v[218:221], v[114:117]
	v_mfma_f32_16x16x32_bf16 v[106:109], v[234:237], v[222:225], v[106:109]
	v_mfma_f32_16x16x32_bf16 v[98:101], v[238:241], v[222:225], v[98:101]
	v_mfma_f32_16x16x32_bf16 v[90:93], v[242:245], v[222:225], v[90:93]
	v_mfma_f32_16x16x32_bf16 v[82:85], v[246:249], v[222:225], v[82:85]
	v_mfma_f32_16x16x32_bf16 v[74:77], v[234:237], v[226:229], v[74:77]
	v_mfma_f32_16x16x32_bf16 v[66:69], v[238:241], v[226:229], v[66:69]
	v_mfma_f32_16x16x32_bf16 v[58:61], v[242:245], v[226:229], v[58:61]
	v_mfma_f32_16x16x32_bf16 v[50:53], v[246:249], v[226:229], v[50:53]
	v_mfma_f32_16x16x32_bf16 v[42:45], v[234:237], v[230:233], v[42:45]
	v_mfma_f32_16x16x32_bf16 v[34:37], v[238:241], v[230:233], v[34:37]
	v_mfma_f32_16x16x32_bf16 v[26:29], v[242:245], v[230:233], v[26:29]
	v_mfma_f32_16x16x32_bf16 v[18:21], v[246:249], v[230:233], v[18:21]
; DI void gemm8_accum(f32x4 (&acc)[8][4], const bf16_t* a, size_t lda, const bf16_t* b, size_t ldb, int nkb, bf16_t* L,
;                     const bool pre, const bf16_t* an, size_t ldan, const bf16_t* bn, size_t ldbn) {
;     ...
;   for (int kb = 0; kb + 2 < nkb; ++kb) {
;     __syncthreads();
;     g8_store1(L + ((kb + 1) & 1) * 32768, ra, lrow, lch);
;     g8_load1o(ra, a + (kb + 2) * 64, offa);
;     __builtin_amdgcn_sched_barrier(0);
;     g8_compute<0, 1>(acc, L + (kb & 1) * 32768, wm, wn, lane);
;     __builtin_amdgcn_sched_barrier(0);
;     g8_store1(L + ((kb + 1) & 1) * 32768 + 16384, rb, lrow, lch);
;     g8_load1o(rb, b + (kb + 2) * 64, offb);
;     __builtin_amdgcn_sched_barrier(0);
;     g8_compute<1, 2>(acc, L + (kb & 1) * 32768, wm, wn, lane);
.Lstg_780_a:
	s_waitcnt vmcnt(3)
	ds_write_b128 v193, v[146:149]
	ds_write_b128 v193, v[150:153] offset:8192
	ds_write_b128 v193, v[154:157] offset:16384
	ds_write_b128 v193, v[158:161] offset:24576
	s_add_u32 s54, s52, s0
	s_addc_u32 s55, s53, s1
	global_load_dwordx4 v[146:149], v187, s[54:55]
	global_load_dwordx4 v[150:153], v185, s[54:55]
	global_load_dwordx4 v[154:157], v183, s[54:55]
	global_load_dwordx4 v[158:161], v181, s[54:55]
	v_add_u32_e32 v195, s2, v172
	ds_read_b128 v[198:201], v195
	ds_read_b128 v[206:209], v195 offset:2048
	ds_read_b128 v[210:213], v195 offset:4096
	ds_read_b128 v[214:217], v195 offset:6144
	ds_read_b128 v[218:221], v195 offset:8192
	ds_read_b128 v[222:225], v195 offset:10240
	ds_read_b128 v[226:229], v195 offset:12288
	ds_read_b128 v[230:233], v195 offset:14336
	v_add_u32_e32 v194, s2, v174
	ds_read_b128 v[234:237], v194 offset:32768
	ds_read_b128 v[238:241], v194 offset:34816
	ds_read_b128 v[242:245], v194 offset:36864
	ds_read_b128 v[246:249], v194 offset:38912
	s_waitcnt lgkmcnt(3)
	v_mfma_f32_16x16x32_bf16 v[2:5], v[234:237], v[198:201], v[2:5]
	s_waitcnt lgkmcnt(2)
	v_mfma_f32_16x16x32_bf16 v[6:9], v[238:241], v[198:201], v[6:9]
	s_waitcnt lgkmcnt(1)
	v_mfma_f32_16x16x32_bf16 v[10:13], v[242:245], v[198:201], v[10:13]
	s_waitcnt lgkmcnt(0)
	v_mfma_f32_16x16x32_bf16 v[14:17], v[246:249], v[198:201], v[14:17]
	v_mfma_f32_16x16x32_bf16 v[22:25], v[234:237], v[206:209], v[22:25]
	v_mfma_f32_16x16x32_bf16 v[30:33], v[238:241], v[206:209], v[30:33]
	v_mfma_f32_16x16x32_bf16 v[38:41], v[242:245], v[206:209], v[38:41]
	v_mfma_f32_16x16x32_bf16 v[46:49], v[246:249], v[206:209], v[46:49]
	v_mfma_f32_16x16x32_bf16 v[54:57], v[234:237], v[210:213], v[54:57]
	v_mfma_f32_16x16x32_bf16 v[62:65], v[238:241], v[210:213], v[62:65]
	v_mfma_f32_16x16x32_bf16 v[70:73], v[242:245], v[210:213], v[70:73]
	v_mfma_f32_16x16x32_bf16 v[78:81], v[246:249], v[210:213], v[78:81]
	v_mfma_f32_16x16x32_bf16 v[86:89], v[234:237], v[214:217], v[86:89]
	v_mfma_f32_16x16x32_bf16 v[94:97], v[238:241], v[214:217], v[94:97]
	v_mfma_f32_16x16x32_bf16 v[102:105], v[242:245], v[214:217], v[102:105]
	v_mfma_f32_16x16x32_bf16 v[110:113], v[246:249], v[214:217], v[110:113]
	v_mfma_f32_16x16x32_bf16 v[118:121], v[234:237], v[218:221], v[118:121]
	v_mfma_f32_16x16x32_bf16 v[126:129], v[238:241], v[218:221], v[126:129]
	v_mfma_f32_16x16x32_bf16 v[122:125], v[242:245], v[218:221], v[122:125]
	v_mfma_f32_16x16x32_bf16 v[114:117], v[246:249], v[218:221], v[114:117]
	v_mfma_f32_16x16x32_bf16 v[106:109], v[234:237], v[222:225], v[106:109]
	v_mfma_f32_16x16x32_bf16 v[98:101], v[238:241], v[222:225], v[98:101]
	v_mfma_f32_16x16x32_bf16 v[90:93], v[242:245], v[222:225], v[90:93]
	v_mfma_f32_16x16x32_bf16 v[82:85], v[246:249], v[222:225], v[82:85]
	v_mfma_f32_16x16x32_bf16 v[74:77], v[234:237], v[226:229], v[74:77]
	v_mfma_f32_16x16x32_bf16 v[66:69], v[238:241], v[226:229], v[66:69]
	v_mfma_f32_16x16x32_bf16 v[58:61], v[242:245], v[226:229], v[58:61]
	v_mfma_f32_16x16x32_bf16 v[50:53], v[246:249], v[226:229], v[50:53]
	v_mfma_f32_16x16x32_bf16 v[42:45], v[234:237], v[230:233], v[42:45]
	v_mfma_f32_16x16x32_bf16 v[34:37], v[238:241], v[230:233], v[34:37]
	v_mfma_f32_16x16x32_bf16 v[26:29], v[242:245], v[230:233], v[26:29]
	v_mfma_f32_16x16x32_bf16 v[18:21], v[246:249], v[230:233], v[18:21]
	s_waitcnt vmcnt(4)
	ds_write_b128 v193, v[130:133] offset:32768
	ds_write_b128 v193, v[138:141] offset:40960
	ds_write_b128 v193, v[134:137] offset:49152
	ds_write_b128 v193, v[142:145] offset:57344
	s_add_u32 s58, s56, s0
	s_addc_u32 s59, s57, s1
	global_load_dwordx4 v[130:133], v179, s[58:59]
	global_load_dwordx4 v[138:141], v177, s[58:59]
	global_load_dwordx4 v[134:137], v175, s[58:59]
	global_load_dwordx4 v[142:145], v173, s[58:59]
	v_add_u32_e32 v194, s2, v176
	ds_read_b128 v[198:201], v194
	ds_read_b128 v[206:209], v194 offset:2048
	ds_read_b128 v[210:213], v194 offset:4096
	ds_read_b128 v[214:217], v194 offset:6144
	ds_read_b128 v[218:221], v194 offset:8192
	ds_read_b128 v[222:225], v194 offset:10240
	ds_read_b128 v[226:229], v194 offset:12288
	ds_read_b128 v[230:233], v194 offset:14336
	v_add_u32_e32 v193, s2, v178
	ds_read_b128 v[234:237], v193 offset:32768
	ds_read_b128 v[238:241], v193 offset:34816
	ds_read_b128 v[242:245], v193 offset:36864
	ds_read_b128 v[246:249], v193 offset:38912
	s_cmp_lg_u32 s101, 0
	s_cbranch_scc1 .Lstg_780_b
	s_waitcnt lgkmcnt(3)
	v_mfma_f32_16x16x32_bf16 v[2:5], v[234:237], v[198:201], v[2:5]
	s_waitcnt lgkmcnt(2)
	v_mfma_f32_16x16x32_bf16 v[6:9], v[238:241], v[198:201], v[6:9]
	s_waitcnt lgkmcnt(1)
	v_mfma_f32_16x16x32_bf16 v[10:13], v[242:245], v[198:201], v[10:13]
	s_waitcnt lgkmcnt(0)
	v_mfma_f32_16x16x32_bf16 v[14:17], v[246:249], v[198:201], v[14:17]
	v_mfma_f32_16x16x32_bf16 v[22:25], v[234:237], v[206:209], v[22:25]
	v_mfma_f32_16x16x32_bf16 v[30:33], v[238:241], v[206:209], v[30:33]
	v_mfma_f32_16x16x32_bf16 v[38:41], v[242:245], v[206:209], v[38:41]
	v_mfma_f32_16x16x32_bf16 v[46:49], v[246:249], v[206:209], v[46:49]
	v_mfma_f32_16x16x32_bf16 v[54:57], v[234:237], v[210:213], v[54:57]
	v_mfma_f32_16x16x32_bf16 v[62:65], v[238:241], v[210:213], v[62:65]
	v_mfma_f32_16x16x32_bf16 v[70:73], v[242:245], v[210:213], v[70:73]
	v_mfma_f32_16x16x32_bf16 v[78:81], v[246:249], v[210:213], v[78:81]
	v_mfma_f32_16x16x32_bf16 v[86:89], v[234:237], v[214:217], v[86:89]
	v_mfma_f32_16x16x32_bf16 v[94:97], v[238:241], v[214:217], v[94:97]
	v_mfma_f32_16x16x32_bf16 v[102:105], v[242:245], v[214:217], v[102:105]
	v_mfma_f32_16x16x32_bf16 v[110:113], v[246:249], v[214:217], v[110:113]
	v_mfma_f32_16x16x32_bf16 v[118:121], v[234:237], v[218:221], v[118:121]
	v_mfma_f32_16x16x32_bf16 v[126:129], v[238:241], v[218:221], v[126:129]
	v_mfma_f32_16x16x32_bf16 v[122:125], v[242:245], v[218:221], v[122:125]
	v_mfma_f32_16x16x32_bf16 v[114:117], v[246:249], v[218:221], v[114:117]
	v_mfma_f32_16x16x32_bf16 v[106:109], v[234:237], v[222:225], v[106:109]
	v_mfma_f32_16x16x32_bf16 v[98:101], v[238:241], v[222:225], v[98:101]
	v_mfma_f32_16x16x32_bf16 v[90:93], v[242:245], v[222:225], v[90:93]
	v_mfma_f32_16x16x32_bf16 v[82:85], v[246:249], v[222:225], v[82:85]
	v_mfma_f32_16x16x32_bf16 v[74:77], v[234:237], v[226:229], v[74:77]
	v_mfma_f32_16x16x32_bf16 v[66:69], v[238:241], v[226:229], v[66:69]
	v_mfma_f32_16x16x32_bf16 v[58:61], v[242:245], v[226:229], v[58:61]
	v_mfma_f32_16x16x32_bf16 v[50:53], v[246:249], v[226:229], v[50:53]
	v_mfma_f32_16x16x32_bf16 v[42:45], v[234:237], v[230:233], v[42:45]
	v_mfma_f32_16x16x32_bf16 v[34:37], v[238:241], v[230:233], v[34:37]
	v_mfma_f32_16x16x32_bf16 v[26:29], v[242:245], v[230:233], v[26:29]
	v_mfma_f32_16x16x32_bf16 v[18:21], v[246:249], v[230:233], v[18:21]
; DI void gemm8_accum(f32x4 (&acc)[8][4], const bf16_t* a, size_t lda, const bf16_t* b, size_t ldb, int nkb, bf16_t* L,
;                     const bool pre, const bf16_t* an, size_t ldan, const bf16_t* bn, size_t ldbn) {
;     ...
;   for (int kb = 0; kb + 2 < nkb; ++kb) {
;     __syncthreads();
;     g8_store1(L + ((kb + 1) & 1) * 32768, ra, lrow, lch);
;     g8_load1o(ra, a + (kb + 2) * 64, offa);
;     __builtin_amdgcn_sched_barrier(0);
;     g8_compute<0, 1>(acc, L + (kb & 1) * 32768, wm, wn, lane);
;     __builtin_amdgcn_sched_barrier(0);
;     g8_store1(L + ((kb + 1) & 1) * 32768 + 16384, rb, lrow, lch);
;     g8_load1o(rb, b + (kb + 2) * 64, offb);
;     __builtin_amdgcn_sched_barrier(0);
;     g8_compute<1, 2>(acc, L + (kb & 1) * 32768, wm, wn, lane);
;   }
;   __syncthreads();
;   g8_store1(L + 32768, ra, lrow, lch);
;   g8_load1(ra, an, ldan, 0, lrow, lch);
;   __builtin_amdgcn_sched_barrier(0);
;   g8_compute<0, 1>(acc, L, wm, wn, lane);
.Lstg_780_b:
	s_mov_b32 s100, s101
	s_xor_b32 s2, s2, 0x10000
	s_add_u32 s0, s0, 0x80
	s_addc_u32 s1, s1, 0
	s_cmpk_lg_i32 s0, 0x300
	s_cbranch_scc1 .LBB0_780
	s_cmp_eq_u32 s100, 0
	s_cbranch_scc1 .Lstg_780_c
	s_waitcnt lgkmcnt(0)
	v_mfma_f32_16x16x32_bf16 v[2:5], v[234:237], v[198:201], v[2:5]
	v_mfma_f32_16x16x32_bf16 v[6:9], v[238:241], v[198:201], v[6:9]
	v_mfma_f32_16x16x32_bf16 v[10:13], v[242:245], v[198:201], v[10:13]
	v_mfma_f32_16x16x32_bf16 v[14:17], v[246:249], v[198:201], v[14:17]
	v_mfma_f32_16x16x32_bf16 v[22:25], v[234:237], v[206:209], v[22:25]
	v_mfma_f32_16x16x32_bf16 v[30:33], v[238:241], v[206:209], v[30:33]
	v_mfma_f32_16x16x32_bf16 v[38:41], v[242:245], v[206:209], v[38:41]
	v_mfma_f32_16x16x32_bf16 v[46:49], v[246:249], v[206:209], v[46:49]
	v_mfma_f32_16x16x32_bf16 v[54:57], v[234:237], v[210:213], v[54:57]
	v_mfma_f32_16x16x32_bf16 v[62:65], v[238:241], v[210:213], v[62:65]
	v_mfma_f32_16x16x32_bf16 v[70:73], v[242:245], v[210:213], v[70:73]
	v_mfma_f32_16x16x32_bf16 v[78:81], v[246:249], v[210:213], v[78:81]
	v_mfma_f32_16x16x32_bf16 v[86:89], v[234:237], v[214:217], v[86:89]
	v_mfma_f32_16x16x32_bf16 v[94:97], v[238:241], v[214:217], v[94:97]
	v_mfma_f32_16x16x32_bf16 v[102:105], v[242:245], v[214:217], v[102:105]
	v_mfma_f32_16x16x32_bf16 v[110:113], v[246:249], v[214:217], v[110:113]
	v_mfma_f32_16x16x32_bf16 v[118:121], v[234:237], v[218:221], v[118:121]
	v_mfma_f32_16x16x32_bf16 v[126:129], v[238:241], v[218:221], v[126:129]
	v_mfma_f32_16x16x32_bf16 v[122:125], v[242:245], v[218:221], v[122:125]
	v_mfma_f32_16x16x32_bf16 v[114:117], v[246:249], v[218:221], v[114:117]
	v_mfma_f32_16x16x32_bf16 v[106:109], v[234:237], v[222:225], v[106:109]
	v_mfma_f32_16x16x32_bf16 v[98:101], v[238:241], v[222:225], v[98:101]
	v_mfma_f32_16x16x32_bf16 v[90:93], v[242:245], v[222:225], v[90:93]
	v_mfma_f32_16x16x32_bf16 v[82:85], v[246:249], v[222:225], v[82:85]
	v_mfma_f32_16x16x32_bf16 v[74:77], v[234:237], v[226:229], v[74:77]
	v_mfma_f32_16x16x32_bf16 v[66:69], v[238:241], v[226:229], v[66:69]
	v_mfma_f32_16x16x32_bf16 v[58:61], v[242:245], v[226:229], v[58:61]
	v_mfma_f32_16x16x32_bf16 v[50:53], v[246:249], v[226:229], v[50:53]
	v_mfma_f32_16x16x32_bf16 v[42:45], v[234:237], v[230:233], v[42:45]
	v_mfma_f32_16x16x32_bf16 v[34:37], v[238:241], v[230:233], v[34:37]
	v_mfma_f32_16x16x32_bf16 v[26:29], v[242:245], v[230:233], v[26:29]
	v_mfma_f32_16x16x32_bf16 v[18:21], v[246:249], v[230:233], v[18:21]
	s_mov_b32 s100, 0

; DI int TID8() { int t = threadIdx.x; asm volatile("" : "+v"(t)); return t; }
; DI void gemm8_accum(f32x4 (&acc)[8][4], const bf16_t* a, size_t lda, const bf16_t* b, size_t ldb, int nkb, bf16_t* L,
;                     const bool pre, const bf16_t* an, size_t ldan, const bf16_t* bn, size_t ldbn) {
;   const int tid = TID8(), lane = tid & 63, w = tid >> 6;
;   const int wm = w >> 2, wn = w & 3;
;   const int lrow = tid >> 3, lch = tid & 7;
;   u32x4 ra[4], rb[4];
;   unsigned offa[4], offb[4];
; #pragma unroll
;   for (int i = 0; i < 4; ++i) {
;     offa[i] = (unsigned)(lrow + 64 * i) * (unsigned)lda + (unsigned)(lch * 8);
;     offb[i] = (unsigned)(lrow + 64 * i) * (unsigned)ldb + (unsigned)(lch * 8);
;   }
;   if (!pre) {
;     g8_load1o(ra, a, offa);
;     g8_load1o(rb, b, offb);
;     __syncthreads();
;     g8_store(L, ra, rb, lrow, lch);
;   }
;   g8_load1o(ra, a + 64, offa);
;   g8_load1o(rb, b + 64, offb);
; __global__ void __launch_bounds__(512, 2) mega(Params p) {
;     ...
;       gemm8_accum(acc8, z + (size_t)m0 * ZS + C_RK, ZS, wl + W_OUT + (size_t)n0 * 1024, 1024, 16, lds_all, !first_,
;                   z + (size_t)mtn * 256 * ZS + C_RK, ZS, wl + W_OUT + (size_t)ntilen * 256 * 1024, 1024);
.LBB0_829:
	v_lshlrev_b64 v[38:39], 1, v[0:1]
	v_lshlrev_b64 v[40:41], 1, v[176:177]
	v_lshl_add_u64 v[2:3], s[2:3], 0, v[38:39]
	v_lshl_add_u64 v[4:5], s[2:3], 0, v[40:41]
	v_lshlrev_b64 v[42:43], 1, v[174:175]
	v_lshlrev_b64 v[44:45], 1, v[172:173]
	global_load_dwordx4 v[18:21], v[2:3], off offset:3760
	global_load_dwordx4 v[22:25], v[4:5], off offset:3760
	v_lshl_add_u64 v[2:3], s[2:3], 0, v[42:43]
	v_lshl_add_u64 v[4:5], s[2:3], 0, v[44:45]
	v_lshlrev_b64 v[46:47], 1, v[170:171]
	v_lshlrev_b64 v[48:49], 1, v[168:169]
	v_lshlrev_b64 v[50:51], 1, v[166:167]
	v_lshlrev_b64 v[52:53], 1, v[164:165]
	global_load_dwordx4 v[26:29], v[2:3], off offset:3760
	global_load_dwordx4 v[30:33], v[4:5], off offset:3760
	v_lshl_add_u64 v[2:3], s[0:1], 0, v[46:47]
	v_lshl_add_u64 v[4:5], s[0:1], 0, v[48:49]
	v_lshl_add_u64 v[6:7], s[0:1], 0, v[50:51]
	v_lshl_add_u64 v[10:11], s[0:1], 0, v[52:53]
	global_load_dwordx4 v[14:17], v[2:3], off offset:128
	s_nop 0
	global_load_dwordx4 v[2:5], v[4:5], off offset:128
	s_nop 0
	global_load_dwordx4 v[6:9], v[6:7], off offset:128
	s_nop 0
	global_load_dwordx4 v[10:13], v[10:11], off offset:128
	v_bfe_u32 v37, v34, 4, 2
	v_lshrrev_b32_e32 v54, 1, v34
	v_bitop3_b32 v54, v54, v37, 7 bitop3:0x6c
	s_lshr_b32 s7, s13, 2
	s_lshl_b32 s6, s12, 8
	s_and_b32 s12, s10, 0x60
	v_readlane_b32 s20, v252, 25
	v_lshlrev_b32_e32 v169, 3, v54
	v_lshlrev_b32_e32 v54, 5, v34
	s_and_b32 s7, s7, 3
	s_or_b32 s12, s20, s12
	s_and_b32 s20, s9, 3
	v_bfe_u32 v55, v34, 1, 3
	v_and_b32_e32 v54, 0xffffe000, v54
	v_lshlrev_b32_e32 v34, 6, v34
	s_movk_i32 s0, 0x3c0
	s_lshl_b32 s7, s7, 19
	s_add_i32 s12, s12, s20
	v_and_or_b32 v54, v34, s0, v54
	v_readlane_b32 s0, v254, 24
	s_add_u32 s0, s0, s7
	v_readlane_b32 s1, v254, 25
	s_addc_u32 s1, s1, 0
	s_mul_i32 s12, s12, 0x2a3000
	v_lshl_add_u64 v[178:179], s[0:1], 0, v[52:53]
	v_lshl_add_u64 v[180:181], s[0:1], 0, v[50:51]
	v_lshl_add_u64 v[182:183], s[0:1], 0, v[48:49]
	v_lshl_add_u64 v[184:185], s[0:1], 0, v[46:47]
	v_readlane_b32 s0, v254, 26
	v_and_b32_e32 v56, 0x33c0, v34
	v_bitop3_b32 v34, v37, v55, 4 bitop3:0x36
	s_add_u32 s0, s0, s12
	v_readlane_b32 s1, v254, 27
	v_lshlrev_b32_e32 v205, 3, v34
	v_lshlrev_b32_e32 v165, 1, v36
	v_lshlrev_b32_e32 v167, 1, v35
	s_addc_u32 s1, s1, 0
	v_mov_b32_e32 v34, 0
	v_add3_u32 v163, 0, v165, v167
	v_lshl_add_u64 v[186:187], s[0:1], 0, v[44:45]
	v_lshl_add_u64 v[188:189], s[0:1], 0, v[42:43]
	v_lshl_add_u64 v[190:191], s[0:1], 0, v[40:41]
	v_lshl_add_u64 v[192:193], s[0:1], 0, v[38:39]
	s_mov_b64 s[0:1], 0
	s_mov_b32 s2, 0
	v_lshlrev_b32_e32 v195, 1, v54
	v_lshlrev_b32_e32 v194, 1, v56
	v_mov_b32_e32 v35, v34
	v_mov_b64_e32 v[36:37], v[34:35]
	v_mov_b64_e32 v[38:39], v[34:35]
	v_mov_b64_e32 v[40:41], v[34:35]
	v_mov_b64_e32 v[42:43], v[34:35]
	v_mov_b64_e32 v[44:45], v[34:35]
	v_mov_b64_e32 v[46:47], v[34:35]
	v_mov_b64_e32 v[48:49], v[34:35]
	v_mov_b64_e32 v[50:51], v[34:35]
	v_mov_b64_e32 v[52:53], v[34:35]
	v_mov_b64_e32 v[54:55], v[34:35]
	v_mov_b64_e32 v[56:57], v[34:35]
	v_mov_b64_e32 v[58:59], v[34:35]
	v_mov_b64_e32 v[60:61], v[34:35]
	v_mov_b64_e32 v[62:63], v[34:35]
	v_mov_b64_e32 v[64:65], v[34:35]
	v_mov_b64_e32 v[66:67], v[34:35]
	v_mov_b64_e32 v[68:69], v[34:35]
	v_mov_b64_e32 v[70:71], v[34:35]
	v_mov_b64_e32 v[72:73], v[34:35]
	v_mov_b64_e32 v[74:75], v[34:35]
	v_mov_b64_e32 v[76:77], v[34:35]
	v_mov_b64_e32 v[78:79], v[34:35]
	v_mov_b64_e32 v[80:81], v[34:35]
	v_mov_b64_e32 v[82:83], v[34:35]
	v_mov_b64_e32 v[84:85], v[34:35]
	v_mov_b64_e32 v[86:87], v[34:35]
	v_mov_b64_e32 v[88:89], v[34:35]
	v_mov_b64_e32 v[90:91], v[34:35]
	v_mov_b64_e32 v[92:93], v[34:35]
	v_mov_b64_e32 v[94:95], v[34:35]
	v_mov_b64_e32 v[96:97], v[34:35]
	v_mov_b64_e32 v[98:99], v[34:35]
	v_mov_b64_e32 v[100:101], v[34:35]
	v_mov_b64_e32 v[102:103], v[34:35]
	v_mov_b64_e32 v[104:105], v[34:35]
	v_mov_b64_e32 v[106:107], v[34:35]
	v_mov_b64_e32 v[108:109], v[34:35]
	v_mov_b64_e32 v[110:111], v[34:35]
	v_mov_b64_e32 v[112:113], v[34:35]
	v_mov_b64_e32 v[114:115], v[34:35]
	v_mov_b64_e32 v[116:117], v[34:35]
	v_mov_b64_e32 v[118:119], v[34:35]
	v_mov_b64_e32 v[120:121], v[34:35]
	v_mov_b64_e32 v[122:123], v[34:35]
	v_mov_b64_e32 v[124:125], v[34:35]
	v_mov_b64_e32 v[126:127], v[34:35]
	v_mov_b64_e32 v[128:129], v[34:35]
	v_mov_b64_e32 v[130:131], v[34:35]
	v_mov_b64_e32 v[132:133], v[34:35]
	v_mov_b64_e32 v[134:135], v[34:35]
	v_mov_b64_e32 v[136:137], v[34:35]
	v_mov_b64_e32 v[138:139], v[34:35]
	v_mov_b64_e32 v[140:141], v[34:35]
	v_mov_b64_e32 v[142:143], v[34:35]
	v_mov_b64_e32 v[144:145], v[34:35]
	v_mov_b64_e32 v[146:147], v[34:35]
	v_mov_b64_e32 v[148:149], v[34:35]
	v_mov_b64_e32 v[150:151], v[34:35]
	v_mov_b64_e32 v[152:153], v[34:35]
	v_mov_b64_e32 v[154:155], v[34:35]
	v_mov_b64_e32 v[156:157], v[34:35]
	v_mov_b64_e32 v[158:159], v[34:35]
	v_mov_b64_e32 v[160:161], v[34:35]
	v_readfirstlane_b32 s52, v192
	v_readfirstlane_b32 s53, v193
	s_sub_u32 s52, s52, 0x40000000
	s_subb_u32 s53, s53, 0
	v_readfirstlane_b32 s56, v184
	v_readfirstlane_b32 s57, v185
	s_sub_u32 s56, s56, 0x40000000
	s_subb_u32 s57, s57, 0
	v_subrev_u32_e32 v193, s52, v192
	v_subrev_u32_e32 v191, s52, v190
	v_subrev_u32_e32 v189, s52, v188
	v_subrev_u32_e32 v187, s52, v186
	v_subrev_u32_e32 v185, s56, v184
	v_subrev_u32_e32 v183, s56, v182
	v_subrev_u32_e32 v181, s56, v180
	v_subrev_u32_e32 v179, s56, v178
	v_lshl_add_u32 v177, v169, 1, v195
	v_lshl_add_u32 v178, v169, 1, v194
	v_lshl_add_u32 v180, v205, 1, v195
	v_lshl_add_u32 v182, v205, 1, v194
; DI void gemm8_accum(f32x4 (&acc)[8][4], const bf16_t* a, size_t lda, const bf16_t* b, size_t ldb, int nkb, bf16_t* L,
;                     const bool pre, const bf16_t* an, size_t ldan, const bf16_t* bn, size_t ldbn) {
;     ...
;   for (int kb = 0; kb + 2 < nkb; ++kb) {
;     __syncthreads();
;     g8_store1(L + ((kb + 1) & 1) * 32768, ra, lrow, lch);
;     g8_load1o(ra, a + (kb + 2) * 64, offa);
;     __builtin_amdgcn_sched_barrier(0);
;     g8_compute<0, 1>(acc, L + (kb & 1) * 32768, wm, wn, lane);
;     __builtin_amdgcn_sched_barrier(0);
;     g8_store1(L + ((kb + 1) & 1) * 32768 + 16384, rb, lrow, lch);
;     g8_load1o(rb, b + (kb + 2) * 64, offb);
;     __builtin_amdgcn_sched_barrier(0);
;     g8_compute<1, 2>(acc, L + (kb & 1) * 32768, wm, wn, lane);
.LBB0_830:
	s_xor_b32 s7, s2, 0x10000
	v_add_u32_e32 v171, s7, v163
	s_waitcnt lgkmcnt(0)
	s_barrier
	s_cmp_eq_u32 s100, 0
	s_cbranch_scc1 .Lstg_830_a
	v_mfma_f32_16x16x32_bf16 v[158:161], v[234:237], v[198:201], v[158:161]
	v_mfma_f32_16x16x32_bf16 v[154:157], v[238:241], v[198:201], v[154:157]
	v_mfma_f32_16x16x32_bf16 v[150:153], v[242:245], v[198:201], v[150:153]
	v_mfma_f32_16x16x32_bf16 v[146:149], v[246:249], v[198:201], v[146:149]
	v_mfma_f32_16x16x32_bf16 v[142:145], v[234:237], v[206:209], v[142:145]
	v_mfma_f32_16x16x32_bf16 v[138:141], v[238:241], v[206:209], v[138:141]
	v_mfma_f32_16x16x32_bf16 v[134:137], v[242:245], v[206:209], v[134:137]
	v_mfma_f32_16x16x32_bf16 v[130:133], v[246:249], v[206:209], v[130:133]
	v_mfma_f32_16x16x32_bf16 v[126:129], v[234:237], v[210:213], v[126:129]
	v_mfma_f32_16x16x32_bf16 v[122:125], v[238:241], v[210:213], v[122:125]
	v_mfma_f32_16x16x32_bf16 v[118:121], v[242:245], v[210:213], v[118:121]
	v_mfma_f32_16x16x32_bf16 v[114:117], v[246:249], v[210:213], v[114:117]
	v_mfma_f32_16x16x32_bf16 v[110:113], v[234:237], v[214:217], v[110:113]
	v_mfma_f32_16x16x32_bf16 v[106:109], v[238:241], v[214:217], v[106:109]
	v_mfma_f32_16x16x32_bf16 v[102:105], v[242:245], v[214:217], v[102:105]
	v_mfma_f32_16x16x32_bf16 v[98:101], v[246:249], v[214:217], v[98:101]
	v_mfma_f32_16x16x32_bf16 v[94:97], v[234:237], v[218:221], v[94:97]
	v_mfma_f32_16x16x32_bf16 v[90:93], v[238:241], v[218:221], v[90:93]
	v_mfma_f32_16x16x32_bf16 v[86:89], v[242:245], v[218:221], v[86:89]
	v_mfma_f32_16x16x32_bf16 v[82:85], v[246:249], v[218:221], v[82:85]
	v_mfma_f32_16x16x32_bf16 v[78:81], v[234:237], v[222:225], v[78:81]
	v_mfma_f32_16x16x32_bf16 v[74:77], v[238:241], v[222:225], v[74:77]
	v_mfma_f32_16x16x32_bf16 v[70:73], v[242:245], v[222:225], v[70:73]
	v_mfma_f32_16x16x32_bf16 v[66:69], v[246:249], v[222:225], v[66:69]
	v_mfma_f32_16x16x32_bf16 v[62:65], v[234:237], v[226:229], v[62:65]
	v_mfma_f32_16x16x32_bf16 v[58:61], v[238:241], v[226:229], v[58:61]
	v_mfma_f32_16x16x32_bf16 v[54:57], v[242:245], v[226:229], v[54:57]
	v_mfma_f32_16x16x32_bf16 v[50:53], v[246:249], v[226:229], v[50:53]
	v_mfma_f32_16x16x32_bf16 v[46:49], v[234:237], v[230:233], v[46:49]
	v_mfma_f32_16x16x32_bf16 v[42:45], v[238:241], v[230:233], v[42:45]
	v_mfma_f32_16x16x32_bf16 v[38:41], v[242:245], v[230:233], v[38:41]
	v_mfma_f32_16x16x32_bf16 v[34:37], v[246:249], v[230:233], v[34:37]
.Lstg_830_a:
	s_waitcnt vmcnt(4)
	ds_write_b128 v171, v[18:21]
	ds_write_b128 v171, v[22:25] offset:8192
	ds_write_b128 v171, v[26:29] offset:16384
	ds_write_b128 v171, v[30:33] offset:24576
	s_add_u32 s54, s52, s0
	s_addc_u32 s55, s53, s1
	global_load_dwordx4 v[18:21], v193, s[54:55]
	global_load_dwordx4 v[22:25], v191, s[54:55]
	global_load_dwordx4 v[26:29], v189, s[54:55]
	global_load_dwordx4 v[30:33], v187, s[54:55]
	v_add_u32_e32 v175, s2, v177
	ds_read_b128 v[198:201], v175
	ds_read_b128 v[206:209], v175 offset:2048
	ds_read_b128 v[210:213], v175 offset:4096
	ds_read_b128 v[214:217], v175 offset:6144
	ds_read_b128 v[218:221], v175 offset:8192
	ds_read_b128 v[222:225], v175 offset:10240
	ds_read_b128 v[226:229], v175 offset:12288
	ds_read_b128 v[230:233], v175 offset:14336
	v_add_u32_e32 v173, s2, v178
	ds_read_b128 v[234:237], v173 offset:32768
	ds_read_b128 v[238:241], v173 offset:34816
	ds_read_b128 v[242:245], v173 offset:36864
	ds_read_b128 v[246:249], v173 offset:38912
	s_waitcnt lgkmcnt(3)
	v_mfma_f32_16x16x32_bf16 v[158:161], v[234:237], v[198:201], v[158:161]
	s_waitcnt lgkmcnt(2)
	v_mfma_f32_16x16x32_bf16 v[154:157], v[238:241], v[198:201], v[154:157]
	s_waitcnt lgkmcnt(1)
	v_mfma_f32_16x16x32_bf16 v[150:153], v[242:245], v[198:201], v[150:153]
	s_waitcnt lgkmcnt(0)
	v_mfma_f32_16x16x32_bf16 v[146:149], v[246:249], v[198:201], v[146:149]
	v_mfma_f32_16x16x32_bf16 v[142:145], v[234:237], v[206:209], v[142:145]
	v_mfma_f32_16x16x32_bf16 v[138:141], v[238:241], v[206:209], v[138:141]
	v_mfma_f32_16x16x32_bf16 v[134:137], v[242:245], v[206:209], v[134:137]
	v_mfma_f32_16x16x32_bf16 v[130:133], v[246:249], v[206:209], v[130:133]
	v_mfma_f32_16x16x32_bf16 v[126:129], v[234:237], v[210:213], v[126:129]
	v_mfma_f32_16x16x32_bf16 v[122:125], v[238:241], v[210:213], v[122:125]
	v_mfma_f32_16x16x32_bf16 v[118:121], v[242:245], v[210:213], v[118:121]
	v_mfma_f32_16x16x32_bf16 v[114:117], v[246:249], v[210:213], v[114:117]
	v_mfma_f32_16x16x32_bf16 v[110:113], v[234:237], v[214:217], v[110:113]
	v_mfma_f32_16x16x32_bf16 v[106:109], v[238:241], v[214:217], v[106:109]
	v_mfma_f32_16x16x32_bf16 v[102:105], v[242:245], v[214:217], v[102:105]
	v_mfma_f32_16x16x32_bf16 v[98:101], v[246:249], v[214:217], v[98:101]
	v_mfma_f32_16x16x32_bf16 v[94:97], v[234:237], v[218:221], v[94:97]
	v_mfma_f32_16x16x32_bf16 v[90:93], v[238:241], v[218:221], v[90:93]
	v_mfma_f32_16x16x32_bf16 v[86:89], v[242:245], v[218:221], v[86:89]
	v_mfma_f32_16x16x32_bf16 v[82:85], v[246:249], v[218:221], v[82:85]
	v_mfma_f32_16x16x32_bf16 v[78:81], v[234:237], v[222:225], v[78:81]
	v_mfma_f32_16x16x32_bf16 v[74:77], v[238:241], v[222:225], v[74:77]
	v_mfma_f32_16x16x32_bf16 v[70:73], v[242:245], v[222:225], v[70:73]
	v_mfma_f32_16x16x32_bf16 v[66:69], v[246:249], v[222:225], v[66:69]
	v_mfma_f32_16x16x32_bf16 v[62:65], v[234:237], v[226:229], v[62:65]
	v_mfma_f32_16x16x32_bf16 v[58:61], v[238:241], v[226:229], v[58:61]
	v_mfma_f32_16x16x32_bf16 v[54:57], v[242:245], v[226:229], v[54:57]
	v_mfma_f32_16x16x32_bf16 v[50:53], v[246:249], v[226:229], v[50:53]
	v_mfma_f32_16x16x32_bf16 v[46:49], v[234:237], v[230:233], v[46:49]
	v_mfma_f32_16x16x32_bf16 v[42:45], v[238:241], v[230:233], v[42:45]
	v_mfma_f32_16x16x32_bf16 v[38:41], v[242:245], v[230:233], v[38:41]
	v_mfma_f32_16x16x32_bf16 v[34:37], v[246:249], v[230:233], v[34:37]
	s_waitcnt vmcnt(4)
	ds_write_b128 v171, v[14:17] offset:32768
	ds_write_b128 v171, v[2:5] offset:40960
	ds_write_b128 v171, v[6:9] offset:49152
	ds_write_b128 v171, v[10:13] offset:57344
	s_add_u32 s58, s56, s0
	s_addc_u32 s59, s57, s1
	global_load_dwordx4 v[14:17], v185, s[58:59]
	global_load_dwordx4 v[2:5], v183, s[58:59]
	global_load_dwordx4 v[6:9], v181, s[58:59]
	global_load_dwordx4 v[10:13], v179, s[58:59]
	v_add_u32_e32 v173, s2, v180
	ds_read_b128 v[198:201], v173
	ds_read_b128 v[206:209], v173 offset:2048
	ds_read_b128 v[210:213], v173 offset:4096
	ds_read_b128 v[214:217], v173 offset:6144
	ds_read_b128 v[218:221], v173 offset:8192
	ds_read_b128 v[222:225], v173 offset:10240
	ds_read_b128 v[226:229], v173 offset:12288
	ds_read_b128 v[230:233], v173 offset:14336
	v_add_u32_e32 v171, s2, v182
	ds_read_b128 v[234:237], v171 offset:32768
	ds_read_b128 v[238:241], v171 offset:34816
	ds_read_b128 v[242:245], v171 offset:36864
	ds_read_b128 v[246:249], v171 offset:38912
	s_cmp_lg_u32 s101, 0
	s_cbranch_scc1 .Lstg_830_b
; DI void gemm8_accum(f32x4 (&acc)[8][4], const bf16_t* a, size_t lda, const bf16_t* b, size_t ldb, int nkb, bf16_t* L,
;                     const bool pre, const bf16_t* an, size_t ldan, const bf16_t* bn, size_t ldbn) {
;     ...
;     g8_compute<0, 1>(acc, L + (kb & 1) * 32768, wm, wn, lane);
;     __builtin_amdgcn_sched_barrier(0);
;     g8_store1(L + ((kb + 1) & 1) * 32768 + 16384, rb, lrow, lch);
;     g8_load1o(rb, b + (kb + 2) * 64, offb);
;     __builtin_amdgcn_sched_barrier(0);
;     g8_compute<1, 2>(acc, L + (kb & 1) * 32768, wm, wn, lane);
;   }
;   __syncthreads();
;   g8_store1(L + 32768, ra, lrow, lch);
;   g8_load1(ra, an, ldan, 0, lrow, lch);
;   __builtin_amdgcn_sched_barrier(0);
;   g8_compute<0, 1>(acc, L, wm, wn, lane);
	s_waitcnt lgkmcnt(3)
	v_mfma_f32_16x16x32_bf16 v[158:161], v[234:237], v[198:201], v[158:161]
	s_waitcnt lgkmcnt(2)
	v_mfma_f32_16x16x32_bf16 v[154:157], v[238:241], v[198:201], v[154:157]
	s_waitcnt lgkmcnt(1)
	v_mfma_f32_16x16x32_bf16 v[150:153], v[242:245], v[198:201], v[150:153]
	s_waitcnt lgkmcnt(0)
	v_mfma_f32_16x16x32_bf16 v[146:149], v[246:249], v[198:201], v[146:149]
	v_mfma_f32_16x16x32_bf16 v[142:145], v[234:237], v[206:209], v[142:145]
	v_mfma_f32_16x16x32_bf16 v[138:141], v[238:241], v[206:209], v[138:141]
	v_mfma_f32_16x16x32_bf16 v[134:137], v[242:245], v[206:209], v[134:137]
	v_mfma_f32_16x16x32_bf16 v[130:133], v[246:249], v[206:209], v[130:133]
	v_mfma_f32_16x16x32_bf16 v[126:129], v[234:237], v[210:213], v[126:129]
	v_mfma_f32_16x16x32_bf16 v[122:125], v[238:241], v[210:213], v[122:125]
	v_mfma_f32_16x16x32_bf16 v[118:121], v[242:245], v[210:213], v[118:121]
	v_mfma_f32_16x16x32_bf16 v[114:117], v[246:249], v[210:213], v[114:117]
	v_mfma_f32_16x16x32_bf16 v[110:113], v[234:237], v[214:217], v[110:113]
	v_mfma_f32_16x16x32_bf16 v[106:109], v[238:241], v[214:217], v[106:109]
	v_mfma_f32_16x16x32_bf16 v[102:105], v[242:245], v[214:217], v[102:105]
	v_mfma_f32_16x16x32_bf16 v[98:101], v[246:249], v[214:217], v[98:101]
	v_mfma_f32_16x16x32_bf16 v[94:97], v[234:237], v[218:221], v[94:97]
	v_mfma_f32_16x16x32_bf16 v[90:93], v[238:241], v[218:221], v[90:93]
	v_mfma_f32_16x16x32_bf16 v[86:89], v[242:245], v[218:221], v[86:89]
	v_mfma_f32_16x16x32_bf16 v[82:85], v[246:249], v[218:221], v[82:85]
	v_mfma_f32_16x16x32_bf16 v[78:81], v[234:237], v[222:225], v[78:81]
	v_mfma_f32_16x16x32_bf16 v[74:77], v[238:241], v[222:225], v[74:77]
	v_mfma_f32_16x16x32_bf16 v[70:73], v[242:245], v[222:225], v[70:73]
	v_mfma_f32_16x16x32_bf16 v[66:69], v[246:249], v[222:225], v[66:69]
	v_mfma_f32_16x16x32_bf16 v[62:65], v[234:237], v[226:229], v[62:65]
	v_mfma_f32_16x16x32_bf16 v[58:61], v[238:241], v[226:229], v[58:61]
	v_mfma_f32_16x16x32_bf16 v[54:57], v[242:245], v[226:229], v[54:57]
	v_mfma_f32_16x16x32_bf16 v[50:53], v[246:249], v[226:229], v[50:53]
	v_mfma_f32_16x16x32_bf16 v[46:49], v[234:237], v[230:233], v[46:49]
	v_mfma_f32_16x16x32_bf16 v[42:45], v[238:241], v[230:233], v[42:45]
	v_mfma_f32_16x16x32_bf16 v[38:41], v[242:245], v[230:233], v[38:41]
	v_mfma_f32_16x16x32_bf16 v[34:37], v[246:249], v[230:233], v[34:37]
.Lstg_830_b:
	s_mov_b32 s100, s101
	s_xor_b32 s2, s2, 0x10000
	s_add_u32 s0, s0, 0x80
	s_addc_u32 s1, s1, 0
	s_cmpk_lg_i32 s0, 0x700
	s_cbranch_scc1 .LBB0_830
	s_cmp_eq_u32 s100, 0
	s_cbranch_scc1 .Lstg_830_c
	s_waitcnt lgkmcnt(0)
	v_mfma_f32_16x16x32_bf16 v[158:161], v[234:237], v[198:201], v[158:161]
	v_mfma_f32_16x16x32_bf16 v[154:157], v[238:241], v[198:201], v[154:157]
	v_mfma_f32_16x16x32_bf16 v[150:153], v[242:245], v[198:201], v[150:153]
	v_mfma_f32_16x16x32_bf16 v[146:149], v[246:249], v[198:201], v[146:149]
	v_mfma_f32_16x16x32_bf16 v[142:145], v[234:237], v[206:209], v[142:145]
	v_mfma_f32_16x16x32_bf16 v[138:141], v[238:241], v[206:209], v[138:141]
	v_mfma_f32_16x16x32_bf16 v[134:137], v[242:245], v[206:209], v[134:137]
	v_mfma_f32_16x16x32_bf16 v[130:133], v[246:249], v[206:209], v[130:133]
	v_mfma_f32_16x16x32_bf16 v[126:129], v[234:237], v[210:213], v[126:129]
	v_mfma_f32_16x16x32_bf16 v[122:125], v[238:241], v[210:213], v[122:125]
	v_mfma_f32_16x16x32_bf16 v[118:121], v[242:245], v[210:213], v[118:121]
	v_mfma_f32_16x16x32_bf16 v[114:117], v[246:249], v[210:213], v[114:117]
	v_mfma_f32_16x16x32_bf16 v[110:113], v[234:237], v[214:217], v[110:113]
	v_mfma_f32_16x16x32_bf16 v[106:109], v[238:241], v[214:217], v[106:109]
	v_mfma_f32_16x16x32_bf16 v[102:105], v[242:245], v[214:217], v[102:105]
	v_mfma_f32_16x16x32_bf16 v[98:101], v[246:249], v[214:217], v[98:101]
	v_mfma_f32_16x16x32_bf16 v[94:97], v[234:237], v[218:221], v[94:97]
	v_mfma_f32_16x16x32_bf16 v[90:93], v[238:241], v[218:221], v[90:93]
	v_mfma_f32_16x16x32_bf16 v[86:89], v[242:245], v[218:221], v[86:89]
	v_mfma_f32_16x16x32_bf16 v[82:85], v[246:249], v[218:221], v[82:85]
	v_mfma_f32_16x16x32_bf16 v[78:81], v[234:237], v[222:225], v[78:81]
	v_mfma_f32_16x16x32_bf16 v[74:77], v[238:241], v[222:225], v[74:77]
	v_mfma_f32_16x16x32_bf16 v[70:73], v[242:245], v[222:225], v[70:73]
	v_mfma_f32_16x16x32_bf16 v[66:69], v[246:249], v[222:225], v[66:69]
	v_mfma_f32_16x16x32_bf16 v[62:65], v[234:237], v[226:229], v[62:65]
	v_mfma_f32_16x16x32_bf16 v[58:61], v[238:241], v[226:229], v[58:61]
	v_mfma_f32_16x16x32_bf16 v[54:57], v[242:245], v[226:229], v[54:57]
	v_mfma_f32_16x16x32_bf16 v[50:53], v[246:249], v[226:229], v[50:53]
	v_mfma_f32_16x16x32_bf16 v[46:49], v[234:237], v[230:233], v[46:49]
	v_mfma_f32_16x16x32_bf16 v[42:45], v[238:241], v[230:233], v[42:45]
	v_mfma_f32_16x16x32_bf16 v[38:41], v[242:245], v[230:233], v[38:41]
	v_mfma_f32_16x16x32_bf16 v[34:37], v[246:249], v[230:233], v[34:37]
	s_mov_b32 s100, 0

; DI int TID8() { int t = threadIdx.x; asm volatile("" : "+v"(t)); return t; }
; DI void gemm8_accum(f32x4 (&acc)[8][4], const bf16_t* a, size_t lda, const bf16_t* b, size_t ldb, int nkb, bf16_t* L,
;                     const bool pre, const bf16_t* an, size_t ldan, const bf16_t* bn, size_t ldbn) {
;   const int tid = TID8(), lane = tid & 63, w = tid >> 6;
;   const int wm = w >> 2, wn = w & 3;
;   const int lrow = tid >> 3, lch = tid & 7;
;   u32x4 ra[4], rb[4];
;   unsigned offa[4], offb[4];
; #pragma unroll
;   for (int i = 0; i < 4; ++i) {
;     offa[i] = (unsigned)(lrow + 64 * i) * (unsigned)lda + (unsigned)(lch * 8);
;     offb[i] = (unsigned)(lrow + 64 * i) * (unsigned)ldb + (unsigned)(lch * 8);
;   }
;   if (!pre) {
;     g8_load1o(ra, a, offa);
;     g8_load1o(rb, b, offb);
;     __syncthreads();
;     g8_store(L, ra, rb, lrow, lch);
;   }
;   g8_load1o(ra, a + 64, offa);
;   g8_load1o(rb, b + 64, offb);
; __global__ void __launch_bounds__(512, 2) mega(Params p) {
;     ...
;       gemm8_accum(acc8, hbuf + (size_t)m0 * DM, DM, wl + W_FF1 + (size_t)n0 * 1024, 1024, 16, lds_all, !first_,
;                   hbuf + (size_t)mtn * 256 * DM, DM, wl + W_FF1 + (size_t)ntilen * 256 * 1024, 1024);
.LBB0_891:
	v_lshlrev_b64 v[40:41], 1, v[168:169]
	v_lshl_add_u64 v[6:7], s[2:3], 0, v[40:41]
	v_lshlrev_b64 v[42:43], 1, v[166:167]
	v_lshlrev_b64 v[44:45], 1, v[0:1]
	v_lshl_add_u64 v[8:9], s[2:3], 0, v[42:43]
	global_load_dwordx4 v[18:21], v[6:7], off offset:128
	global_load_dwordx4 v[26:29], v[8:9], off offset:128
	v_lshl_add_u64 v[6:7], s[2:3], 0, v[44:45]
	global_load_dwordx4 v[22:25], v[4:5], off offset:128
	global_load_dwordx4 v[30:33], v[6:7], off offset:128
	global_load_dwordx4 v[14:17], v[2:3], off offset:128
	v_lshl_add_u64 v[2:3], s[0:1], 0, v[40:41]
	s_nop 1
	global_load_dwordx4 v[2:5], v[2:3], off offset:128
	v_lshl_add_u64 v[6:7], s[0:1], 0, v[42:43]
	v_lshl_add_u64 v[10:11], s[0:1], 0, v[44:45]
	global_load_dwordx4 v[6:9], v[6:7], off offset:128
	s_nop 0
	global_load_dwordx4 v[10:13], v[10:11], off offset:128
	v_bfe_u32 v39, v36, 4, 2
	v_lshrrev_b32_e32 v46, 1, v36
	v_readlane_b32 s7, v252, 25
	v_bitop3_b32 v46, v46, v39, 7 bitop3:0x6c
	s_or_b32 s7, s7, s12
	s_and_b32 s12, s9, 3
	v_lshlrev_b32_e32 v191, 3, v46
	v_lshlrev_b32_e32 v46, 5, v36
	s_lshl_b32 s6, s10, 11
	s_add_i32 s7, s7, s12
	v_bfe_u32 v47, v36, 1, 3
	v_and_b32_e32 v46, 0xffffe000, v46
	v_lshlrev_b32_e32 v36, 6, v36
	s_movk_i32 s0, 0x3c0
	s_and_b32 s6, s6, 0x780000
	s_lshl_b32 s7, s7, 19
	v_and_or_b32 v46, v36, s0, v46
	v_readlane_b32 s0, v254, 28
	s_add_u32 s0, s0, s6
	v_readlane_b32 s1, v254, 29
	v_add_u32_e32 v34, v35, v34
	v_mov_b32_e32 v35, v1
	s_addc_u32 s1, s1, 0
	v_lshlrev_b64 v[34:35], 1, v[34:35]
	v_lshl_add_u64 v[170:171], s[0:1], 0, v[44:45]
	v_lshl_add_u64 v[172:173], s[0:1], 0, v[42:43]
	v_lshl_add_u64 v[174:175], s[0:1], 0, v[40:41]
	v_lshl_add_u64 v[176:177], s[0:1], 0, v[34:35]
	v_readlane_b32 s0, v253, 57
	s_add_u32 s0, s0, s7
	v_readlane_b32 s1, v253, 58
	s_addc_u32 s1, s1, 0
	v_and_b32_e32 v36, 0x33c0, v36
	v_bitop3_b32 v39, v39, v47, 4 bitop3:0x36
	v_lshlrev_b32_e32 v189, 1, v38
	v_lshlrev_b32_e32 v190, 1, v37
	v_lshl_add_u64 v[184:185], s[0:1], 0, v[34:35]
	v_mov_b32_e32 v34, 0
	v_lshlrev_b32_e32 v188, 3, v39
	v_add3_u32 v163, 0, v189, v190
	v_lshl_add_u64 v[178:179], s[0:1], 0, v[44:45]
	v_lshl_add_u64 v[180:181], s[0:1], 0, v[42:43]
	v_lshl_add_u64 v[182:183], s[0:1], 0, v[40:41]
	s_mov_b64 s[0:1], 0
	s_mov_b32 s2, 0
	v_lshlrev_b32_e32 v187, 1, v46
	v_lshlrev_b32_e32 v186, 1, v36
	v_mov_b32_e32 v35, v34
	v_mov_b64_e32 v[36:37], v[34:35]
	v_mov_b64_e32 v[38:39], v[34:35]
	v_mov_b64_e32 v[40:41], v[34:35]
	v_mov_b64_e32 v[42:43], v[34:35]
	v_mov_b64_e32 v[44:45], v[34:35]
	v_mov_b64_e32 v[46:47], v[34:35]
	v_mov_b64_e32 v[48:49], v[34:35]
	v_mov_b64_e32 v[50:51], v[34:35]
	v_mov_b64_e32 v[52:53], v[34:35]
	v_mov_b64_e32 v[54:55], v[34:35]
	v_mov_b64_e32 v[56:57], v[34:35]
	v_mov_b64_e32 v[58:59], v[34:35]
	v_mov_b64_e32 v[60:61], v[34:35]
	v_mov_b64_e32 v[62:63], v[34:35]
	v_mov_b64_e32 v[64:65], v[34:35]
	v_mov_b64_e32 v[66:67], v[34:35]
	v_mov_b64_e32 v[68:69], v[34:35]
	v_mov_b64_e32 v[70:71], v[34:35]
	v_mov_b64_e32 v[72:73], v[34:35]
	v_mov_b64_e32 v[74:75], v[34:35]
	v_mov_b64_e32 v[76:77], v[34:35]
	v_mov_b64_e32 v[78:79], v[34:35]
	v_mov_b64_e32 v[80:81], v[34:35]
	v_mov_b64_e32 v[82:83], v[34:35]
	v_mov_b64_e32 v[84:85], v[34:35]
	v_mov_b64_e32 v[86:87], v[34:35]
	v_mov_b64_e32 v[88:89], v[34:35]
	v_mov_b64_e32 v[90:91], v[34:35]
	v_mov_b64_e32 v[92:93], v[34:35]
	v_mov_b64_e32 v[94:95], v[34:35]
	v_mov_b64_e32 v[96:97], v[34:35]
	v_mov_b64_e32 v[98:99], v[34:35]
	v_mov_b64_e32 v[100:101], v[34:35]
	v_mov_b64_e32 v[102:103], v[34:35]
	v_mov_b64_e32 v[104:105], v[34:35]
	v_mov_b64_e32 v[106:107], v[34:35]
	v_mov_b64_e32 v[108:109], v[34:35]
	v_mov_b64_e32 v[110:111], v[34:35]
	v_mov_b64_e32 v[112:113], v[34:35]
	v_mov_b64_e32 v[114:115], v[34:35]
	v_mov_b64_e32 v[116:117], v[34:35]
	v_mov_b64_e32 v[118:119], v[34:35]
	v_mov_b64_e32 v[120:121], v[34:35]
	v_mov_b64_e32 v[122:123], v[34:35]
	v_mov_b64_e32 v[124:125], v[34:35]
	v_mov_b64_e32 v[126:127], v[34:35]
	v_mov_b64_e32 v[128:129], v[34:35]
	v_mov_b64_e32 v[130:131], v[34:35]
	v_mov_b64_e32 v[132:133], v[34:35]
	v_mov_b64_e32 v[134:135], v[34:35]
	v_mov_b64_e32 v[136:137], v[34:35]
	v_mov_b64_e32 v[138:139], v[34:35]
	v_mov_b64_e32 v[140:141], v[34:35]
	v_mov_b64_e32 v[142:143], v[34:35]
	v_mov_b64_e32 v[144:145], v[34:35]
	v_mov_b64_e32 v[146:147], v[34:35]
	v_mov_b64_e32 v[148:149], v[34:35]
	v_mov_b64_e32 v[150:151], v[34:35]
	v_mov_b64_e32 v[152:153], v[34:35]
	v_mov_b64_e32 v[154:155], v[34:35]
	v_mov_b64_e32 v[156:157], v[34:35]
	v_mov_b64_e32 v[158:159], v[34:35]
	v_mov_b64_e32 v[160:161], v[34:35]
	v_readfirstlane_b32 s52, v184
	v_readfirstlane_b32 s53, v185
	s_sub_u32 s52, s52, 0x40000000
	s_subb_u32 s53, s53, 0
	v_readfirstlane_b32 s56, v176
	v_readfirstlane_b32 s57, v177
	s_sub_u32 s56, s56, 0x40000000
	s_subb_u32 s57, s57, 0
	v_subrev_u32_e32 v185, s52, v184
	v_subrev_u32_e32 v181, s52, v180
	v_subrev_u32_e32 v179, s52, v178
	v_subrev_u32_e32 v183, s52, v182
	v_subrev_u32_e32 v177, s56, v176
	v_subrev_u32_e32 v175, s56, v174
	v_subrev_u32_e32 v173, s56, v172
	v_subrev_u32_e32 v171, s56, v170
	v_lshl_add_u32 v170, v191, 1, v187
	v_lshl_add_u32 v172, v191, 1, v186
	v_lshl_add_u32 v174, v188, 1, v187
	v_lshl_add_u32 v176, v188, 1, v186
; DI void gemm8_accum(f32x4 (&acc)[8][4], const bf16_t* a, size_t lda, const bf16_t* b, size_t ldb, int nkb, bf16_t* L,
;                     const bool pre, const bf16_t* an, size_t ldan, const bf16_t* bn, size_t ldbn) {
;     ...
;   for (int kb = 0; kb + 2 < nkb; ++kb) {
;     __syncthreads();
;     g8_store1(L + ((kb + 1) & 1) * 32768, ra, lrow, lch);
;     g8_load1o(ra, a + (kb + 2) * 64, offa);
;     __builtin_amdgcn_sched_barrier(0);
;     g8_compute<0, 1>(acc, L + (kb & 1) * 32768, wm, wn, lane);
;     __builtin_amdgcn_sched_barrier(0);
;     g8_store1(L + ((kb + 1) & 1) * 32768 + 16384, rb, lrow, lch);
;     g8_load1o(rb, b + (kb + 2) * 64, offb);
;     __builtin_amdgcn_sched_barrier(0);
;     g8_compute<1, 2>(acc, L + (kb & 1) * 32768, wm, wn, lane);
.LBB0_892:
	s_xor_b32 s6, s2, 0x10000
	v_add_u32_e32 v167, s6, v163
	s_waitcnt lgkmcnt(0)
	s_barrier
	s_cmp_eq_u32 s100, 0
	s_cbranch_scc1 .Lstg_892_a
	v_mfma_f32_16x16x32_bf16 v[158:161], v[230:233], v[192:195], v[158:161]
	v_mfma_f32_16x16x32_bf16 v[154:157], v[234:237], v[192:195], v[154:157]
	v_mfma_f32_16x16x32_bf16 v[150:153], v[238:241], v[192:195], v[150:153]
	v_mfma_f32_16x16x32_bf16 v[146:149], v[242:245], v[192:195], v[146:149]
	v_mfma_f32_16x16x32_bf16 v[142:145], v[230:233], v[198:201], v[142:145]
	v_mfma_f32_16x16x32_bf16 v[138:141], v[234:237], v[198:201], v[138:141]
	v_mfma_f32_16x16x32_bf16 v[134:137], v[238:241], v[198:201], v[134:137]
	v_mfma_f32_16x16x32_bf16 v[130:133], v[242:245], v[198:201], v[130:133]
	v_mfma_f32_16x16x32_bf16 v[126:129], v[230:233], v[206:209], v[126:129]
	v_mfma_f32_16x16x32_bf16 v[122:125], v[234:237], v[206:209], v[122:125]
	v_mfma_f32_16x16x32_bf16 v[118:121], v[238:241], v[206:209], v[118:121]
	v_mfma_f32_16x16x32_bf16 v[114:117], v[242:245], v[206:209], v[114:117]
	v_mfma_f32_16x16x32_bf16 v[110:113], v[230:233], v[210:213], v[110:113]
	v_mfma_f32_16x16x32_bf16 v[106:109], v[234:237], v[210:213], v[106:109]
	v_mfma_f32_16x16x32_bf16 v[102:105], v[238:241], v[210:213], v[102:105]
	v_mfma_f32_16x16x32_bf16 v[98:101], v[242:245], v[210:213], v[98:101]
	v_mfma_f32_16x16x32_bf16 v[94:97], v[230:233], v[214:217], v[94:97]
	v_mfma_f32_16x16x32_bf16 v[90:93], v[234:237], v[214:217], v[90:93]
	v_mfma_f32_16x16x32_bf16 v[86:89], v[238:241], v[214:217], v[86:89]
	v_mfma_f32_16x16x32_bf16 v[82:85], v[242:245], v[214:217], v[82:85]
	v_mfma_f32_16x16x32_bf16 v[78:81], v[230:233], v[218:221], v[78:81]
	v_mfma_f32_16x16x32_bf16 v[74:77], v[234:237], v[218:221], v[74:77]
	v_mfma_f32_16x16x32_bf16 v[70:73], v[238:241], v[218:221], v[70:73]
	v_mfma_f32_16x16x32_bf16 v[66:69], v[242:245], v[218:221], v[66:69]
	v_mfma_f32_16x16x32_bf16 v[62:65], v[230:233], v[222:225], v[62:65]
	v_mfma_f32_16x16x32_bf16 v[58:61], v[234:237], v[222:225], v[58:61]
	v_mfma_f32_16x16x32_bf16 v[54:57], v[238:241], v[222:225], v[54:57]
	v_mfma_f32_16x16x32_bf16 v[50:53], v[242:245], v[222:225], v[50:53]
	v_mfma_f32_16x16x32_bf16 v[46:49], v[230:233], v[226:229], v[46:49]
	v_mfma_f32_16x16x32_bf16 v[42:45], v[234:237], v[226:229], v[42:45]
	v_mfma_f32_16x16x32_bf16 v[38:41], v[238:241], v[226:229], v[38:41]
	v_mfma_f32_16x16x32_bf16 v[34:37], v[242:245], v[226:229], v[34:37]
.Lstg_892_a:
	s_waitcnt vmcnt(4)
	ds_write_b128 v167, v[22:25]
	ds_write_b128 v167, v[18:21] offset:8192
	ds_write_b128 v167, v[26:29] offset:16384
	ds_write_b128 v167, v[30:33] offset:24576
	s_add_u32 s54, s52, s0
	s_addc_u32 s55, s53, s1
	global_load_dwordx4 v[22:25], v185, s[54:55]
	global_load_dwordx4 v[26:29], v181, s[54:55]
	global_load_dwordx4 v[18:21], v183, s[54:55]
	global_load_dwordx4 v[30:33], v179, s[54:55]
	v_add_u32_e32 v202, s2, v170
	ds_read_b128 v[192:195], v202
	ds_read_b128 v[198:201], v202 offset:2048
	ds_read_b128 v[206:209], v202 offset:4096
	ds_read_b128 v[210:213], v202 offset:6144
	ds_read_b128 v[214:217], v202 offset:8192
	ds_read_b128 v[218:221], v202 offset:10240
	ds_read_b128 v[222:225], v202 offset:12288
	ds_read_b128 v[226:229], v202 offset:14336
	v_add_u32_e32 v169, s2, v172
	ds_read_b128 v[230:233], v169 offset:32768
	ds_read_b128 v[234:237], v169 offset:34816
	ds_read_b128 v[238:241], v169 offset:36864
	ds_read_b128 v[242:245], v169 offset:38912
	s_waitcnt lgkmcnt(3)
	v_mfma_f32_16x16x32_bf16 v[158:161], v[230:233], v[192:195], v[158:161]
	s_waitcnt lgkmcnt(2)
	v_mfma_f32_16x16x32_bf16 v[154:157], v[234:237], v[192:195], v[154:157]
	s_waitcnt lgkmcnt(1)
	v_mfma_f32_16x16x32_bf16 v[150:153], v[238:241], v[192:195], v[150:153]
	s_waitcnt lgkmcnt(0)
	v_mfma_f32_16x16x32_bf16 v[146:149], v[242:245], v[192:195], v[146:149]
	v_mfma_f32_16x16x32_bf16 v[142:145], v[230:233], v[198:201], v[142:145]
	v_mfma_f32_16x16x32_bf16 v[138:141], v[234:237], v[198:201], v[138:141]
	v_mfma_f32_16x16x32_bf16 v[134:137], v[238:241], v[198:201], v[134:137]
	v_mfma_f32_16x16x32_bf16 v[130:133], v[242:245], v[198:201], v[130:133]
	v_mfma_f32_16x16x32_bf16 v[126:129], v[230:233], v[206:209], v[126:129]
	v_mfma_f32_16x16x32_bf16 v[122:125], v[234:237], v[206:209], v[122:125]
	v_mfma_f32_16x16x32_bf16 v[118:121], v[238:241], v[206:209], v[118:121]
	v_mfma_f32_16x16x32_bf16 v[114:117], v[242:245], v[206:209], v[114:117]
	v_mfma_f32_16x16x32_bf16 v[110:113], v[230:233], v[210:213], v[110:113]
	v_mfma_f32_16x16x32_bf16 v[106:109], v[234:237], v[210:213], v[106:109]
	v_mfma_f32_16x16x32_bf16 v[102:105], v[238:241], v[210:213], v[102:105]
	v_mfma_f32_16x16x32_bf16 v[98:101], v[242:245], v[210:213], v[98:101]
	v_mfma_f32_16x16x32_bf16 v[94:97], v[230:233], v[214:217], v[94:97]
	v_mfma_f32_16x16x32_bf16 v[90:93], v[234:237], v[214:217], v[90:93]
	v_mfma_f32_16x16x32_bf16 v[86:89], v[238:241], v[214:217], v[86:89]
	v_mfma_f32_16x16x32_bf16 v[82:85], v[242:245], v[214:217], v[82:85]
	v_mfma_f32_16x16x32_bf16 v[78:81], v[230:233], v[218:221], v[78:81]
	v_mfma_f32_16x16x32_bf16 v[74:77], v[234:237], v[218:221], v[74:77]
	v_mfma_f32_16x16x32_bf16 v[70:73], v[238:241], v[218:221], v[70:73]
	v_mfma_f32_16x16x32_bf16 v[66:69], v[242:245], v[218:221], v[66:69]
	v_mfma_f32_16x16x32_bf16 v[62:65], v[230:233], v[222:225], v[62:65]
	v_mfma_f32_16x16x32_bf16 v[58:61], v[234:237], v[222:225], v[58:61]
	v_mfma_f32_16x16x32_bf16 v[54:57], v[238:241], v[222:225], v[54:57]
	v_mfma_f32_16x16x32_bf16 v[50:53], v[242:245], v[222:225], v[50:53]
	v_mfma_f32_16x16x32_bf16 v[46:49], v[230:233], v[226:229], v[46:49]
	v_mfma_f32_16x16x32_bf16 v[42:45], v[234:237], v[226:229], v[42:45]
	v_mfma_f32_16x16x32_bf16 v[38:41], v[238:241], v[226:229], v[38:41]
	v_mfma_f32_16x16x32_bf16 v[34:37], v[242:245], v[226:229], v[34:37]
	s_waitcnt vmcnt(4)
	ds_write_b128 v167, v[14:17] offset:32768
	ds_write_b128 v167, v[2:5] offset:40960
	ds_write_b128 v167, v[6:9] offset:49152
	ds_write_b128 v167, v[10:13] offset:57344
	s_add_u32 s58, s56, s0
	s_addc_u32 s59, s57, s1
	global_load_dwordx4 v[14:17], v177, s[58:59]
	global_load_dwordx4 v[2:5], v175, s[58:59]
	global_load_dwordx4 v[6:9], v173, s[58:59]
	global_load_dwordx4 v[10:13], v171, s[58:59]
	v_add_u32_e32 v169, s2, v174
	ds_read_b128 v[192:195], v169
	ds_read_b128 v[198:201], v169 offset:2048
	ds_read_b128 v[206:209], v169 offset:4096
	ds_read_b128 v[210:213], v169 offset:6144
	ds_read_b128 v[214:217], v169 offset:8192
	ds_read_b128 v[218:221], v169 offset:10240
	ds_read_b128 v[222:225], v169 offset:12288
	ds_read_b128 v[226:229], v169 offset:14336
	v_add_u32_e32 v167, s2, v176
	ds_read_b128 v[230:233], v167 offset:32768
	ds_read_b128 v[234:237], v167 offset:34816
	ds_read_b128 v[238:241], v167 offset:36864
	ds_read_b128 v[242:245], v167 offset:38912
	s_cmp_lg_u32 s101, 0
	s_cbranch_scc1 .Lstg_892_b
; DI void gemm8_accum(f32x4 (&acc)[8][4], const bf16_t* a, size_t lda, const bf16_t* b, size_t ldb, int nkb, bf16_t* L,
;                     const bool pre, const bf16_t* an, size_t ldan, const bf16_t* bn, size_t ldbn) {
;     ...
;     g8_compute<0, 1>(acc, L + (kb & 1) * 32768, wm, wn, lane);
;     __builtin_amdgcn_sched_barrier(0);
;     g8_store1(L + ((kb + 1) & 1) * 32768 + 16384, rb, lrow, lch);
;     g8_load1o(rb, b + (kb + 2) * 64, offb);
;     __builtin_amdgcn_sched_barrier(0);
;     g8_compute<1, 2>(acc, L + (kb & 1) * 32768, wm, wn, lane);
;   }
;   __syncthreads();
;   g8_store1(L + 32768, ra, lrow, lch);
;   g8_load1(ra, an, ldan, 0, lrow, lch);
;   __builtin_amdgcn_sched_barrier(0);
;   g8_compute<0, 1>(acc, L, wm, wn, lane);
	s_waitcnt lgkmcnt(3)
	v_mfma_f32_16x16x32_bf16 v[158:161], v[230:233], v[192:195], v[158:161]
	s_waitcnt lgkmcnt(2)
	v_mfma_f32_16x16x32_bf16 v[154:157], v[234:237], v[192:195], v[154:157]
	s_waitcnt lgkmcnt(1)
	v_mfma_f32_16x16x32_bf16 v[150:153], v[238:241], v[192:195], v[150:153]
	s_waitcnt lgkmcnt(0)
	v_mfma_f32_16x16x32_bf16 v[146:149], v[242:245], v[192:195], v[146:149]
	v_mfma_f32_16x16x32_bf16 v[142:145], v[230:233], v[198:201], v[142:145]
	v_mfma_f32_16x16x32_bf16 v[138:141], v[234:237], v[198:201], v[138:141]
	v_mfma_f32_16x16x32_bf16 v[134:137], v[238:241], v[198:201], v[134:137]
	v_mfma_f32_16x16x32_bf16 v[130:133], v[242:245], v[198:201], v[130:133]
	v_mfma_f32_16x16x32_bf16 v[126:129], v[230:233], v[206:209], v[126:129]
	v_mfma_f32_16x16x32_bf16 v[122:125], v[234:237], v[206:209], v[122:125]
	v_mfma_f32_16x16x32_bf16 v[118:121], v[238:241], v[206:209], v[118:121]
	v_mfma_f32_16x16x32_bf16 v[114:117], v[242:245], v[206:209], v[114:117]
	v_mfma_f32_16x16x32_bf16 v[110:113], v[230:233], v[210:213], v[110:113]
	v_mfma_f32_16x16x32_bf16 v[106:109], v[234:237], v[210:213], v[106:109]
	v_mfma_f32_16x16x32_bf16 v[102:105], v[238:241], v[210:213], v[102:105]
	v_mfma_f32_16x16x32_bf16 v[98:101], v[242:245], v[210:213], v[98:101]
	v_mfma_f32_16x16x32_bf16 v[94:97], v[230:233], v[214:217], v[94:97]
	v_mfma_f32_16x16x32_bf16 v[90:93], v[234:237], v[214:217], v[90:93]
	v_mfma_f32_16x16x32_bf16 v[86:89], v[238:241], v[214:217], v[86:89]
	v_mfma_f32_16x16x32_bf16 v[82:85], v[242:245], v[214:217], v[82:85]
	v_mfma_f32_16x16x32_bf16 v[78:81], v[230:233], v[218:221], v[78:81]
	v_mfma_f32_16x16x32_bf16 v[74:77], v[234:237], v[218:221], v[74:77]
	v_mfma_f32_16x16x32_bf16 v[70:73], v[238:241], v[218:221], v[70:73]
	v_mfma_f32_16x16x32_bf16 v[66:69], v[242:245], v[218:221], v[66:69]
	v_mfma_f32_16x16x32_bf16 v[62:65], v[230:233], v[222:225], v[62:65]
	v_mfma_f32_16x16x32_bf16 v[58:61], v[234:237], v[222:225], v[58:61]
	v_mfma_f32_16x16x32_bf16 v[54:57], v[238:241], v[222:225], v[54:57]
	v_mfma_f32_16x16x32_bf16 v[50:53], v[242:245], v[222:225], v[50:53]
	v_mfma_f32_16x16x32_bf16 v[46:49], v[230:233], v[226:229], v[46:49]
	v_mfma_f32_16x16x32_bf16 v[42:45], v[234:237], v[226:229], v[42:45]
	v_mfma_f32_16x16x32_bf16 v[38:41], v[238:241], v[226:229], v[38:41]
	v_mfma_f32_16x16x32_bf16 v[34:37], v[242:245], v[226:229], v[34:37]
.Lstg_892_b:
	s_mov_b32 s100, s101
	s_xor_b32 s2, s2, 0x10000
	s_add_u32 s0, s0, 0x80
	s_addc_u32 s1, s1, 0
	s_cmpk_lg_i32 s0, 0x700
	s_cbranch_scc1 .LBB0_892
	s_cmp_eq_u32 s100, 0
	s_cbranch_scc1 .Lstg_892_c
	s_waitcnt lgkmcnt(0)
	v_mfma_f32_16x16x32_bf16 v[158:161], v[230:233], v[192:195], v[158:161]
	v_mfma_f32_16x16x32_bf16 v[154:157], v[234:237], v[192:195], v[154:157]
	v_mfma_f32_16x16x32_bf16 v[150:153], v[238:241], v[192:195], v[150:153]
	v_mfma_f32_16x16x32_bf16 v[146:149], v[242:245], v[192:195], v[146:149]
	v_mfma_f32_16x16x32_bf16 v[142:145], v[230:233], v[198:201], v[142:145]
	v_mfma_f32_16x16x32_bf16 v[138:141], v[234:237], v[198:201], v[138:141]
	v_mfma_f32_16x16x32_bf16 v[134:137], v[238:241], v[198:201], v[134:137]
	v_mfma_f32_16x16x32_bf16 v[130:133], v[242:245], v[198:201], v[130:133]
	v_mfma_f32_16x16x32_bf16 v[126:129], v[230:233], v[206:209], v[126:129]
	v_mfma_f32_16x16x32_bf16 v[122:125], v[234:237], v[206:209], v[122:125]
	v_mfma_f32_16x16x32_bf16 v[118:121], v[238:241], v[206:209], v[118:121]
	v_mfma_f32_16x16x32_bf16 v[114:117], v[242:245], v[206:209], v[114:117]
	v_mfma_f32_16x16x32_bf16 v[110:113], v[230:233], v[210:213], v[110:113]
	v_mfma_f32_16x16x32_bf16 v[106:109], v[234:237], v[210:213], v[106:109]
	v_mfma_f32_16x16x32_bf16 v[102:105], v[238:241], v[210:213], v[102:105]
	v_mfma_f32_16x16x32_bf16 v[98:101], v[242:245], v[210:213], v[98:101]
	v_mfma_f32_16x16x32_bf16 v[94:97], v[230:233], v[214:217], v[94:97]
	v_mfma_f32_16x16x32_bf16 v[90:93], v[234:237], v[214:217], v[90:93]
	v_mfma_f32_16x16x32_bf16 v[86:89], v[238:241], v[214:217], v[86:89]
	v_mfma_f32_16x16x32_bf16 v[82:85], v[242:245], v[214:217], v[82:85]
	v_mfma_f32_16x16x32_bf16 v[78:81], v[230:233], v[218:221], v[78:81]
	v_mfma_f32_16x16x32_bf16 v[74:77], v[234:237], v[218:221], v[74:77]
	v_mfma_f32_16x16x32_bf16 v[70:73], v[238:241], v[218:221], v[70:73]
	v_mfma_f32_16x16x32_bf16 v[66:69], v[242:245], v[218:221], v[66:69]
	v_mfma_f32_16x16x32_bf16 v[62:65], v[230:233], v[222:225], v[62:65]
	v_mfma_f32_16x16x32_bf16 v[58:61], v[234:237], v[222:225], v[58:61]
	v_mfma_f32_16x16x32_bf16 v[54:57], v[238:241], v[222:225], v[54:57]
	v_mfma_f32_16x16x32_bf16 v[50:53], v[242:245], v[222:225], v[50:53]
	v_mfma_f32_16x16x32_bf16 v[46:49], v[230:233], v[226:229], v[46:49]
	v_mfma_f32_16x16x32_bf16 v[42:45], v[234:237], v[226:229], v[42:45]
	v_mfma_f32_16x16x32_bf16 v[38:41], v[238:241], v[226:229], v[38:41]
	v_mfma_f32_16x16x32_bf16 v[34:37], v[242:245], v[226:229], v[34:37]
	s_mov_b32 s100, 0

; DI int TID8() { int t = threadIdx.x; asm volatile("" : "+v"(t)); return t; }
; DI void gemm8_accum(f32x4 (&acc)[8][4], const bf16_t* a, size_t lda, const bf16_t* b, size_t ldb, int nkb, bf16_t* L,
;                     const bool pre, const bf16_t* an, size_t ldan, const bf16_t* bn, size_t ldbn) {
;   const int tid = TID8(), lane = tid & 63, w = tid >> 6;
;   const int wm = w >> 2, wn = w & 3;
;   const int lrow = tid >> 3, lch = tid & 7;
;   u32x4 ra[4], rb[4];
;   unsigned offa[4], offb[4];
; #pragma unroll
;   for (int i = 0; i < 4; ++i) {
;     offa[i] = (unsigned)(lrow + 64 * i) * (unsigned)lda + (unsigned)(lch * 8);
;     offb[i] = (unsigned)(lrow + 64 * i) * (unsigned)ldb + (unsigned)(lch * 8);
;   }
;   if (!pre) {
;     g8_load1o(ra, a, offa);
;     g8_load1o(rb, b, offb);
;     __syncthreads();
;     g8_store(L, ra, rb, lrow, lch);
;   }
;   g8_load1o(ra, a + 64, offa);
;   g8_load1o(rb, b + 64, offb);
; __global__ void __launch_bounds__(512, 2) mega(Params p) {
;     ...
;       gemm8_accum(acc8, ubuf + (size_t)m0 * 4096, 4096, wl + W_FF2 + (size_t)n0 * 4096, 4096, 64, lds_all, !first_,
;                   ubuf + (size_t)mtn * 256 * 4096, 4096, wl + W_FF2 + (size_t)ntilen * 256 * 4096, 4096);
.LBB0_941:
	v_lshlrev_b64 v[40:41], 1, v[168:169]
	v_lshl_add_u64 v[6:7], s[2:3], 0, v[40:41]
	v_lshlrev_b64 v[42:43], 1, v[166:167]
	v_lshlrev_b64 v[44:45], 1, v[0:1]
	v_lshl_add_u64 v[8:9], s[2:3], 0, v[42:43]
	global_load_dwordx4 v[18:21], v[6:7], off offset:128
	global_load_dwordx4 v[26:29], v[8:9], off offset:128
	v_lshl_add_u64 v[6:7], s[2:3], 0, v[44:45]
	global_load_dwordx4 v[22:25], v[4:5], off offset:128
	global_load_dwordx4 v[30:33], v[6:7], off offset:128
	global_load_dwordx4 v[14:17], v[2:3], off offset:128
	v_lshl_add_u64 v[2:3], s[0:1], 0, v[40:41]
	s_nop 1
	global_load_dwordx4 v[2:5], v[2:3], off offset:128
	v_lshl_add_u64 v[6:7], s[0:1], 0, v[42:43]
	v_lshl_add_u64 v[10:11], s[0:1], 0, v[44:45]
	global_load_dwordx4 v[6:9], v[6:7], off offset:128
	s_nop 0
	global_load_dwordx4 v[10:13], v[10:11], off offset:128
	v_bfe_u32 v39, v36, 4, 2
	v_lshrrev_b32_e32 v46, 1, v36
	s_lshl_b32 s6, s12, 8
	s_and_b32 s12, s10, 0x60
	v_readlane_b32 s20, v252, 25
	v_bitop3_b32 v46, v46, v39, 7 bitop3:0x6c
	s_lshr_b32 s7, s13, 2
	s_or_b32 s12, s20, s12
	s_and_b32 s20, s9, 3
	v_lshlrev_b32_e32 v191, 3, v46
	v_lshlrev_b32_e32 v46, 5, v36
	s_and_b32 s7, s7, 3
	s_add_i32 s12, s12, s20
	v_bfe_u32 v47, v36, 1, 3
	v_and_b32_e32 v46, 0xffffe000, v46
	v_lshlrev_b32_e32 v36, 6, v36
	s_movk_i32 s0, 0x3c0
	s_lshl_b32 s7, s7, 21
	s_lshl_b32 s12, s12, 21
	v_and_or_b32 v46, v36, s0, v46
	v_readlane_b32 s0, v254, 30
	s_add_u32 s0, s0, s7
	v_readlane_b32 s1, v254, 31
	v_add_u32_e32 v34, v35, v34
	v_mov_b32_e32 v35, v1
	s_addc_u32 s1, s1, 0
	v_lshlrev_b64 v[34:35], 1, v[34:35]
	v_lshl_add_u64 v[170:171], s[0:1], 0, v[44:45]
	v_lshl_add_u64 v[172:173], s[0:1], 0, v[42:43]
	v_lshl_add_u64 v[174:175], s[0:1], 0, v[40:41]
	v_lshl_add_u64 v[176:177], s[0:1], 0, v[34:35]
	v_readlane_b32 s0, v254, 32
	s_add_u32 s0, s0, s12
	v_readlane_b32 s1, v254, 33
	s_addc_u32 s1, s1, 0
	v_and_b32_e32 v36, 0x33c0, v36
	v_bitop3_b32 v39, v39, v47, 4 bitop3:0x36
	v_lshlrev_b32_e32 v189, 1, v38
	v_lshlrev_b32_e32 v190, 1, v37
	v_lshl_add_u64 v[184:185], s[0:1], 0, v[34:35]
	v_mov_b32_e32 v34, 0
	v_lshlrev_b32_e32 v188, 3, v39
	v_add3_u32 v163, 0, v189, v190
	v_lshl_add_u64 v[178:179], s[0:1], 0, v[44:45]
	v_lshl_add_u64 v[180:181], s[0:1], 0, v[42:43]
	v_lshl_add_u64 v[182:183], s[0:1], 0, v[40:41]
	s_mov_b64 s[0:1], 0
	s_mov_b32 s2, 0
	v_lshlrev_b32_e32 v187, 1, v46
	v_lshlrev_b32_e32 v186, 1, v36
	v_mov_b32_e32 v35, v34
	v_mov_b64_e32 v[36:37], v[34:35]
	v_mov_b64_e32 v[38:39], v[34:35]
	v_mov_b64_e32 v[40:41], v[34:35]
	v_mov_b64_e32 v[42:43], v[34:35]
	v_mov_b64_e32 v[44:45], v[34:35]
	v_mov_b64_e32 v[46:47], v[34:35]
	v_mov_b64_e32 v[48:49], v[34:35]
	v_mov_b64_e32 v[50:51], v[34:35]
	v_mov_b64_e32 v[52:53], v[34:35]
	v_mov_b64_e32 v[54:55], v[34:35]
	v_mov_b64_e32 v[56:57], v[34:35]
	v_mov_b64_e32 v[58:59], v[34:35]
	v_mov_b64_e32 v[60:61], v[34:35]
	v_mov_b64_e32 v[62:63], v[34:35]
	v_mov_b64_e32 v[64:65], v[34:35]
	v_mov_b64_e32 v[66:67], v[34:35]
	v_mov_b64_e32 v[68:69], v[34:35]
	v_mov_b64_e32 v[70:71], v[34:35]
	v_mov_b64_e32 v[72:73], v[34:35]
	v_mov_b64_e32 v[74:75], v[34:35]
	v_mov_b64_e32 v[76:77], v[34:35]
	v_mov_b64_e32 v[78:79], v[34:35]
	v_mov_b64_e32 v[80:81], v[34:35]
	v_mov_b64_e32 v[82:83], v[34:35]
	v_mov_b64_e32 v[84:85], v[34:35]
	v_mov_b64_e32 v[86:87], v[34:35]
	v_mov_b64_e32 v[88:89], v[34:35]
	v_mov_b64_e32 v[90:91], v[34:35]
	v_mov_b64_e32 v[92:93], v[34:35]
	v_mov_b64_e32 v[94:95], v[34:35]
	v_mov_b64_e32 v[96:97], v[34:35]
	v_mov_b64_e32 v[98:99], v[34:35]
	v_mov_b64_e32 v[100:101], v[34:35]
	v_mov_b64_e32 v[102:103], v[34:35]
	v_mov_b64_e32 v[104:105], v[34:35]
	v_mov_b64_e32 v[106:107], v[34:35]
	v_mov_b64_e32 v[108:109], v[34:35]
	v_mov_b64_e32 v[110:111], v[34:35]
	v_mov_b64_e32 v[112:113], v[34:35]
	v_mov_b64_e32 v[114:115], v[34:35]
	v_mov_b64_e32 v[116:117], v[34:35]
	v_mov_b64_e32 v[118:119], v[34:35]
	v_mov_b64_e32 v[120:121], v[34:35]
	v_mov_b64_e32 v[122:123], v[34:35]
	v_mov_b64_e32 v[124:125], v[34:35]
	v_mov_b64_e32 v[126:127], v[34:35]
	v_mov_b64_e32 v[128:129], v[34:35]
	v_mov_b64_e32 v[130:131], v[34:35]
	v_mov_b64_e32 v[132:133], v[34:35]
	v_mov_b64_e32 v[134:135], v[34:35]
	v_mov_b64_e32 v[136:137], v[34:35]
	v_mov_b64_e32 v[138:139], v[34:35]
	v_mov_b64_e32 v[140:141], v[34:35]
	v_mov_b64_e32 v[142:143], v[34:35]
	v_mov_b64_e32 v[144:145], v[34:35]
	v_mov_b64_e32 v[146:147], v[34:35]
	v_mov_b64_e32 v[148:149], v[34:35]
	v_mov_b64_e32 v[150:151], v[34:35]
	v_mov_b64_e32 v[152:153], v[34:35]
	v_mov_b64_e32 v[154:155], v[34:35]
	v_mov_b64_e32 v[156:157], v[34:35]
	v_mov_b64_e32 v[158:159], v[34:35]
	v_mov_b64_e32 v[160:161], v[34:35]
	v_readfirstlane_b32 s52, v184
	v_readfirstlane_b32 s53, v185
	s_sub_u32 s52, s52, 0x40000000
	s_subb_u32 s53, s53, 0
	v_readfirstlane_b32 s56, v176
	v_readfirstlane_b32 s57, v177
	s_sub_u32 s56, s56, 0x40000000
	s_subb_u32 s57, s57, 0
	v_subrev_u32_e32 v185, s52, v184
	v_subrev_u32_e32 v181, s52, v180
	v_subrev_u32_e32 v179, s52, v178
	v_subrev_u32_e32 v183, s52, v182
	v_subrev_u32_e32 v177, s56, v176
	v_subrev_u32_e32 v175, s56, v174
	v_subrev_u32_e32 v173, s56, v172
	v_subrev_u32_e32 v171, s56, v170
	v_lshl_add_u32 v170, v191, 1, v187
	v_lshl_add_u32 v172, v191, 1, v186
	v_lshl_add_u32 v174, v188, 1, v187
	v_lshl_add_u32 v176, v188, 1, v186
; DI void gemm8_accum(f32x4 (&acc)[8][4], const bf16_t* a, size_t lda, const bf16_t* b, size_t ldb, int nkb, bf16_t* L,
;                     const bool pre, const bf16_t* an, size_t ldan, const bf16_t* bn, size_t ldbn) {
;     ...
;   for (int kb = 0; kb + 2 < nkb; ++kb) {
;     __syncthreads();
;     g8_store1(L + ((kb + 1) & 1) * 32768, ra, lrow, lch);
;     g8_load1o(ra, a + (kb + 2) * 64, offa);
;     __builtin_amdgcn_sched_barrier(0);
;     g8_compute<0, 1>(acc, L + (kb & 1) * 32768, wm, wn, lane);
;     __builtin_amdgcn_sched_barrier(0);
;     g8_store1(L + ((kb + 1) & 1) * 32768 + 16384, rb, lrow, lch);
;     g8_load1o(rb, b + (kb + 2) * 64, offb);
;     __builtin_amdgcn_sched_barrier(0);
;     g8_compute<1, 2>(acc, L + (kb & 1) * 32768, wm, wn, lane);
.LBB0_942:
	s_xor_b32 s7, s2, 0x10000
	v_add_u32_e32 v167, s7, v163
	s_waitcnt lgkmcnt(0)
	s_barrier
	s_cmp_eq_u32 s100, 0
	s_cbranch_scc1 .Lstg_942_a
	v_mfma_f32_16x16x32_bf16 v[158:161], v[226:229], v[192:195], v[158:161]
	v_mfma_f32_16x16x32_bf16 v[154:157], v[230:233], v[192:195], v[154:157]
	v_mfma_f32_16x16x32_bf16 v[150:153], v[234:237], v[192:195], v[150:153]
	v_mfma_f32_16x16x32_bf16 v[146:149], v[238:241], v[192:195], v[146:149]
	v_mfma_f32_16x16x32_bf16 v[142:145], v[226:229], v[198:201], v[142:145]
	v_mfma_f32_16x16x32_bf16 v[138:141], v[230:233], v[198:201], v[138:141]
	v_mfma_f32_16x16x32_bf16 v[134:137], v[234:237], v[198:201], v[134:137]
	v_mfma_f32_16x16x32_bf16 v[130:133], v[238:241], v[198:201], v[130:133]
	v_mfma_f32_16x16x32_bf16 v[126:129], v[226:229], v[202:205], v[126:129]
	v_mfma_f32_16x16x32_bf16 v[122:125], v[230:233], v[202:205], v[122:125]
	v_mfma_f32_16x16x32_bf16 v[118:121], v[234:237], v[202:205], v[118:121]
	v_mfma_f32_16x16x32_bf16 v[114:117], v[238:241], v[202:205], v[114:117]
	v_mfma_f32_16x16x32_bf16 v[110:113], v[226:229], v[206:209], v[110:113]
	v_mfma_f32_16x16x32_bf16 v[106:109], v[230:233], v[206:209], v[106:109]
	v_mfma_f32_16x16x32_bf16 v[102:105], v[234:237], v[206:209], v[102:105]
	v_mfma_f32_16x16x32_bf16 v[98:101], v[238:241], v[206:209], v[98:101]
	v_mfma_f32_16x16x32_bf16 v[94:97], v[226:229], v[210:213], v[94:97]
	v_mfma_f32_16x16x32_bf16 v[90:93], v[230:233], v[210:213], v[90:93]
	v_mfma_f32_16x16x32_bf16 v[86:89], v[234:237], v[210:213], v[86:89]
	v_mfma_f32_16x16x32_bf16 v[82:85], v[238:241], v[210:213], v[82:85]
	v_mfma_f32_16x16x32_bf16 v[78:81], v[226:229], v[214:217], v[78:81]
	v_mfma_f32_16x16x32_bf16 v[74:77], v[230:233], v[214:217], v[74:77]
	v_mfma_f32_16x16x32_bf16 v[70:73], v[234:237], v[214:217], v[70:73]
	v_mfma_f32_16x16x32_bf16 v[66:69], v[238:241], v[214:217], v[66:69]
	v_mfma_f32_16x16x32_bf16 v[62:65], v[226:229], v[218:221], v[62:65]
	v_mfma_f32_16x16x32_bf16 v[58:61], v[230:233], v[218:221], v[58:61]
	v_mfma_f32_16x16x32_bf16 v[54:57], v[234:237], v[218:221], v[54:57]
	v_mfma_f32_16x16x32_bf16 v[50:53], v[238:241], v[218:221], v[50:53]
	v_mfma_f32_16x16x32_bf16 v[46:49], v[226:229], v[222:225], v[46:49]
	v_mfma_f32_16x16x32_bf16 v[42:45], v[230:233], v[222:225], v[42:45]
	v_mfma_f32_16x16x32_bf16 v[38:41], v[234:237], v[222:225], v[38:41]
	v_mfma_f32_16x16x32_bf16 v[34:37], v[238:241], v[222:225], v[34:37]
.Lstg_942_a:
	s_waitcnt vmcnt(4)
	ds_write_b128 v167, v[22:25]
	ds_write_b128 v167, v[18:21] offset:8192
	ds_write_b128 v167, v[26:29] offset:16384
	ds_write_b128 v167, v[30:33] offset:24576
	s_add_u32 s54, s52, s0
	s_addc_u32 s55, s53, s1
	global_load_dwordx4 v[22:25], v185, s[54:55]
	global_load_dwordx4 v[26:29], v181, s[54:55]
	global_load_dwordx4 v[18:21], v183, s[54:55]
	global_load_dwordx4 v[30:33], v179, s[54:55]
	v_add_u32_e32 v222, s2, v170
	ds_read_b128 v[192:195], v222
	ds_read_b128 v[198:201], v222 offset:2048
	ds_read_b128 v[202:205], v222 offset:4096
	ds_read_b128 v[206:209], v222 offset:6144
	ds_read_b128 v[210:213], v222 offset:8192
	ds_read_b128 v[214:217], v222 offset:10240
	ds_read_b128 v[218:221], v222 offset:12288
	ds_read_b128 v[222:225], v222 offset:14336
	v_add_u32_e32 v169, s2, v172
	ds_read_b128 v[226:229], v169 offset:32768
	ds_read_b128 v[230:233], v169 offset:34816
	ds_read_b128 v[234:237], v169 offset:36864
	ds_read_b128 v[238:241], v169 offset:38912
	s_waitcnt lgkmcnt(3)
	v_mfma_f32_16x16x32_bf16 v[158:161], v[226:229], v[192:195], v[158:161]
	s_waitcnt lgkmcnt(2)
	v_mfma_f32_16x16x32_bf16 v[154:157], v[230:233], v[192:195], v[154:157]
	s_waitcnt lgkmcnt(1)
	v_mfma_f32_16x16x32_bf16 v[150:153], v[234:237], v[192:195], v[150:153]
	s_waitcnt lgkmcnt(0)
	v_mfma_f32_16x16x32_bf16 v[146:149], v[238:241], v[192:195], v[146:149]
	v_mfma_f32_16x16x32_bf16 v[142:145], v[226:229], v[198:201], v[142:145]
	v_mfma_f32_16x16x32_bf16 v[138:141], v[230:233], v[198:201], v[138:141]
	v_mfma_f32_16x16x32_bf16 v[134:137], v[234:237], v[198:201], v[134:137]
	v_mfma_f32_16x16x32_bf16 v[130:133], v[238:241], v[198:201], v[130:133]
	v_mfma_f32_16x16x32_bf16 v[126:129], v[226:229], v[202:205], v[126:129]
	v_mfma_f32_16x16x32_bf16 v[122:125], v[230:233], v[202:205], v[122:125]
	v_mfma_f32_16x16x32_bf16 v[118:121], v[234:237], v[202:205], v[118:121]
	v_mfma_f32_16x16x32_bf16 v[114:117], v[238:241], v[202:205], v[114:117]
	v_mfma_f32_16x16x32_bf16 v[110:113], v[226:229], v[206:209], v[110:113]
	v_mfma_f32_16x16x32_bf16 v[106:109], v[230:233], v[206:209], v[106:109]
	v_mfma_f32_16x16x32_bf16 v[102:105], v[234:237], v[206:209], v[102:105]
	v_mfma_f32_16x16x32_bf16 v[98:101], v[238:241], v[206:209], v[98:101]
	v_mfma_f32_16x16x32_bf16 v[94:97], v[226:229], v[210:213], v[94:97]
	v_mfma_f32_16x16x32_bf16 v[90:93], v[230:233], v[210:213], v[90:93]
	v_mfma_f32_16x16x32_bf16 v[86:89], v[234:237], v[210:213], v[86:89]
	v_mfma_f32_16x16x32_bf16 v[82:85], v[238:241], v[210:213], v[82:85]
	v_mfma_f32_16x16x32_bf16 v[78:81], v[226:229], v[214:217], v[78:81]
	v_mfma_f32_16x16x32_bf16 v[74:77], v[230:233], v[214:217], v[74:77]
	v_mfma_f32_16x16x32_bf16 v[70:73], v[234:237], v[214:217], v[70:73]
	v_mfma_f32_16x16x32_bf16 v[66:69], v[238:241], v[214:217], v[66:69]
	v_mfma_f32_16x16x32_bf16 v[62:65], v[226:229], v[218:221], v[62:65]
	v_mfma_f32_16x16x32_bf16 v[58:61], v[230:233], v[218:221], v[58:61]
	v_mfma_f32_16x16x32_bf16 v[54:57], v[234:237], v[218:221], v[54:57]
	v_mfma_f32_16x16x32_bf16 v[50:53], v[238:241], v[218:221], v[50:53]
	v_mfma_f32_16x16x32_bf16 v[46:49], v[226:229], v[222:225], v[46:49]
	v_mfma_f32_16x16x32_bf16 v[42:45], v[230:233], v[222:225], v[42:45]
	v_mfma_f32_16x16x32_bf16 v[38:41], v[234:237], v[222:225], v[38:41]
	v_mfma_f32_16x16x32_bf16 v[34:37], v[238:241], v[222:225], v[34:37]
	s_waitcnt vmcnt(4)
	ds_write_b128 v167, v[14:17] offset:32768
	ds_write_b128 v167, v[2:5] offset:40960
	ds_write_b128 v167, v[6:9] offset:49152
	ds_write_b128 v167, v[10:13] offset:57344
	s_add_u32 s58, s56, s0
	s_addc_u32 s59, s57, s1
	global_load_dwordx4 v[14:17], v177, s[58:59]
	global_load_dwordx4 v[2:5], v175, s[58:59]
	global_load_dwordx4 v[6:9], v173, s[58:59]
	global_load_dwordx4 v[10:13], v171, s[58:59]
	v_add_u32_e32 v169, s2, v174
	ds_read_b128 v[192:195], v169
	ds_read_b128 v[198:201], v169 offset:2048
	ds_read_b128 v[202:205], v169 offset:4096
	ds_read_b128 v[206:209], v169 offset:6144
	ds_read_b128 v[210:213], v169 offset:8192
	ds_read_b128 v[214:217], v169 offset:10240
	ds_read_b128 v[218:221], v169 offset:12288
	ds_read_b128 v[222:225], v169 offset:14336
	v_add_u32_e32 v167, s2, v176
	ds_read_b128 v[226:229], v167 offset:32768
	ds_read_b128 v[230:233], v167 offset:34816
	ds_read_b128 v[234:237], v167 offset:36864
	ds_read_b128 v[238:241], v167 offset:38912
	s_cmp_lg_u32 s101, 0
	s_cbranch_scc1 .Lstg_942_b
; DI void gemm8_accum(f32x4 (&acc)[8][4], const bf16_t* a, size_t lda, const bf16_t* b, size_t ldb, int nkb, bf16_t* L,
;                     const bool pre, const bf16_t* an, size_t ldan, const bf16_t* bn, size_t ldbn) {
;     ...
;     g8_compute<0, 1>(acc, L + (kb & 1) * 32768, wm, wn, lane);
;     __builtin_amdgcn_sched_barrier(0);
;     g8_store1(L + ((kb + 1) & 1) * 32768 + 16384, rb, lrow, lch);
;     g8_load1o(rb, b + (kb + 2) * 64, offb);
;     __builtin_amdgcn_sched_barrier(0);
;     g8_compute<1, 2>(acc, L + (kb & 1) * 32768, wm, wn, lane);
;   }
;   __syncthreads();
;   g8_store1(L + 32768, ra, lrow, lch);
;   g8_load1(ra, an, ldan, 0, lrow, lch);
;   __builtin_amdgcn_sched_barrier(0);
;   g8_compute<0, 1>(acc, L, wm, wn, lane);
	s_waitcnt lgkmcnt(3)
	v_mfma_f32_16x16x32_bf16 v[158:161], v[226:229], v[192:195], v[158:161]
	s_waitcnt lgkmcnt(2)
	v_mfma_f32_16x16x32_bf16 v[154:157], v[230:233], v[192:195], v[154:157]
	s_waitcnt lgkmcnt(1)
	v_mfma_f32_16x16x32_bf16 v[150:153], v[234:237], v[192:195], v[150:153]
	s_waitcnt lgkmcnt(0)
	v_mfma_f32_16x16x32_bf16 v[146:149], v[238:241], v[192:195], v[146:149]
	v_mfma_f32_16x16x32_bf16 v[142:145], v[226:229], v[198:201], v[142:145]
	v_mfma_f32_16x16x32_bf16 v[138:141], v[230:233], v[198:201], v[138:141]
	v_mfma_f32_16x16x32_bf16 v[134:137], v[234:237], v[198:201], v[134:137]
	v_mfma_f32_16x16x32_bf16 v[130:133], v[238:241], v[198:201], v[130:133]
	v_mfma_f32_16x16x32_bf16 v[126:129], v[226:229], v[202:205], v[126:129]
	v_mfma_f32_16x16x32_bf16 v[122:125], v[230:233], v[202:205], v[122:125]
	v_mfma_f32_16x16x32_bf16 v[118:121], v[234:237], v[202:205], v[118:121]
	v_mfma_f32_16x16x32_bf16 v[114:117], v[238:241], v[202:205], v[114:117]
	v_mfma_f32_16x16x32_bf16 v[110:113], v[226:229], v[206:209], v[110:113]
	v_mfma_f32_16x16x32_bf16 v[106:109], v[230:233], v[206:209], v[106:109]
	v_mfma_f32_16x16x32_bf16 v[102:105], v[234:237], v[206:209], v[102:105]
	v_mfma_f32_16x16x32_bf16 v[98:101], v[238:241], v[206:209], v[98:101]
	v_mfma_f32_16x16x32_bf16 v[94:97], v[226:229], v[210:213], v[94:97]
	v_mfma_f32_16x16x32_bf16 v[90:93], v[230:233], v[210:213], v[90:93]
	v_mfma_f32_16x16x32_bf16 v[86:89], v[234:237], v[210:213], v[86:89]
	v_mfma_f32_16x16x32_bf16 v[82:85], v[238:241], v[210:213], v[82:85]
	v_mfma_f32_16x16x32_bf16 v[78:81], v[226:229], v[214:217], v[78:81]
	v_mfma_f32_16x16x32_bf16 v[74:77], v[230:233], v[214:217], v[74:77]
	v_mfma_f32_16x16x32_bf16 v[70:73], v[234:237], v[214:217], v[70:73]
	v_mfma_f32_16x16x32_bf16 v[66:69], v[238:241], v[214:217], v[66:69]
	v_mfma_f32_16x16x32_bf16 v[62:65], v[226:229], v[218:221], v[62:65]
	v_mfma_f32_16x16x32_bf16 v[58:61], v[230:233], v[218:221], v[58:61]
	v_mfma_f32_16x16x32_bf16 v[54:57], v[234:237], v[218:221], v[54:57]
	v_mfma_f32_16x16x32_bf16 v[50:53], v[238:241], v[218:221], v[50:53]
	v_mfma_f32_16x16x32_bf16 v[46:49], v[226:229], v[222:225], v[46:49]
	v_mfma_f32_16x16x32_bf16 v[42:45], v[230:233], v[222:225], v[42:45]
	v_mfma_f32_16x16x32_bf16 v[38:41], v[234:237], v[222:225], v[38:41]
	v_mfma_f32_16x16x32_bf16 v[34:37], v[238:241], v[222:225], v[34:37]
.Lstg_942_b:
	s_mov_b32 s100, s101
	s_xor_b32 s2, s2, 0x10000
	s_add_u32 s0, s0, 0x80
	s_addc_u32 s1, s1, 0
	s_cmpk_lg_i32 s0, 0x1f00
	s_cbranch_scc1 .LBB0_942
	s_cmp_eq_u32 s100, 0
	s_cbranch_scc1 .Lstg_942_c
	s_waitcnt lgkmcnt(0)
	v_mfma_f32_16x16x32_bf16 v[158:161], v[226:229], v[192:195], v[158:161]
	v_mfma_f32_16x16x32_bf16 v[154:157], v[230:233], v[192:195], v[154:157]
	v_mfma_f32_16x16x32_bf16 v[150:153], v[234:237], v[192:195], v[150:153]
	v_mfma_f32_16x16x32_bf16 v[146:149], v[238:241], v[192:195], v[146:149]
	v_mfma_f32_16x16x32_bf16 v[142:145], v[226:229], v[198:201], v[142:145]
	v_mfma_f32_16x16x32_bf16 v[138:141], v[230:233], v[198:201], v[138:141]
	v_mfma_f32_16x16x32_bf16 v[134:137], v[234:237], v[198:201], v[134:137]
	v_mfma_f32_16x16x32_bf16 v[130:133], v[238:241], v[198:201], v[130:133]
	v_mfma_f32_16x16x32_bf16 v[126:129], v[226:229], v[202:205], v[126:129]
	v_mfma_f32_16x16x32_bf16 v[122:125], v[230:233], v[202:205], v[122:125]
	v_mfma_f32_16x16x32_bf16 v[118:121], v[234:237], v[202:205], v[118:121]
	v_mfma_f32_16x16x32_bf16 v[114:117], v[238:241], v[202:205], v[114:117]
	v_mfma_f32_16x16x32_bf16 v[110:113], v[226:229], v[206:209], v[110:113]
	v_mfma_f32_16x16x32_bf16 v[106:109], v[230:233], v[206:209], v[106:109]
	v_mfma_f32_16x16x32_bf16 v[102:105], v[234:237], v[206:209], v[102:105]
	v_mfma_f32_16x16x32_bf16 v[98:101], v[238:241], v[206:209], v[98:101]
	v_mfma_f32_16x16x32_bf16 v[94:97], v[226:229], v[210:213], v[94:97]
	v_mfma_f32_16x16x32_bf16 v[90:93], v[230:233], v[210:213], v[90:93]
	v_mfma_f32_16x16x32_bf16 v[86:89], v[234:237], v[210:213], v[86:89]
	v_mfma_f32_16x16x32_bf16 v[82:85], v[238:241], v[210:213], v[82:85]
	v_mfma_f32_16x16x32_bf16 v[78:81], v[226:229], v[214:217], v[78:81]
	v_mfma_f32_16x16x32_bf16 v[74:77], v[230:233], v[214:217], v[74:77]
	v_mfma_f32_16x16x32_bf16 v[70:73], v[234:237], v[214:217], v[70:73]
	v_mfma_f32_16x16x32_bf16 v[66:69], v[238:241], v[214:217], v[66:69]
	v_mfma_f32_16x16x32_bf16 v[62:65], v[226:229], v[218:221], v[62:65]
	v_mfma_f32_16x16x32_bf16 v[58:61], v[230:233], v[218:221], v[58:61]
	v_mfma_f32_16x16x32_bf16 v[54:57], v[234:237], v[218:221], v[54:57]
	v_mfma_f32_16x16x32_bf16 v[50:53], v[238:241], v[218:221], v[50:53]
	v_mfma_f32_16x16x32_bf16 v[46:49], v[226:229], v[222:225], v[46:49]
	v_mfma_f32_16x16x32_bf16 v[42:45], v[230:233], v[222:225], v[42:45]
	v_mfma_f32_16x16x32_bf16 v[38:41], v[234:237], v[222:225], v[38:41]
	v_mfma_f32_16x16x32_bf16 v[34:37], v[238:241], v[222:225], v[34:37]
	s_mov_b32 s100, 0

; DI int TID8() { int t = threadIdx.x; asm volatile("" : "+v"(t)); return t; }
; DI void gemm8_accum(f32x4 (&acc)[8][4], const bf16_t* a, size_t lda, const bf16_t* b, size_t ldb, int nkb, bf16_t* L,
;                     const bool pre, const bf16_t* an, size_t ldan, const bf16_t* bn, size_t ldbn) {
;   const int tid = TID8(), lane = tid & 63, w = tid >> 6;
;   const int wm = w >> 2, wn = w & 3;
;   const int lrow = tid >> 3, lch = tid & 7;
;   u32x4 ra[4], rb[4];
;   unsigned offa[4], offb[4];
; #pragma unroll
;   for (int i = 0; i < 4; ++i) {
;     offa[i] = (unsigned)(lrow + 64 * i) * (unsigned)lda + (unsigned)(lch * 8);
;     offb[i] = (unsigned)(lrow + 64 * i) * (unsigned)ldb + (unsigned)(lch * 8);
;   }
;   if (!pre) {
;     g8_load1o(ra, a, offa);
;     g8_load1o(rb, b, offb);
;     __syncthreads();
;     g8_store(L, ra, rb, lrow, lch);
;   }
;   g8_load1o(ra, a + 64, offa);
;   g8_load1o(rb, b + 64, offb);
; template <class F>
; DI void gemm8_epi_staged(f32x4 (&acc)[8][4], int m0, int n0, bf16_t* L0, F f, bf16_t* dst, size_t ld, int nmax) {
;     ...
; #pragma unroll
;     for (int it = 0; it < 8; ++it) {
;       const int idx = tid + 512 * it;
;       const int row = idx >> 5, ch = idx & 31;
;       const u32x4 v = *(const u32x4*)(L + row * 264 + ch * 8);
;       const int n = n0 + ch * 8;
;       if (n < nmax) *(u32x4*)(dst + (size_t)(m0 + half * 128 + row) * ld + n) = v;
;     }
;     __syncthreads();
.LBB0_1006:
	s_or_b64 exec, exec, s[4:5]
	s_and_b32 s5, s10, 0x60
	v_readlane_b32 s6, v252, 25
	s_or_b32 s5, s6, s5
	s_and_b32 s6, s9, 3
	s_add_i32 s5, s5, s6
	s_waitcnt lgkmcnt(0)
	s_barrier
	s_or_b32 s6, s13, 0x80
	ds_read_b128 v[2:5], v77
	v_add_u32_e32 v6, s6, v0
	v_ashrrev_i32_e32 v7, 31, v6
	v_lshlrev_b64 v[6:7], 11, v[6:7]
	v_lshl_add_u64 v[10:11], v[66:67], 0, v[6:7]
	ds_read_b128 v[6:9], v79
	s_waitcnt lgkmcnt(1)
	global_store_dwordx4 v[10:11], v[2:5], off
	v_mov_b32_e32 v26, v196
	s_lshl_b32 s4, s11, 11
	v_add_u32_e32 v2, s6, v78
	v_ashrrev_i32_e32 v3, 31, v2
	v_lshlrev_b64 v[2:3], 11, v[2:3]
	v_lshl_add_u64 v[2:3], v[66:67], 0, v[2:3]
	s_waitcnt lgkmcnt(0)
	global_store_dwordx4 v[2:3], v[6:9], off
	ds_read_b128 v[2:5], v81
	s_and_b32 s4, s4, 0x180000
	v_add_u32_e32 v6, s6, v80
	v_ashrrev_i32_e32 v7, 31, v6
	v_lshlrev_b64 v[6:7], 11, v[6:7]
	v_lshl_add_u64 v[10:11], v[66:67], 0, v[6:7]
	ds_read_b128 v[6:9], v83
	s_waitcnt lgkmcnt(1)
	global_store_dwordx4 v[10:11], v[2:5], off
	s_lshl_b32 s5, s5, 19
	s_nop 0
	v_add_u32_e32 v2, s6, v82
	v_ashrrev_i32_e32 v3, 31, v2
	v_lshlrev_b64 v[2:3], 11, v[2:3]
	v_lshl_add_u64 v[2:3], v[66:67], 0, v[2:3]
	s_waitcnt lgkmcnt(0)
	global_store_dwordx4 v[2:3], v[6:9], off
	ds_read_b128 v[2:5], v85
	s_nop 0
	v_add_u32_e32 v6, s6, v84
	v_ashrrev_i32_e32 v7, 31, v6
	v_lshlrev_b64 v[6:7], 11, v[6:7]
	v_lshl_add_u64 v[10:11], v[66:67], 0, v[6:7]
	ds_read_b128 v[6:9], v87
	s_waitcnt lgkmcnt(1)
	global_store_dwordx4 v[10:11], v[2:5], off
	s_nop 1
	v_add_u32_e32 v2, s6, v86
	v_ashrrev_i32_e32 v3, 31, v2
	v_lshlrev_b64 v[2:3], 11, v[2:3]
	v_lshl_add_u64 v[2:3], v[66:67], 0, v[2:3]
	s_waitcnt lgkmcnt(0)
	global_store_dwordx4 v[2:3], v[6:9], off
	ds_read_b128 v[2:5], v89
	s_nop 0
	v_add_u32_e32 v6, s6, v88
	v_ashrrev_i32_e32 v7, 31, v6
	v_lshlrev_b64 v[6:7], 11, v[6:7]
	v_lshl_add_u64 v[10:11], v[66:67], 0, v[6:7]
	ds_read_b128 v[6:9], v91
	s_waitcnt lgkmcnt(1)
	global_store_dwordx4 v[10:11], v[2:5], off
	s_nop 1
	v_add_u32_e32 v2, s6, v90
	v_ashrrev_i32_e32 v3, 31, v2
	v_lshlrev_b64 v[2:3], 11, v[2:3]
	v_lshl_add_u64 v[2:3], v[66:67], 0, v[2:3]
	s_waitcnt lgkmcnt(0)
	global_store_dwordx4 v[2:3], v[6:9], off
	s_barrier
	v_mov_b32_e32 v3, v1
	v_ashrrev_i32_e32 v189, 3, v26
	v_lshlrev_b32_e32 v0, 3, v26
	v_and_b32_e32 v184, 56, v0
	v_add_u32_e32 v188, 64, v189
	v_lshrrev_b32_e32 v8, 1, v189
	v_lshl_or_b32 v0, v189, 10, v184
	v_lshl_or_b32 v2, v188, 10, v184
	v_add_u32_e32 v187, 0x80, v189
	v_add_u32_e32 v185, 0xc0, v189
	v_xor_b32_e32 v8, v8, v26
	v_lshl_or_b32 v4, v187, 10, v184
	v_lshl_or_b32 v6, v185, 10, v184
	v_mov_b32_e32 v5, v1
	v_mov_b32_e32 v7, v1
	v_lshlrev_b32_e32 v8, 3, v8
	v_lshlrev_b64 v[18:19], 1, v[0:1]
	v_lshlrev_b64 v[20:21], 1, v[2:3]
	v_and_b32_e32 v27, 56, v8
	v_lshl_add_u64 v[8:9], s[2:3], 0, v[18:19]
	v_lshl_add_u64 v[2:3], s[2:3], 0, v[20:21]
	v_lshlrev_b64 v[22:23], 1, v[4:5]
	v_lshlrev_b64 v[24:25], 1, v[6:7]
	global_load_dwordx4 v[34:37], v[8:9], off offset:128
	global_load_dwordx4 v[42:45], v[2:3], off offset:128
	v_lshl_add_u64 v[2:3], s[2:3], 0, v[22:23]
	v_lshl_add_u64 v[4:5], s[2:3], 0, v[24:25]
	global_load_dwordx4 v[54:57], v[2:3], off offset:128
	global_load_dwordx4 v[94:97], v[4:5], off offset:128
	v_lshl_add_u64 v[2:3], s[0:1], 0, v[18:19]
	v_lshl_add_u64 v[4:5], s[0:1], 0, v[20:21]
	v_lshl_add_u64 v[6:7], s[0:1], 0, v[22:23]
	v_lshl_add_u64 v[10:11], s[0:1], 0, v[24:25]
	global_load_dwordx4 v[14:17], v[2:3], off offset:128
	s_nop 0
	global_load_dwordx4 v[2:5], v[4:5], off offset:128
	s_nop 0
	global_load_dwordx4 v[6:9], v[6:7], off offset:128
	s_nop 0
	global_load_dwordx4 v[10:13], v[10:11], off offset:128
	v_bfe_u32 v0, v26, 4, 2
	v_lshrrev_b32_e32 v28, 1, v26
	v_bitop3_b32 v28, v28, v0, 7 bitop3:0x6c
	v_lshlrev_b32_e32 v186, 3, v28
	v_lshlrev_b32_e32 v28, 5, v26
	v_bfe_u32 v29, v26, 1, 3
	v_and_b32_e32 v28, 0xffffe000, v28
	v_lshlrev_b32_e32 v26, 6, v26
	s_movk_i32 s0, 0x3c0
	v_and_or_b32 v28, v26, s0, v28
	v_readlane_b32 s0, v254, 34
	s_add_u32 s0, s0, s4
	v_readlane_b32 s1, v254, 35
	s_addc_u32 s1, s1, 0
	v_bitop3_b32 v0, v0, v29, 4 bitop3:0x36
	v_lshl_add_u64 v[164:165], s[0:1], 0, v[24:25]
	v_lshl_add_u64 v[166:167], s[0:1], 0, v[22:23]
	v_lshl_add_u64 v[168:169], s[0:1], 0, v[20:21]
	v_lshl_add_u64 v[170:171], s[0:1], 0, v[18:19]
	v_readlane_b32 s0, v253, 57
	s_add_u32 s0, s0, s5
	v_readlane_b32 s1, v253, 58
	s_addc_u32 s1, s1, 0
	v_and_b32_e32 v26, 0x33c0, v26
	v_lshlrev_b32_e32 v182, 3, v0
	v_lshlrev_b32_e32 v183, 1, v27
	v_lshlrev_b32_e32 v0, 7, v189
	v_lshl_add_u64 v[178:179], s[0:1], 0, v[18:19]
	v_mov_b32_e32 v18, 0
	v_lshlrev_b32_e32 v190, 6, v189
	v_add3_u32 v163, 0, v183, v0
	v_lshl_add_u64 v[172:173], s[0:1], 0, v[24:25]
	v_lshl_add_u64 v[174:175], s[0:1], 0, v[22:23]
	v_lshl_add_u64 v[176:177], s[0:1], 0, v[20:21]
	s_mov_b64 s[0:1], 0
	s_mov_b32 s2, 0
	v_lshlrev_b32_e32 v181, 1, v28
	v_lshlrev_b32_e32 v180, 1, v26
	v_mov_b32_e32 v19, v18
	v_mov_b32_e32 v20, v18
	v_mov_b32_e32 v21, v18
	v_mov_b32_e32 v22, v18
	v_mov_b32_e32 v23, v18
	v_mov_b32_e32 v24, v18
	v_mov_b32_e32 v25, v18
	v_mov_b32_e32 v26, v18
	v_mov_b32_e32 v27, v18
	v_mov_b32_e32 v28, v18
	v_mov_b32_e32 v29, v18
	v_mov_b32_e32 v30, v18
	v_mov_b32_e32 v31, v18
	v_mov_b32_e32 v32, v18
	v_mov_b32_e32 v33, v18
	v_mov_b32_e32 v38, v18
	v_mov_b32_e32 v39, v18
	v_mov_b32_e32 v40, v18
	v_mov_b32_e32 v41, v18
	v_mov_b32_e32 v46, v18
	v_mov_b32_e32 v47, v18
	v_mov_b32_e32 v48, v18
	v_mov_b32_e32 v49, v18
	v_mov_b32_e32 v50, v18
	v_mov_b32_e32 v51, v18
	v_mov_b32_e32 v52, v18
	v_mov_b32_e32 v53, v18
	v_mov_b32_e32 v58, v18
	v_mov_b32_e32 v59, v18
	v_mov_b32_e32 v60, v18
	v_mov_b32_e32 v61, v18
; DI void gemm8_accum(f32x4 (&acc)[8][4], const bf16_t* a, size_t lda, const bf16_t* b, size_t ldb, int nkb, bf16_t* L,
;                     const bool pre, const bf16_t* an, size_t ldan, const bf16_t* bn, size_t ldbn) {
;     ...
;   u32x4 ra[4], rb[4];
;   unsigned offa[4], offb[4];
; #pragma unroll
;   for (int i = 0; i < 4; ++i) {
;     offa[i] = (unsigned)(lrow + 64 * i) * (unsigned)lda + (unsigned)(lch * 8);
;     offb[i] = (unsigned)(lrow + 64 * i) * (unsigned)ldb + (unsigned)(lch * 8);
;   }
;   if (!pre) {
;     g8_load1o(ra, a, offa);
;     g8_load1o(rb, b, offb);
;     __syncthreads();
;     g8_store(L, ra, rb, lrow, lch);
;   }
;   g8_load1o(ra, a + 64, offa);
;   g8_load1o(rb, b + 64, offb);
;   for (int kb = 0; kb + 2 < nkb; ++kb) {
;     __syncthreads();
;     g8_store1(L + ((kb + 1) & 1) * 32768, ra, lrow, lch);
;     g8_load1o(ra, a + (kb + 2) * 64, offa);
;     __builtin_amdgcn_sched_barrier(0);
;     g8_compute<0, 1>(acc, L + (kb & 1) * 32768, wm, wn, lane);
; DI void zero_acc8(f32x4 (&acc)[8][4]) {
; #pragma unroll
;   for (int i = 0; i < 8; ++i)
; #pragma unroll
;     for (int j = 0; j < 4; ++j) acc[i][j] = f32x4{0.f, 0.f, 0.f, 0.f};
; }
	v_mov_b32_e32 v62, v18
	v_mov_b32_e32 v63, v18
	v_mov_b32_e32 v64, v18
	v_mov_b32_e32 v65, v18
	v_mov_b32_e32 v66, v18
	v_mov_b32_e32 v67, v18
	v_mov_b32_e32 v68, v18
	v_mov_b32_e32 v69, v18
	v_mov_b32_e32 v70, v18
	v_mov_b32_e32 v71, v18
	v_mov_b32_e32 v72, v18
	v_mov_b32_e32 v73, v18
	v_mov_b32_e32 v74, v18
	v_mov_b32_e32 v75, v18
	v_mov_b32_e32 v76, v18
	v_mov_b32_e32 v77, v18
	v_mov_b32_e32 v78, v18
	v_mov_b32_e32 v79, v18
	v_mov_b32_e32 v80, v18
	v_mov_b32_e32 v81, v18
	v_mov_b32_e32 v82, v18
	v_mov_b32_e32 v83, v18
	v_mov_b32_e32 v84, v18
	v_mov_b32_e32 v85, v18
	v_mov_b32_e32 v86, v18
	v_mov_b32_e32 v87, v18
	v_mov_b32_e32 v88, v18
	v_mov_b32_e32 v89, v18
	v_mov_b32_e32 v90, v18
	v_mov_b32_e32 v91, v18
	v_mov_b32_e32 v92, v18
	v_mov_b32_e32 v93, v18
	v_mov_b32_e32 v98, v18
	v_mov_b32_e32 v99, v18
	v_mov_b32_e32 v100, v18
	v_mov_b32_e32 v101, v18
	v_mov_b32_e32 v102, v18
	v_mov_b32_e32 v103, v18
	v_mov_b32_e32 v104, v18
	v_mov_b32_e32 v105, v18
	v_mov_b32_e32 v106, v18
	v_mov_b32_e32 v107, v18
	v_mov_b32_e32 v108, v18
	v_mov_b32_e32 v109, v18
	v_mov_b32_e32 v110, v18
	v_mov_b32_e32 v111, v18
	v_mov_b32_e32 v112, v18
	v_mov_b32_e32 v113, v18
	v_mov_b32_e32 v114, v18
	v_mov_b32_e32 v115, v18
	v_mov_b32_e32 v116, v18
	v_mov_b32_e32 v117, v18
	v_mov_b32_e32 v118, v18
	v_mov_b32_e32 v119, v18
	v_mov_b32_e32 v120, v18
	v_mov_b32_e32 v121, v18
	v_mov_b32_e32 v122, v18
	v_mov_b32_e32 v123, v18
	v_mov_b32_e32 v124, v18
	v_mov_b32_e32 v125, v18
	v_mov_b32_e32 v126, v18
	v_mov_b32_e32 v127, v18
	v_mov_b32_e32 v128, v18
	v_mov_b32_e32 v129, v18
	v_mov_b32_e32 v130, v18
	v_mov_b32_e32 v131, v18
	v_mov_b32_e32 v132, v18
	v_mov_b32_e32 v133, v18
	v_mov_b32_e32 v134, v18
	v_mov_b32_e32 v135, v18
	v_mov_b32_e32 v136, v18
	v_mov_b32_e32 v137, v18
	v_mov_b32_e32 v138, v18
	v_mov_b32_e32 v139, v18
	v_mov_b32_e32 v140, v18
	v_mov_b32_e32 v141, v18
	v_mov_b32_e32 v142, v18
	v_mov_b32_e32 v143, v18
	v_mov_b32_e32 v144, v18
	v_mov_b32_e32 v145, v18
	v_mov_b32_e32 v146, v18
	v_mov_b32_e32 v147, v18
	v_mov_b32_e32 v148, v18
	v_mov_b32_e32 v149, v18
	v_mov_b32_e32 v150, v18
	v_mov_b32_e32 v151, v18
	v_mov_b32_e32 v152, v18
	v_mov_b32_e32 v153, v18
	v_mov_b32_e32 v154, v18
	v_mov_b32_e32 v155, v18
	v_mov_b32_e32 v156, v18
	v_mov_b32_e32 v157, v18
	v_mov_b32_e32 v158, v18
	v_mov_b32_e32 v159, v18
	v_mov_b32_e32 v160, v18
	v_mov_b32_e32 v161, v18
	v_readfirstlane_b32 s52, v178
	v_readfirstlane_b32 s53, v179
	s_sub_u32 s52, s52, 0x40000000
	s_subb_u32 s53, s53, 0
	v_readfirstlane_b32 s56, v170
	v_readfirstlane_b32 s57, v171
	s_sub_u32 s56, s56, 0x40000000
	s_subb_u32 s57, s57, 0
	v_subrev_u32_e32 v179, s52, v178
	v_subrev_u32_e32 v177, s52, v176
	v_subrev_u32_e32 v175, s52, v174
	v_subrev_u32_e32 v173, s52, v172
	v_subrev_u32_e32 v171, s56, v170
	v_subrev_u32_e32 v169, s56, v168
	v_subrev_u32_e32 v167, s56, v166
	v_subrev_u32_e32 v165, s56, v164
	v_lshl_add_u32 v164, v186, 1, v181
	v_lshl_add_u32 v166, v186, 1, v180
	v_lshl_add_u32 v168, v182, 1, v181
	v_lshl_add_u32 v170, v182, 1, v180
.LBB0_1007:
	s_xor_b32 s4, s2, 0x10000
	v_add_u32_e32 v0, s4, v163
	s_waitcnt lgkmcnt(0)
	s_barrier
	s_cmp_eq_u32 s100, 0
	s_cbranch_scc1 .Lstg_1007_a
	v_mfma_f32_16x16x32_bf16 v[158:161], v[226:229], v[192:195], v[158:161]
	v_mfma_f32_16x16x32_bf16 v[154:157], v[230:233], v[192:195], v[154:157]
	v_mfma_f32_16x16x32_bf16 v[150:153], v[234:237], v[192:195], v[150:153]
	v_mfma_f32_16x16x32_bf16 v[146:149], v[238:241], v[192:195], v[146:149]
	v_mfma_f32_16x16x32_bf16 v[142:145], v[226:229], v[198:201], v[142:145]
	v_mfma_f32_16x16x32_bf16 v[138:141], v[230:233], v[198:201], v[138:141]
	v_mfma_f32_16x16x32_bf16 v[134:137], v[234:237], v[198:201], v[134:137]
	v_mfma_f32_16x16x32_bf16 v[130:133], v[238:241], v[198:201], v[130:133]
	v_mfma_f32_16x16x32_bf16 v[126:129], v[226:229], v[202:205], v[126:129]
	v_mfma_f32_16x16x32_bf16 v[122:125], v[230:233], v[202:205], v[122:125]
	v_mfma_f32_16x16x32_bf16 v[118:121], v[234:237], v[202:205], v[118:121]
	v_mfma_f32_16x16x32_bf16 v[114:117], v[238:241], v[202:205], v[114:117]
	v_mfma_f32_16x16x32_bf16 v[110:113], v[226:229], v[206:209], v[110:113]
	v_mfma_f32_16x16x32_bf16 v[106:109], v[230:233], v[206:209], v[106:109]
	v_mfma_f32_16x16x32_bf16 v[102:105], v[234:237], v[206:209], v[102:105]
	v_mfma_f32_16x16x32_bf16 v[98:101], v[238:241], v[206:209], v[98:101]
	v_mfma_f32_16x16x32_bf16 v[90:93], v[226:229], v[210:213], v[90:93]
	v_mfma_f32_16x16x32_bf16 v[86:89], v[230:233], v[210:213], v[86:89]
	v_mfma_f32_16x16x32_bf16 v[82:85], v[234:237], v[210:213], v[82:85]
	v_mfma_f32_16x16x32_bf16 v[78:81], v[238:241], v[210:213], v[78:81]
	v_mfma_f32_16x16x32_bf16 v[74:77], v[226:229], v[214:217], v[74:77]
	v_mfma_f32_16x16x32_bf16 v[70:73], v[230:233], v[214:217], v[70:73]
	v_mfma_f32_16x16x32_bf16 v[66:69], v[234:237], v[214:217], v[66:69]
	v_mfma_f32_16x16x32_bf16 v[62:65], v[238:241], v[214:217], v[62:65]
	v_mfma_f32_16x16x32_bf16 v[58:61], v[226:229], v[218:221], v[58:61]
	v_mfma_f32_16x16x32_bf16 v[50:53], v[230:233], v[218:221], v[50:53]
	v_mfma_f32_16x16x32_bf16 v[46:49], v[234:237], v[218:221], v[46:49]
	v_mfma_f32_16x16x32_bf16 v[38:41], v[238:241], v[218:221], v[38:41]
	v_mfma_f32_16x16x32_bf16 v[30:33], v[226:229], v[222:225], v[30:33]
	v_mfma_f32_16x16x32_bf16 v[26:29], v[230:233], v[222:225], v[26:29]
	v_mfma_f32_16x16x32_bf16 v[22:25], v[234:237], v[222:225], v[22:25]
	v_mfma_f32_16x16x32_bf16 v[18:21], v[238:241], v[222:225], v[18:21]
; DI void gemm8_accum(f32x4 (&acc)[8][4], const bf16_t* a, size_t lda, const bf16_t* b, size_t ldb, int nkb, bf16_t* L,
;                     const bool pre, const bf16_t* an, size_t ldan, const bf16_t* bn, size_t ldbn) {
;     ...
;   for (int kb = 0; kb + 2 < nkb; ++kb) {
;     __syncthreads();
;     g8_store1(L + ((kb + 1) & 1) * 32768, ra, lrow, lch);
;     g8_load1o(ra, a + (kb + 2) * 64, offa);
;     __builtin_amdgcn_sched_barrier(0);
;     g8_compute<0, 1>(acc, L + (kb & 1) * 32768, wm, wn, lane);
;     __builtin_amdgcn_sched_barrier(0);
;     g8_store1(L + ((kb + 1) & 1) * 32768 + 16384, rb, lrow, lch);
;     g8_load1o(rb, b + (kb + 2) * 64, offb);
;     __builtin_amdgcn_sched_barrier(0);
;     g8_compute<1, 2>(acc, L + (kb & 1) * 32768, wm, wn, lane);
.Lstg_1007_a:
	s_waitcnt vmcnt(4)
	ds_write_b128 v0, v[34:37]
	ds_write_b128 v0, v[42:45] offset:8192
	ds_write_b128 v0, v[54:57] offset:16384
	ds_write_b128 v0, v[94:97] offset:24576
	s_add_u32 s54, s52, s0
	s_addc_u32 s55, s53, s1
	global_load_dwordx4 v[34:37], v179, s[54:55]
	global_load_dwordx4 v[42:45], v177, s[54:55]
	global_load_dwordx4 v[54:57], v175, s[54:55]
	global_load_dwordx4 v[94:97], v173, s[54:55]
	v_add_u32_e32 v222, s2, v164
	ds_read_b128 v[192:195], v222
	ds_read_b128 v[198:201], v222 offset:2048
	ds_read_b128 v[202:205], v222 offset:4096
	ds_read_b128 v[206:209], v222 offset:6144
	ds_read_b128 v[210:213], v222 offset:8192
	ds_read_b128 v[214:217], v222 offset:10240
	ds_read_b128 v[218:221], v222 offset:12288
	ds_read_b128 v[222:225], v222 offset:14336
	v_add_u32_e32 v191, s2, v166
	ds_read_b128 v[226:229], v191 offset:32768
	ds_read_b128 v[230:233], v191 offset:34816
	ds_read_b128 v[234:237], v191 offset:36864
	ds_read_b128 v[238:241], v191 offset:38912
	s_waitcnt lgkmcnt(3)
	v_mfma_f32_16x16x32_bf16 v[158:161], v[226:229], v[192:195], v[158:161]
	s_waitcnt lgkmcnt(2)
	v_mfma_f32_16x16x32_bf16 v[154:157], v[230:233], v[192:195], v[154:157]
	s_waitcnt lgkmcnt(1)
	v_mfma_f32_16x16x32_bf16 v[150:153], v[234:237], v[192:195], v[150:153]
	s_waitcnt lgkmcnt(0)
	v_mfma_f32_16x16x32_bf16 v[146:149], v[238:241], v[192:195], v[146:149]
	v_mfma_f32_16x16x32_bf16 v[142:145], v[226:229], v[198:201], v[142:145]
	v_mfma_f32_16x16x32_bf16 v[138:141], v[230:233], v[198:201], v[138:141]
	v_mfma_f32_16x16x32_bf16 v[134:137], v[234:237], v[198:201], v[134:137]
	v_mfma_f32_16x16x32_bf16 v[130:133], v[238:241], v[198:201], v[130:133]
	v_mfma_f32_16x16x32_bf16 v[126:129], v[226:229], v[202:205], v[126:129]
	v_mfma_f32_16x16x32_bf16 v[122:125], v[230:233], v[202:205], v[122:125]
	v_mfma_f32_16x16x32_bf16 v[118:121], v[234:237], v[202:205], v[118:121]
	v_mfma_f32_16x16x32_bf16 v[114:117], v[238:241], v[202:205], v[114:117]
	v_mfma_f32_16x16x32_bf16 v[110:113], v[226:229], v[206:209], v[110:113]
	v_mfma_f32_16x16x32_bf16 v[106:109], v[230:233], v[206:209], v[106:109]
	v_mfma_f32_16x16x32_bf16 v[102:105], v[234:237], v[206:209], v[102:105]
	v_mfma_f32_16x16x32_bf16 v[98:101], v[238:241], v[206:209], v[98:101]
	v_mfma_f32_16x16x32_bf16 v[90:93], v[226:229], v[210:213], v[90:93]
	v_mfma_f32_16x16x32_bf16 v[86:89], v[230:233], v[210:213], v[86:89]
	v_mfma_f32_16x16x32_bf16 v[82:85], v[234:237], v[210:213], v[82:85]
	v_mfma_f32_16x16x32_bf16 v[78:81], v[238:241], v[210:213], v[78:81]
	v_mfma_f32_16x16x32_bf16 v[74:77], v[226:229], v[214:217], v[74:77]
	v_mfma_f32_16x16x32_bf16 v[70:73], v[230:233], v[214:217], v[70:73]
	v_mfma_f32_16x16x32_bf16 v[66:69], v[234:237], v[214:217], v[66:69]
	v_mfma_f32_16x16x32_bf16 v[62:65], v[238:241], v[214:217], v[62:65]
	v_mfma_f32_16x16x32_bf16 v[58:61], v[226:229], v[218:221], v[58:61]
	v_mfma_f32_16x16x32_bf16 v[50:53], v[230:233], v[218:221], v[50:53]
	v_mfma_f32_16x16x32_bf16 v[46:49], v[234:237], v[218:221], v[46:49]
	v_mfma_f32_16x16x32_bf16 v[38:41], v[238:241], v[218:221], v[38:41]
	v_mfma_f32_16x16x32_bf16 v[30:33], v[226:229], v[222:225], v[30:33]
	v_mfma_f32_16x16x32_bf16 v[26:29], v[230:233], v[222:225], v[26:29]
	v_mfma_f32_16x16x32_bf16 v[22:25], v[234:237], v[222:225], v[22:25]
	v_mfma_f32_16x16x32_bf16 v[18:21], v[238:241], v[222:225], v[18:21]
	s_waitcnt vmcnt(4)
	ds_write_b128 v0, v[14:17] offset:32768
	ds_write_b128 v0, v[2:5] offset:40960
	ds_write_b128 v0, v[6:9] offset:49152
	ds_write_b128 v0, v[10:13] offset:57344
	s_add_u32 s58, s56, s0
	s_addc_u32 s59, s57, s1
	global_load_dwordx4 v[14:17], v171, s[58:59]
	global_load_dwordx4 v[2:5], v169, s[58:59]
	global_load_dwordx4 v[6:9], v167, s[58:59]
	global_load_dwordx4 v[10:13], v165, s[58:59]
	v_add_u32_e32 v191, s2, v168
	ds_read_b128 v[192:195], v191
	ds_read_b128 v[198:201], v191 offset:2048
	ds_read_b128 v[202:205], v191 offset:4096
	ds_read_b128 v[206:209], v191 offset:6144
	ds_read_b128 v[210:213], v191 offset:8192
	ds_read_b128 v[214:217], v191 offset:10240
	ds_read_b128 v[218:221], v191 offset:12288
	ds_read_b128 v[222:225], v191 offset:14336
	v_add_u32_e32 v0, s2, v170
	ds_read_b128 v[226:229], v0 offset:32768
	ds_read_b128 v[230:233], v0 offset:34816
	ds_read_b128 v[234:237], v0 offset:36864
	ds_read_b128 v[238:241], v0 offset:38912
	s_cmp_lg_u32 s101, 0
	s_cbranch_scc1 .Lstg_1007_b
	s_waitcnt lgkmcnt(3)
	v_mfma_f32_16x16x32_bf16 v[158:161], v[226:229], v[192:195], v[158:161]
	s_waitcnt lgkmcnt(2)
	v_mfma_f32_16x16x32_bf16 v[154:157], v[230:233], v[192:195], v[154:157]
	s_waitcnt lgkmcnt(1)
	v_mfma_f32_16x16x32_bf16 v[150:153], v[234:237], v[192:195], v[150:153]
	s_waitcnt lgkmcnt(0)
	v_mfma_f32_16x16x32_bf16 v[146:149], v[238:241], v[192:195], v[146:149]
	v_mfma_f32_16x16x32_bf16 v[142:145], v[226:229], v[198:201], v[142:145]
	v_mfma_f32_16x16x32_bf16 v[138:141], v[230:233], v[198:201], v[138:141]
	v_mfma_f32_16x16x32_bf16 v[134:137], v[234:237], v[198:201], v[134:137]
	v_mfma_f32_16x16x32_bf16 v[130:133], v[238:241], v[198:201], v[130:133]
	v_mfma_f32_16x16x32_bf16 v[126:129], v[226:229], v[202:205], v[126:129]
	v_mfma_f32_16x16x32_bf16 v[122:125], v[230:233], v[202:205], v[122:125]
	v_mfma_f32_16x16x32_bf16 v[118:121], v[234:237], v[202:205], v[118:121]
	v_mfma_f32_16x16x32_bf16 v[114:117], v[238:241], v[202:205], v[114:117]
	v_mfma_f32_16x16x32_bf16 v[110:113], v[226:229], v[206:209], v[110:113]
	v_mfma_f32_16x16x32_bf16 v[106:109], v[230:233], v[206:209], v[106:109]
	v_mfma_f32_16x16x32_bf16 v[102:105], v[234:237], v[206:209], v[102:105]
	v_mfma_f32_16x16x32_bf16 v[98:101], v[238:241], v[206:209], v[98:101]
	v_mfma_f32_16x16x32_bf16 v[90:93], v[226:229], v[210:213], v[90:93]
	v_mfma_f32_16x16x32_bf16 v[86:89], v[230:233], v[210:213], v[86:89]
	v_mfma_f32_16x16x32_bf16 v[82:85], v[234:237], v[210:213], v[82:85]
	v_mfma_f32_16x16x32_bf16 v[78:81], v[238:241], v[210:213], v[78:81]
	v_mfma_f32_16x16x32_bf16 v[74:77], v[226:229], v[214:217], v[74:77]
	v_mfma_f32_16x16x32_bf16 v[70:73], v[230:233], v[214:217], v[70:73]
	v_mfma_f32_16x16x32_bf16 v[66:69], v[234:237], v[214:217], v[66:69]
	v_mfma_f32_16x16x32_bf16 v[62:65], v[238:241], v[214:217], v[62:65]
	v_mfma_f32_16x16x32_bf16 v[58:61], v[226:229], v[218:221], v[58:61]
	v_mfma_f32_16x16x32_bf16 v[50:53], v[230:233], v[218:221], v[50:53]
	v_mfma_f32_16x16x32_bf16 v[46:49], v[234:237], v[218:221], v[46:49]
	v_mfma_f32_16x16x32_bf16 v[38:41], v[238:241], v[218:221], v[38:41]
	v_mfma_f32_16x16x32_bf16 v[30:33], v[226:229], v[222:225], v[30:33]
	v_mfma_f32_16x16x32_bf16 v[26:29], v[230:233], v[222:225], v[26:29]
	v_mfma_f32_16x16x32_bf16 v[22:25], v[234:237], v[222:225], v[22:25]
	v_mfma_f32_16x16x32_bf16 v[18:21], v[238:241], v[222:225], v[18:21]
; DI void gemm8_accum(f32x4 (&acc)[8][4], const bf16_t* a, size_t lda, const bf16_t* b, size_t ldb, int nkb, bf16_t* L,
;                     const bool pre, const bf16_t* an, size_t ldan, const bf16_t* bn, size_t ldbn) {
;     ...
;   for (int kb = 0; kb + 2 < nkb; ++kb) {
;     __syncthreads();
;     g8_store1(L + ((kb + 1) & 1) * 32768, ra, lrow, lch);
;     g8_load1o(ra, a + (kb + 2) * 64, offa);
;     __builtin_amdgcn_sched_barrier(0);
;     g8_compute<0, 1>(acc, L + (kb & 1) * 32768, wm, wn, lane);
;     __builtin_amdgcn_sched_barrier(0);
;     g8_store1(L + ((kb + 1) & 1) * 32768 + 16384, rb, lrow, lch);
;     g8_load1o(rb, b + (kb + 2) * 64, offb);
;     __builtin_amdgcn_sched_barrier(0);
;     g8_compute<1, 2>(acc, L + (kb & 1) * 32768, wm, wn, lane);
;   }
;   __syncthreads();
;   g8_store1(L + 32768, ra, lrow, lch);
;   g8_load1(ra, an, ldan, 0, lrow, lch);
;   __builtin_amdgcn_sched_barrier(0);
;   g8_compute<0, 1>(acc, L, wm, wn, lane);
.Lstg_1007_b:
	s_mov_b32 s100, s101
	s_xor_b32 s2, s2, 0x10000
	s_add_u32 s0, s0, 0x80
	s_addc_u32 s1, s1, 0
	s_cmpk_lg_i32 s0, 0x700
	s_cbranch_scc1 .LBB0_1007
	s_cmp_eq_u32 s100, 0
	s_cbranch_scc1 .Lstg_1007_c
	s_waitcnt lgkmcnt(0)
	v_mfma_f32_16x16x32_bf16 v[158:161], v[226:229], v[192:195], v[158:161]
	v_mfma_f32_16x16x32_bf16 v[154:157], v[230:233], v[192:195], v[154:157]
	v_mfma_f32_16x16x32_bf16 v[150:153], v[234:237], v[192:195], v[150:153]
	v_mfma_f32_16x16x32_bf16 v[146:149], v[238:241], v[192:195], v[146:149]
	v_mfma_f32_16x16x32_bf16 v[142:145], v[226:229], v[198:201], v[142:145]
	v_mfma_f32_16x16x32_bf16 v[138:141], v[230:233], v[198:201], v[138:141]
	v_mfma_f32_16x16x32_bf16 v[134:137], v[234:237], v[198:201], v[134:137]
	v_mfma_f32_16x16x32_bf16 v[130:133], v[238:241], v[198:201], v[130:133]
	v_mfma_f32_16x16x32_bf16 v[126:129], v[226:229], v[202:205], v[126:129]
	v_mfma_f32_16x16x32_bf16 v[122:125], v[230:233], v[202:205], v[122:125]
	v_mfma_f32_16x16x32_bf16 v[118:121], v[234:237], v[202:205], v[118:121]
	v_mfma_f32_16x16x32_bf16 v[114:117], v[238:241], v[202:205], v[114:117]
	v_mfma_f32_16x16x32_bf16 v[110:113], v[226:229], v[206:209], v[110:113]
	v_mfma_f32_16x16x32_bf16 v[106:109], v[230:233], v[206:209], v[106:109]
	v_mfma_f32_16x16x32_bf16 v[102:105], v[234:237], v[206:209], v[102:105]
	v_mfma_f32_16x16x32_bf16 v[98:101], v[238:241], v[206:209], v[98:101]
	v_mfma_f32_16x16x32_bf16 v[90:93], v[226:229], v[210:213], v[90:93]
	v_mfma_f32_16x16x32_bf16 v[86:89], v[230:233], v[210:213], v[86:89]
	v_mfma_f32_16x16x32_bf16 v[82:85], v[234:237], v[210:213], v[82:85]
	v_mfma_f32_16x16x32_bf16 v[78:81], v[238:241], v[210:213], v[78:81]
	v_mfma_f32_16x16x32_bf16 v[74:77], v[226:229], v[214:217], v[74:77]
	v_mfma_f32_16x16x32_bf16 v[70:73], v[230:233], v[214:217], v[70:73]
	v_mfma_f32_16x16x32_bf16 v[66:69], v[234:237], v[214:217], v[66:69]
	v_mfma_f32_16x16x32_bf16 v[62:65], v[238:241], v[214:217], v[62:65]
	v_mfma_f32_16x16x32_bf16 v[58:61], v[226:229], v[218:221], v[58:61]
	v_mfma_f32_16x16x32_bf16 v[50:53], v[230:233], v[218:221], v[50:53]
	v_mfma_f32_16x16x32_bf16 v[46:49], v[234:237], v[218:221], v[46:49]
	v_mfma_f32_16x16x32_bf16 v[38:41], v[238:241], v[218:221], v[38:41]
	v_mfma_f32_16x16x32_bf16 v[30:33], v[226:229], v[222:225], v[30:33]
	v_mfma_f32_16x16x32_bf16 v[26:29], v[230:233], v[222:225], v[26:29]
	v_mfma_f32_16x16x32_bf16 v[22:25], v[234:237], v[222:225], v[22:25]
	v_mfma_f32_16x16x32_bf16 v[18:21], v[238:241], v[222:225], v[18:21]
	s_mov_b32 s100, 0
